# all in-loop staging in saddr form (address VALU removed) + 6 instead of 4 conversion items per wave in the input projection's idle half round
# speedup vs baseline: 1.0320x; 1.0069x over previous
; #define GAS __attribute__((address_space(1)))
; #define LAS __attribute__((address_space(3)))
; __device__ __forceinline__ void transpose_item64(const float* Wf, int Nsrc, int ca, int nva, int cb, int nvb, int K, bf16* WTf, int drow0, int k0, LAS unsigned char* scr, int lane, const float* gainf = nullptr) {
;     const GAS float* W = (const GAS float*)Wf; GAS bf16* WT = (GAS bf16*)WTf;
;     const int sub = (lane >> 3) & 1, c4 = 4 * (lane & 7), g = lane >> 4, nl = 32 * sub + c4;
;     const bool ok = c4 < (sub ? nvb : nva);
;     const GAS float* src = W + (size_t)(k0 + 2 * g) * Nsrc + (sub ? cb : ca) + c4;
; __device__ __forceinline__ void convert_layer(Frame& F, unsigned char* w, int l) {
;     LAS unsigned char* scr = F.lds + RING_OFF + F.wave * 16384;
;     const int gw = F.vcu * NWAVES + F.wave, NGW = F.G * NWAVES;
;     if (F.G == 256) { for (int q = gw; q < IT_LAYER - R_IDLE; q += NGW) convert_item(F, w, l, q < GU2_BASE ? q : q + R_IDLE, scr); }
;     else for (int r = gw; r < IT_LAYER; r += NGW) convert_item(F, w, l, r, scr);
.LBB0_106:
	s_add_i32 s1, 0, 0x204b0
	v_mov_b32_e32 v2, s1
	ds_read_b32 v2, v2
	s_add_i32 s1, 0, 0x204b4
	v_mov_b32_e32 v3, s1
	ds_read_b32 v3, v3
	s_ashr_i32 s2, s0, 6
	s_waitcnt lgkmcnt(1)
	v_readfirstlane_b32 s0, v2
	v_and_b32_e32 v132, 63, v1
	v_bfe_u32 v133, v1, 3, 3
	v_mov_b32_e32 v2, s0
	s_waitcnt lgkmcnt(0)
	v_readfirstlane_b32 s1, v3
	v_lshlrev_b32_e32 v134, 2, v132
	v_readfirstlane_b32 s0, v2
	v_mov_b32_e32 v2, s1
	s_add_u32 s3, s0, 0x100000
	v_writelane_b32 v254, s3, 7
	v_readfirstlane_b32 s1, v2
	v_writelane_b32 v254, s0, 9
	v_and_b32_e32 v138, 6, v133
	v_and_b32_e32 v2, 60, v134
	v_writelane_b32 v254, s1, 10
	s_addc_u32 s0, s1, 0
	v_writelane_b32 v254, s0, 11
	s_lshl_b32 s0, s2, 14
	s_add_i32 s4, s0, 0
	s_lshl_b32 s0, s5, 3
	s_add_i32 s16, s0, s2
	s_lshl_b32 s18, s6, 3
	s_cmpk_lg_i32 s6, 0x100
	v_writelane_b32 v254, s5, 13
	s_cselect_b64 s[0:1], -1, 0
	s_cmpk_lt_i32 s16, 0x4f00
	v_lshl_add_u32 v137, v138, 1, s4
	s_movk_i32 s5, 0x90
	v_writelane_b32 v254, s2, 14
	s_cselect_b64 s[2:3], -1, 0
	v_mad_u32_u24 v139, v2, s5, v137
	v_and_b32_e32 v2, 7, v1
	s_cmpk_lt_i32 s16, 0x3700
	v_and_b32_e32 v136, 28, v134
	v_lshl_add_u32 v3, v2, 4, s4
	v_bfe_u32 v1, v1, 3, 1
	s_cselect_b64 s[4:5], -1, 0
	v_lshl_or_b32 v5, v1, 5, v136
	v_writelane_b32 v254, s4, 15
	v_mul_u32_u24_e32 v163, 0x90, v5
	v_cndmask_b32_e64 v5, 0, 1, s[0:1]
	v_writelane_b32 v254, s5, 16
	s_lshl_b32 s0, s16, 5
	v_writelane_b32 v254, s0, 17
	s_lshl_b32 s0, s16, 6
	v_writelane_b32 v254, s0, 18
	s_lshl_b32 s0, s16, 1
	s_add_i32 s0, s0, 0x7fff7800
	s_mov_b32 s21, 0
	v_lshlrev_b32_e32 v2, 3, v2
	v_mul_u32_u24_e32 v4, 0x90, v133
	v_cndmask_b32_e64 v6, 0, 1, s[2:3]
	v_writelane_b32 v254, s0, 19
	v_and_b32_e32 v135, 32, v134
	v_or_b32_e32 v156, 8, v133
	v_or_b32_e32 v157, 16, v133
	v_or_b32_e32 v158, 24, v133
	v_or_b32_e32 v159, 32, v133
	v_or_b32_e32 v160, 40, v133
	v_or_b32_e32 v161, 48, v133
	v_or_b32_e32 v162, 56, v133
	s_lshl_b32 s49, s6, 8
	s_lshl_b32 s50, s6, 4
	s_add_i32 s54, 0, 0x204a0
	s_add_i32 s55, 0, 0x204a4
	s_movk_i32 s56, 0x2000
	s_mov_b32 s57, 0x10000
	s_mov_b32 s58, 0x12000
	s_mov_b32 s59, 0x20000
	s_mov_b32 s60, 0x22000
	s_mov_b32 s61, 0x30000
	s_mov_b32 s62, 0x32000
	s_mov_b32 s63, 0x40000
	s_mov_b32 s64, 0x42000
	s_mov_b32 s65, 0x50000
	s_mov_b32 s66, 0x52000
	s_mov_b32 s67, 0x60000
	s_mov_b32 s68, 0x62000
	s_mov_b32 s69, 0x70000
	s_mov_b32 s70, 0x72000
	s_movk_i32 s71, 0x7fff
	s_mov_b32 s72, 0xffff0000
	v_add_u32_e32 v164, v3, v4
	s_add_i32 s73, 0, 0x20490
	s_add_i32 s74, 0, 0x20494
	s_add_i32 s75, 0, 0x20498
	s_add_i32 s76, 0, 0x2049c
	s_add_i32 s77, 0, 0x20488
	s_add_i32 s78, 0, 0x2048c
	s_movk_i32 s79, 0x5800
	s_movk_i32 s80, 0x5000
	s_mov_b32 s81, 0x2c000
	s_mov_b32 s82, 0x31000
	s_mov_b32 s83, 0x58000
	s_mov_b32 s84, 0x5d000
	s_mov_b32 s85, 0x84000
	s_mov_b32 s86, 0x89000
	s_mov_b32 s87, 0xb0000
	s_mov_b32 s88, 0xb5000
	s_mov_b32 s89, 0xdc000
	s_mov_b32 s90, 0xe1000
	s_mov_b32 s91, 0x108000
	s_add_i32 s92, 0, 0x20480
	s_add_i32 s93, 0, 0x20484
	s_add_i32 s94, 0, 0x20470
	s_add_i32 s95, 0, 0x20474
	s_add_i32 s96, 0, 0x20478
	s_add_i32 s97, 0, 0x2047c
	s_add_i32 s48, 0, 0x20438
	s_add_i32 s33, 0, 0x2043c
	s_add_i32 s10, 0, 0x20430
	s_add_i32 s11, 0, 0x20434
	s_add_i32 s24, 0, 0x20428
	s_add_i32 s25, 0, 0x2042c
	s_add_i32 s26, 0, 0x20418
	s_add_i32 s27, 0, 0x2041c
	s_add_i32 s28, 0, 0x20420
	s_add_i32 s29, 0, 0x20424
	s_add_i32 s30, 0, 0x20410
	v_lshlrev_b32_e32 v140, 1, v2
	v_lshlrev_b32_e32 v142, 2, v136
	s_add_i32 s31, 0, 0x20414
	v_cmp_eq_u32_e64 s[2:3], 0, v1
	v_writelane_b32 v254, s6, 20
	s_lshl_b32 s14, s6, 9
	v_cmp_ne_u32_e64 s[4:5], 1, v5
	v_cmp_ne_u32_e64 s[6:7], 1, v6
	s_mov_b32 s36, s21
	s_branch .LBB0_108

; __device__ __forceinline__ void transpose_item64(const float* Wf, int Nsrc, int ca, int nva, int cb, int nvb, int K, bf16* WTf, int drow0, int k0, LAS unsigned char* scr, int lane, const float* gainf = nullptr) {
;     const GAS float* W = (const GAS float*)Wf; GAS bf16* WT = (GAS bf16*)WTf;
;     const int sub = (lane >> 3) & 1, c4 = 4 * (lane & 7), g = lane >> 4, nl = 32 * sub + c4;
;     const bool ok = c4 < (sub ? nvb : nva);
;     const GAS float* src = W + (size_t)(k0 + 2 * g) * Nsrc + (sub ? cb : ca) + c4;
;     f32x4 v[16];
; #pragma unroll
;     for (int i = 0; i < 16; ++i) v[i] = ok ? *(const GAS f32x4*)(src + (size_t)(8 * (i >> 1) + (i & 1)) * Nsrc) : (f32x4){0.f, 0.f, 0.f, 0.f};
;     if (gainf) { const GAS float* gp = (const GAS float*)gainf + k0 + 2 * g;
; #pragma unroll
;         for (int i = 0; i < 16; ++i) v[i] = v[i] * gp[8 * (i >> 1) + (i & 1)]; }
; #pragma unroll
;     for (int m = 0; m < 8; ++m)
; #pragma unroll
;         for (int j = 0; j < 4; ++j) *(LAS unsigned*)(scr + (nl + j) * TP_PITCH + (8 * m + 2 * g) * 2) = pk2(v[2 * m][j], v[2 * m + 1][j]);
; __device__ __forceinline__ void convert_item(Frame& F, unsigned char* w, int l, int r, LAS unsigned char* scr) {
;     unsigned char* wl = w + WS_W + (size_t)l * LW_STRIDE;
;     if (r < IT_GU) { conv_gu(inptr(F, 3) + (size_t)l * D * FF, inptr(F, 4) + (size_t)l * D * FF, (bf16*)(wl + LW_GU1), r, scr, F.lane, inptr(F, 2) + (size_t)l * D); return; } r -= IT_GU;
;     if (r < IT_D) { conv_plain(inptr(F, 5) + (size_t)l * FF * D, FF, D, (bf16*)(wl + LW_D1), r, scr, F.lane); return; } r -= IT_D;
;     if (r < IT_IN) { conv_in(inptr(F, 7) + (size_t)l * D * IN_W, (bf16*)(wl + LW_IN), r, scr, F.lane, inptr(F, 6) + (size_t)l * D); return; } r -= IT_IN;
;     if (r < IT_OUT) { conv_plain(inptr(F, 16) + (size_t)l * D * D, D, D, (bf16*)(wl + LW_OUT), r, scr, F.lane, inptr(F, 14) + (size_t)l * 1024, inptr(F, 15) + (size_t)l * 1024); return; } r -= IT_OUT;
;     if (r < IT_GU) { conv_gu(inptr(F, 18) + (size_t)l * D * FF, inptr(F, 19) + (size_t)l * D * FF, (bf16*)(wl + LW_GU2), r, scr, F.lane, inptr(F, 17) + (size_t)l * D); return; } r -= IT_GU;
;     conv_plain(inptr(F, 20) + (size_t)l * FF * D, FF, D, (bf16*)(wl + LW_D2), r, scr, F.lane);
; }
; __device__ __forceinline__ void convert_layer(Frame& F, unsigned char* w, int l) {
;     LAS unsigned char* scr = F.lds + RING_OFF + F.wave * 16384;
.LBB0_199:
	s_add_i32 s37, s37, s18
	s_cmpk_gt_i32 s37, 0x36ff
	s_cbranch_scc1 .LBB0_107
.LBB0_200:
	s_add_i32 s0, s37, 0x1800
	s_cmpk_lt_i32 s37, 0x2e00
	s_cselect_b32 s51, s37, s0
	s_cmpk_gt_i32 s51, 0x15ff
	s_mov_b64 s[8:9], -1
	s_cbranch_scc0 .LBB0_215
	s_cmpk_gt_u32 s51, 0x20ff
	s_cbranch_scc0 .LBB0_271
	s_cmpk_gt_u32 s51, 0x29ff
	s_cbranch_scc0 .LBB0_220
	s_cmpk_gt_u32 s51, 0x2dff
	s_cbranch_scc0 .LBB0_212
	s_cmpk_gt_u32 s51, 0x43ff
	s_cbranch_scc0 .LBB0_206
	v_mov_b32_e32 v1, s54
	ds_read_b32 v1, v1
	v_mov_b32_e32 v2, s55
	ds_read_b32 v2, v2
	v_mov_b32_e32 v3, v0
	v_mov_b32_e32 v5, v0
	s_waitcnt lgkmcnt(1)
	v_readfirstlane_b32 s0, v1
	s_add_u32 s0, s0, s35
	s_waitcnt lgkmcnt(0)
	v_readfirstlane_b32 s1, v2
	s_addc_u32 s1, s1, s34
	s_lshl_b32 s9, s51, 1
	s_add_i32 s9, s9, 0x7fff7800
	s_lshl_b32 s8, s51, 6
	s_and_b32 s9, s9, 0x7fffffc0
	s_and_b32 s8, s8, 0x7c0
	v_or_b32_e32 v2, s9, v138
	v_lshlrev_b64 v[2:3], 13, v[2:3]
	v_or_b32_e32 v1, s8, v135
	v_lshl_add_u64 v[2:3], s[0:1], 0, v[2:3]
	v_lshlrev_b32_e32 v4, 2, v1
	v_lshl_add_u64 v[2:3], v[2:3], 0, v[4:5]
	v_mov_b32_e32 v143, v0
	s_waitcnt vmcnt(11)
	v_lshl_add_u64 v[58:59], v[2:3], 0, v[142:143]
	v_add_co_u32_e32 v6, vcc, s56, v58
	global_load_dwordx4 v[2:5], v[58:59], off
	s_nop 0
	v_addc_co_u32_e32 v7, vcc, 0, v59, vcc
	global_load_dwordx4 v[6:9], v[6:7], off
	v_add_co_u32_e32 v10, vcc, s57, v58
	s_lshl_b32 s20, s9, 1
	s_nop 0
	v_addc_co_u32_e32 v11, vcc, 0, v59, vcc
	v_add_co_u32_e32 v14, vcc, s58, v58
	s_waitcnt vmcnt(1)
	v_bfe_u32 v1, v2, 16, 1
	v_addc_co_u32_e32 v15, vcc, 0, v59, vcc
	global_load_dwordx4 v[10:13], v[10:11], off
	s_nop 0
	global_load_dwordx4 v[14:17], v[14:15], off
	v_add_co_u32_e32 v18, vcc, s59, v58
	v_add3_u32 v1, v2, v1, s71
	s_nop 0
	v_addc_co_u32_e32 v19, vcc, 0, v59, vcc
	v_add_co_u32_e32 v22, vcc, s60, v58
	s_waitcnt vmcnt(2)
	v_bfe_u32 v2, v6, 16, 1
	v_addc_co_u32_e32 v23, vcc, 0, v59, vcc
	global_load_dwordx4 v[18:21], v[18:19], off
	s_nop 0
	global_load_dwordx4 v[22:25], v[22:23], off
	v_add_co_u32_e32 v26, vcc, s61, v58
	v_lshrrev_b32_e32 v1, 16, v1
	s_nop 0
	v_addc_co_u32_e32 v27, vcc, 0, v59, vcc
	v_add_co_u32_e32 v30, vcc, s62, v58
	v_add3_u32 v2, v6, v2, s71
	s_nop 0
	v_addc_co_u32_e32 v31, vcc, 0, v59, vcc
	global_load_dwordx4 v[26:29], v[26:27], off
	s_nop 0
	global_load_dwordx4 v[30:33], v[30:31], off
	v_add_co_u32_e32 v34, vcc, s63, v58
	v_and_or_b32 v1, v2, s72, v1
	s_nop 0
	v_addc_co_u32_e32 v35, vcc, 0, v59, vcc
	v_add_co_u32_e32 v38, vcc, s64, v58
	v_bfe_u32 v2, v3, 16, 1
	s_nop 0
	v_addc_co_u32_e32 v39, vcc, 0, v59, vcc
	global_load_dwordx4 v[34:37], v[34:35], off
	s_nop 0
	global_load_dwordx4 v[38:41], v[38:39], off
	v_add_co_u32_e32 v42, vcc, s65, v58
	v_add3_u32 v2, v3, v2, s71
	s_nop 0
	v_addc_co_u32_e32 v43, vcc, 0, v59, vcc
	v_add_co_u32_e32 v46, vcc, s66, v58
	v_bfe_u32 v3, v7, 16, 1
	s_nop 0
	v_addc_co_u32_e32 v47, vcc, 0, v59, vcc
	global_load_dwordx4 v[42:45], v[42:43], off
	s_nop 0
	global_load_dwordx4 v[46:49], v[46:47], off
	v_add_co_u32_e32 v50, vcc, s67, v58
	v_lshrrev_b32_e32 v2, 16, v2
	s_nop 0
	v_addc_co_u32_e32 v51, vcc, 0, v59, vcc
	v_add_co_u32_e32 v54, vcc, s68, v58
	v_add3_u32 v3, v7, v3, s71
	s_nop 0
	v_addc_co_u32_e32 v55, vcc, 0, v59, vcc
	global_load_dwordx4 v[50:53], v[50:51], off
	s_nop 0
	global_load_dwordx4 v[54:57], v[54:55], off
	v_and_or_b32 v2, v3, s72, v2
	v_bfe_u32 v3, v4, 16, 1
	v_add3_u32 v3, v4, v3, s71
	v_bfe_u32 v4, v8, 16, 1
	v_lshrrev_b32_e32 v3, 16, v3
	v_add3_u32 v4, v8, v4, s71
	v_and_or_b32 v3, v4, s72, v3
	v_bfe_u32 v4, v5, 16, 1
	v_add3_u32 v4, v5, v4, s71
	v_bfe_u32 v5, v9, 16, 1
	v_lshrrev_b32_e32 v4, 16, v4
	v_add3_u32 v5, v9, v5, s71
	v_add_co_u32_e32 v60, vcc, s69, v58
	v_and_or_b32 v4, v5, s72, v4
	s_nop 0
	v_addc_co_u32_e32 v61, vcc, 0, v59, vcc
	v_add_co_u32_e32 v62, vcc, s70, v58
	v_mov_b32_e32 v7, v0
	s_nop 0
	v_addc_co_u32_e32 v63, vcc, 0, v59, vcc
	global_load_dwordx4 v[58:61], v[60:61], off
	s_nop 0
	global_load_dwordx4 v[62:65], v[62:63], off
	s_waitcnt vmcnt(13)
	v_bfe_u32 v5, v10, 16, 1
	v_add3_u32 v5, v10, v5, s71
	s_waitcnt vmcnt(12)
	v_bfe_u32 v6, v14, 16, 1
	v_lshrrev_b32_e32 v5, 16, v5
	v_add3_u32 v6, v14, v6, s71
	v_and_or_b32 v5, v6, s72, v5
	ds_write2_b32 v139, v1, v5 offset1:4
	v_bfe_u32 v1, v11, 16, 1
	v_add3_u32 v1, v11, v1, s71
	v_bfe_u32 v5, v15, 16, 1
	v_lshrrev_b32_e32 v1, 16, v1
	v_add3_u32 v5, v15, v5, s71
	v_and_or_b32 v1, v5, s72, v1
	ds_write2_b32 v139, v2, v1 offset0:36 offset1:40
	v_bfe_u32 v1, v12, 16, 1
	v_add3_u32 v1, v12, v1, s71
	v_bfe_u32 v2, v16, 16, 1
	v_lshrrev_b32_e32 v1, 16, v1
	v_add3_u32 v2, v16, v2, s71
	v_and_or_b32 v1, v2, s72, v1
	ds_write2_b32 v139, v3, v1 offset0:72 offset1:76
	v_bfe_u32 v1, v13, 16, 1
	v_add3_u32 v1, v13, v1, s71
	v_bfe_u32 v2, v17, 16, 1
	v_lshrrev_b32_e32 v1, 16, v1
	v_add3_u32 v2, v17, v2, s71
	v_and_or_b32 v1, v2, s72, v1
	ds_write2_b32 v139, v4, v1 offset0:108 offset1:112
	s_waitcnt vmcnt(11)
	v_bfe_u32 v1, v18, 16, 1
	v_add3_u32 v1, v18, v1, s71
	s_waitcnt vmcnt(10)
	v_bfe_u32 v2, v22, 16, 1
	v_lshrrev_b32_e32 v1, 16, v1
	v_add3_u32 v2, v22, v2, s71
	v_and_or_b32 v1, v2, s72, v1
	v_bfe_u32 v2, v19, 16, 1
	v_add3_u32 v2, v19, v2, s71
	v_bfe_u32 v3, v23, 16, 1
	v_lshrrev_b32_e32 v2, 16, v2
	v_add3_u32 v3, v23, v3, s71
	v_and_or_b32 v2, v3, s72, v2
	v_bfe_u32 v3, v20, 16, 1
	v_add3_u32 v3, v20, v3, s71
	v_bfe_u32 v4, v24, 16, 1
	v_lshrrev_b32_e32 v3, 16, v3
	v_add3_u32 v4, v24, v4, s71
	v_and_or_b32 v3, v4, s72, v3
	v_bfe_u32 v4, v21, 16, 1
	v_add3_u32 v4, v21, v4, s71
	v_bfe_u32 v5, v25, 16, 1
	v_lshrrev_b32_e32 v4, 16, v4
	v_add3_u32 v5, v25, v5, s71
	v_and_or_b32 v4, v5, s72, v4
	s_waitcnt vmcnt(9)
; #define GAS __attribute__((address_space(1)))
; #define LAS __attribute__((address_space(3)))
; #define LDS_WAIT() asm volatile("s_waitcnt lgkmcnt(0)" ::: "memory")
; __device__ __forceinline__ unsigned pk2(float lo, float hi) { return f2bf(lo) | (f2bf(hi) << 16); }
; __device__ __forceinline__ void transpose_item64(const float* Wf, int Nsrc, int ca, int nva, int cb, int nvb, int K, bf16* WTf, int drow0, int k0, LAS unsigned char* scr, int lane, const float* gainf = nullptr) {
;     ...
; #pragma unroll
;     for (int m = 0; m < 8; ++m)
; #pragma unroll
;         for (int j = 0; j < 4; ++j) *(LAS unsigned*)(scr + (nl + j) * TP_PITCH + (8 * m + 2 * g) * 2) = pk2(v[2 * m][j], v[2 * m + 1][j]);
;     LDS_WAIT(); asm volatile("" ::: "memory");
; #pragma unroll
;     for (int t = 0; t < 8; ++t) { const int id = lane + 64 * t, n = id >> 3, c = id & 7;
;         const v4u o = *(const LAS v4u*)(scr + n * TP_PITCH + 16 * c);
;         *(GAS v4u*)(WT + (size_t)(drow0 + n) * K + k0 + 8 * c) = o; }
;     LDS_WAIT(); asm volatile("" ::: "memory");
	v_bfe_u32 v5, v26, 16, 1
	v_add3_u32 v5, v26, v5, s71
	s_waitcnt vmcnt(8)
	v_bfe_u32 v6, v30, 16, 1
	v_lshrrev_b32_e32 v5, 16, v5
	v_add3_u32 v6, v30, v6, s71
	v_and_or_b32 v5, v6, s72, v5
	ds_write2_b32 v139, v1, v5 offset0:8 offset1:12
	v_bfe_u32 v1, v27, 16, 1
	v_add3_u32 v1, v27, v1, s71
	v_bfe_u32 v5, v31, 16, 1
	v_lshrrev_b32_e32 v1, 16, v1
	v_add3_u32 v5, v31, v5, s71
	v_and_or_b32 v1, v5, s72, v1
	ds_write2_b32 v139, v2, v1 offset0:44 offset1:48
	v_bfe_u32 v1, v28, 16, 1
	v_add3_u32 v1, v28, v1, s71
	v_bfe_u32 v2, v32, 16, 1
	v_lshrrev_b32_e32 v1, 16, v1
	v_add3_u32 v2, v32, v2, s71
	v_and_or_b32 v1, v2, s72, v1
	ds_write2_b32 v139, v3, v1 offset0:80 offset1:84
	v_bfe_u32 v1, v29, 16, 1
	v_add3_u32 v1, v29, v1, s71
	v_bfe_u32 v2, v33, 16, 1
	v_lshrrev_b32_e32 v1, 16, v1
	v_add3_u32 v2, v33, v2, s71
	v_and_or_b32 v1, v2, s72, v1
	ds_write2_b32 v139, v4, v1 offset0:116 offset1:120
	s_waitcnt vmcnt(7)
	v_bfe_u32 v1, v34, 16, 1
	v_add3_u32 v1, v34, v1, s71
	s_waitcnt vmcnt(6)
	v_bfe_u32 v2, v38, 16, 1
	v_lshrrev_b32_e32 v1, 16, v1
	v_add3_u32 v2, v38, v2, s71
	v_and_or_b32 v1, v2, s72, v1
	v_bfe_u32 v2, v35, 16, 1
	v_add3_u32 v2, v35, v2, s71
	v_bfe_u32 v3, v39, 16, 1
	v_lshrrev_b32_e32 v2, 16, v2
	v_add3_u32 v3, v39, v3, s71
	v_and_or_b32 v2, v3, s72, v2
	v_bfe_u32 v3, v36, 16, 1
	v_add3_u32 v3, v36, v3, s71
	v_bfe_u32 v4, v40, 16, 1
	v_lshrrev_b32_e32 v3, 16, v3
	v_add3_u32 v4, v40, v4, s71
	v_and_or_b32 v3, v4, s72, v3
	v_bfe_u32 v4, v37, 16, 1
	v_add3_u32 v4, v37, v4, s71
	v_bfe_u32 v5, v41, 16, 1
	v_lshrrev_b32_e32 v4, 16, v4
	v_add3_u32 v5, v41, v5, s71
	v_and_or_b32 v4, v5, s72, v4
	s_waitcnt vmcnt(5)
	v_bfe_u32 v5, v42, 16, 1
	v_add3_u32 v5, v42, v5, s71
	s_waitcnt vmcnt(4)
	v_bfe_u32 v6, v46, 16, 1
	v_lshrrev_b32_e32 v5, 16, v5
	v_add3_u32 v6, v46, v6, s71
	v_and_or_b32 v5, v6, s72, v5
	ds_write2_b32 v139, v1, v5 offset0:16 offset1:20
	v_bfe_u32 v1, v43, 16, 1
	v_add3_u32 v1, v43, v1, s71
	v_bfe_u32 v5, v47, 16, 1
	v_lshrrev_b32_e32 v1, 16, v1
	v_add3_u32 v5, v47, v5, s71
	v_and_or_b32 v1, v5, s72, v1
	ds_write2_b32 v139, v2, v1 offset0:52 offset1:56
	v_bfe_u32 v1, v44, 16, 1
	v_add3_u32 v1, v44, v1, s71
	v_bfe_u32 v2, v48, 16, 1
	v_lshrrev_b32_e32 v1, 16, v1
	v_add3_u32 v2, v48, v2, s71
	v_and_or_b32 v1, v2, s72, v1
	ds_write2_b32 v139, v3, v1 offset0:88 offset1:92
	v_bfe_u32 v1, v45, 16, 1
	v_add3_u32 v1, v45, v1, s71
	v_bfe_u32 v2, v49, 16, 1
	v_lshrrev_b32_e32 v1, 16, v1
	v_add3_u32 v2, v49, v2, s71
	v_and_or_b32 v1, v2, s72, v1
	ds_write2_b32 v139, v4, v1 offset0:124 offset1:128
	s_waitcnt vmcnt(3)
	v_bfe_u32 v1, v50, 16, 1
	v_add3_u32 v1, v50, v1, s71
	s_waitcnt vmcnt(2)
	v_bfe_u32 v2, v54, 16, 1
	v_lshrrev_b32_e32 v1, 16, v1
	v_add3_u32 v2, v54, v2, s71
	v_and_or_b32 v1, v2, s72, v1
	v_bfe_u32 v2, v51, 16, 1
	v_add3_u32 v2, v51, v2, s71
	v_bfe_u32 v3, v55, 16, 1
	v_lshrrev_b32_e32 v2, 16, v2
	v_add3_u32 v3, v55, v3, s71
	v_and_or_b32 v2, v3, s72, v2
	v_bfe_u32 v3, v52, 16, 1
	v_add3_u32 v3, v52, v3, s71
	v_bfe_u32 v4, v56, 16, 1
	v_lshrrev_b32_e32 v3, 16, v3
	v_add3_u32 v4, v56, v4, s71
	v_and_or_b32 v3, v4, s72, v3
	v_bfe_u32 v4, v53, 16, 1
	v_add3_u32 v4, v53, v4, s71
	v_bfe_u32 v5, v57, 16, 1
	v_lshrrev_b32_e32 v4, 16, v4
	v_add3_u32 v5, v57, v5, s71
	v_and_or_b32 v4, v5, s72, v4
	s_waitcnt vmcnt(1)
	v_bfe_u32 v5, v58, 16, 1
	v_add3_u32 v5, v58, v5, s71
	s_waitcnt vmcnt(0)
	v_bfe_u32 v6, v62, 16, 1
	v_lshrrev_b32_e32 v5, 16, v5
	v_add3_u32 v6, v62, v6, s71
	v_and_or_b32 v5, v6, s72, v5
	ds_write2_b32 v139, v1, v5 offset0:24 offset1:28
	v_bfe_u32 v1, v59, 16, 1
	v_add3_u32 v1, v59, v1, s71
	v_bfe_u32 v5, v63, 16, 1
	v_lshrrev_b32_e32 v1, 16, v1
	v_add3_u32 v5, v63, v5, s71
	v_and_or_b32 v1, v5, s72, v1
	ds_write2_b32 v139, v2, v1 offset0:60 offset1:64
	v_bfe_u32 v1, v60, 16, 1
	v_add3_u32 v1, v60, v1, s71
	v_bfe_u32 v2, v64, 16, 1
	v_lshrrev_b32_e32 v1, 16, v1
	v_add3_u32 v2, v64, v2, s71
	v_and_or_b32 v1, v2, s72, v1
	ds_write2_b32 v139, v3, v1 offset0:96 offset1:100
	v_bfe_u32 v1, v61, 16, 1
	v_add3_u32 v1, v61, v1, s71
	v_bfe_u32 v2, v65, 16, 1
	v_lshrrev_b32_e32 v1, 16, v1
	v_add3_u32 v2, v65, v2, s71
	v_and_or_b32 v1, v2, s72, v1
	ds_write2_b32 v139, v4, v1 offset0:132 offset1:136
	s_waitcnt lgkmcnt(0)
	ds_read_b128 v[2:5], v164
	v_or_b32_e32 v1, s8, v133
	v_lshl_add_u64 v[10:11], v[146:147], 0, s[20:21]
	v_mul_u32_u24_e32 v6, 0x2c00, v1
	v_lshl_add_u64 v[12:13], v[10:11], 0, v[6:7]
	ds_read_b128 v[6:9], v164 offset:1152
	v_or_b32_e32 v1, s8, v156
	s_waitcnt lgkmcnt(1)
	global_store_dwordx4 v[12:13], v[2:5], off
	s_nop 1
	v_mul_u32_u24_e32 v2, 0x2c00, v1
	v_mov_b32_e32 v3, v0
	v_lshl_add_u64 v[2:3], v[10:11], 0, v[2:3]
	s_waitcnt lgkmcnt(0)
	global_store_dwordx4 v[2:3], v[6:9], off
	ds_read_b128 v[2:5], v164 offset:2304
	v_or_b32_e32 v1, s8, v157
	v_mul_u32_u24_e32 v6, 0x2c00, v1
	v_mov_b32_e32 v7, v0
	v_lshl_add_u64 v[12:13], v[10:11], 0, v[6:7]
	ds_read_b128 v[6:9], v164 offset:3456
	v_or_b32_e32 v1, s8, v158
	s_waitcnt lgkmcnt(1)
	global_store_dwordx4 v[12:13], v[2:5], off
	s_nop 1
	v_mul_u32_u24_e32 v2, 0x2c00, v1
	v_mov_b32_e32 v3, v0
	v_lshl_add_u64 v[2:3], v[10:11], 0, v[2:3]
	s_waitcnt lgkmcnt(0)
	global_store_dwordx4 v[2:3], v[6:9], off
	ds_read_b128 v[2:5], v164 offset:4608
	v_or_b32_e32 v1, s8, v159
	v_mul_u32_u24_e32 v6, 0x2c00, v1
	v_mov_b32_e32 v7, v0
	v_lshl_add_u64 v[12:13], v[10:11], 0, v[6:7]
	ds_read_b128 v[6:9], v164 offset:5760
	v_or_b32_e32 v1, s8, v160
	s_waitcnt lgkmcnt(1)
	global_store_dwordx4 v[12:13], v[2:5], off
	s_nop 1
	v_mul_u32_u24_e32 v2, 0x2c00, v1
	v_mov_b32_e32 v3, v0
	v_lshl_add_u64 v[2:3], v[10:11], 0, v[2:3]
	s_waitcnt lgkmcnt(0)
	global_store_dwordx4 v[2:3], v[6:9], off
	ds_read_b128 v[2:5], v164 offset:6912
	v_or_b32_e32 v1, s8, v161
	v_mul_u32_u24_e32 v6, 0x2c00, v1
	v_mov_b32_e32 v7, v0
	v_lshl_add_u64 v[12:13], v[10:11], 0, v[6:7]
	ds_read_b128 v[6:9], v164 offset:8064
	v_or_b32_e32 v1, s8, v162
	s_waitcnt lgkmcnt(1)
	global_store_dwordx4 v[12:13], v[2:5], off
	s_mov_b64 s[8:9], 0
	s_nop 0
	v_mul_u32_u24_e32 v2, 0x2c00, v1
	v_mov_b32_e32 v3, v0
	v_lshl_add_u64 v[2:3], v[10:11], 0, v[2:3]
	s_waitcnt lgkmcnt(0)
	global_store_dwordx4 v[2:3], v[6:9], off
	s_waitcnt lgkmcnt(0)

; #define PG8_STAGE(bufoff, gbase, voff) do { _Pragma("unroll") for (int _i = 0; _i < 2; ++_i) \
;         __builtin_amdgcn_global_load_lds((const unsigned*)((const char*)(gbase) + (voff)[_i]), (PG8_LAS unsigned*)(lds + (bufoff) + ldsw + _i * 8192), 16, 0, 0); } while (0)
; #define PG8_LDA(dst, b, h) do { _Pragma("unroll") for (int m = 0; m < 4; ++m) _Pragma("unroll") for (int k = 0; k < 2; ++k) dst[m][k] = *(const PG8_LAS bf16x8*)(lds + PG8_SA(b, h) + aoff + m * 2048 + k * 1024); } while (0)
; #define PG8_LDB(dst, b, h) do { _Pragma("unroll") for (int n = 0; n < 2; ++n) _Pragma("unroll") for (int k = 0; k < 2; ++k) dst[n][k] = *(const PG8_LAS bf16x8*)(lds + PG8_SB(b, h) + boff + n * 2048 + k * 1024); } while (0)
; #define PG8_WAIT_V(n) asm volatile("s_waitcnt vmcnt(" #n ")" ::: "memory")
; #define PG8_WAIT_L(n) asm volatile("s_waitcnt lgkmcnt(" #n ")" ::: "memory")
; #define PG8_BAR __builtin_amdgcn_s_barrier()
; #define PG8_SCHED __builtin_amdgcn_sched_barrier(0)
; template <class Epi, class Sched, bool ALIGN_EPI = false, bool SP2 = false>
; __device__ __forceinline__ void gemm_phase(PG8_LAS unsigned char* lds, const Gemm g, const Sched& S, const Epi& E) {
;     ...
;     for (;;) {
;         const bool has_next = S.next(ui + 1, nxt);
;         const char* nA = has_next ? (const char*)g.A + (size_t)nxt.pm * tstep : cA; const char* nB = has_next ? (const char*)g.Bt + (size_t)nxt.pn * tstep : cB;
;         for (int t = 0; t < nt; t += 2) {
;             const bool last = (t == nt - 2);
;             const char* a1 = cA + (size_t)(t + 1) * kstep;
;             const char* a2 = last ? nA : cA + (size_t)(t + 2) * kstep; const char* b2 = last ? nB : cB + (size_t)(t + 2) * kstep;
;             const char* a3 = a2 + kstep; const char* b3 = b2 + kstep;
;             if (last && has_next) S.a_ready(nxt);
;             if constexpr (Epi::MID) { if (t == nt / 2) E.mid(acc, cur, wr, wc, fr, fq); }
;             if constexpr (SP2) {
;             PG8_LDB(B0, 0, 0); PG8_LDB(B1, 0, 1); PG8_SCHED; PG8_LDA(At, 0, 0); PG8_STAGE(PG8_SA(1, 1), a1 + hstep, voffA);
;             PG8_WAIT_V(8); PG8_WAIT_L(0); PG8_BAR; PG8_MMA(0, 0, At, B0); PG8_MMA(0, 1, At, B1); PG8_BAR; PG8_SCHED;
;             PG8_LDA(At, 0, 1); PG8_STAGE(PG8_SB(0, 0), b2, voffB); PG8_STAGE(PG8_SB(0, 1), b2 + hstep, voffB); PG8_STAGE(PG8_SA(0, 0), a2, voffA);
.LBB0_372:
	s_ashr_i32 s21, s20, 31
	s_lshl_b64 s[22:23], s[20:21], 20
	s_add_u32 s22, s8, s22
	s_addc_u32 s23, s9, s23
	s_and_b64 s[24:25], s[2:3], exec
	s_cselect_b32 s5, s23, s29
	s_cselect_b32 s11, s22, s28
	s_ashr_i32 s19, s18, 31
	s_lshl_b64 s[24:25], s[18:19], 20
	s_add_u32 s24, s35, s24
	s_addc_u32 s25, s36, s25
	s_and_b64 s[30:31], s[2:3], exec
	s_cselect_b32 s19, s25, s27
	s_cselect_b32 s21, s24, s26
	s_add_u32 s53, s26, 0x100
	s_addc_u32 s54, s27, 0
	s_add_u32 s26, s28, 0x80080
	s_addc_u32 s27, s29, 0
	s_mov_b32 s55, -2
	s_add_u32 s28, s26, 0xfff80080
	s_addc_u32 s29, s27, -1
	s_add_i32 s33, 0, 0x10000
	s_cmp_eq_u32 s55, 28
	s_cselect_b32 s31, s5, s29
	s_cselect_b32 s30, s11, s28
	v_add_u32_e32 v161, s33, v155
	s_cselect_b32 s29, s19, s54
	s_cselect_b32 s28, s21, s53
	s_add_i32 s58, 0, 0x14000
	ds_read_b128 v[142:145], v161
	ds_read_b128 v[146:149], v161 offset:1024
	ds_read_b128 v[150:153], v161 offset:2048
	ds_read_b128 v[162:165], v161 offset:3072
	v_add_u32_e32 v161, s58, v155
	ds_read_b128 v[166:169], v161
	ds_read_b128 v[170:173], v161 offset:1024
	ds_read_b128 v[174:177], v161 offset:2048
	ds_read_b128 v[178:181], v161 offset:3072
	s_add_i32 m0, s41, 0xc000
	ds_read_b128 v[182:185], v160
	ds_read_b128 v[186:189], v160 offset:1024
	ds_read_b128 v[190:193], v160 offset:2048
	ds_read_b128 v[194:197], v160 offset:3072
	ds_read_b128 v[198:201], v160 offset:4096
	ds_read_b128 v[206:209], v160 offset:5120
	ds_read_b128 v[210:213], v160 offset:6144
	ds_read_b128 v[214:217], v160 offset:7168
	global_load_lds_dwordx4 v140, s[26:27]
	s_add_i32 m0, s41, 0xe000
	s_nop 0
	global_load_lds_dwordx4 v138, s[26:27]
	s_waitcnt vmcnt(8)
	s_waitcnt lgkmcnt(0)
	s_barrier
	s_setprio 1
	s_waitcnt lgkmcnt(0)
	v_mfma_f32_16x16x32_bf16 v[130:133], v[142:145], v[182:185], 0
	v_mfma_f32_16x16x32_bf16 v[130:133], v[146:149], v[186:189], v[130:133]
	v_mfma_f32_16x16x32_bf16 v[126:129], v[162:165], v[186:189], 0
	v_mfma_f32_16x16x32_bf16 v[126:129], v[150:153], v[182:185], v[126:129]
	v_mfma_f32_16x16x32_bf16 v[110:113], v[150:153], v[190:193], 0
	v_mfma_f32_16x16x32_bf16 v[110:113], v[162:165], v[194:197], v[110:113]
	v_mfma_f32_16x16x32_bf16 v[114:117], v[146:149], v[194:197], 0
	v_mfma_f32_16x16x32_bf16 v[114:117], v[142:145], v[190:193], v[114:117]
	v_mfma_f32_16x16x32_bf16 v[98:101], v[142:145], v[198:201], 0
	v_mfma_f32_16x16x32_bf16 v[98:101], v[146:149], v[206:209], v[98:101]
	v_mfma_f32_16x16x32_bf16 v[94:97], v[162:165], v[206:209], 0
	v_mfma_f32_16x16x32_bf16 v[94:97], v[150:153], v[198:201], v[94:97]
	v_mfma_f32_16x16x32_bf16 v[78:81], v[150:153], v[210:213], 0
	v_mfma_f32_16x16x32_bf16 v[78:81], v[162:165], v[214:217], v[78:81]
	v_mfma_f32_16x16x32_bf16 v[82:85], v[146:149], v[214:217], 0
	v_mfma_f32_16x16x32_bf16 v[82:85], v[142:145], v[210:213], v[82:85]
	s_setprio 0
	s_setprio 1
	v_mfma_f32_16x16x32_bf16 v[122:125], v[166:169], v[182:185], 0
	v_mfma_f32_16x16x32_bf16 v[122:125], v[170:173], v[186:189], v[122:125]
	v_mfma_f32_16x16x32_bf16 v[118:121], v[178:181], v[186:189], 0
	v_mfma_f32_16x16x32_bf16 v[118:121], v[174:177], v[182:185], v[118:121]
	v_mfma_f32_16x16x32_bf16 v[102:105], v[174:177], v[190:193], 0
	v_mfma_f32_16x16x32_bf16 v[102:105], v[178:181], v[194:197], v[102:105]
	v_mfma_f32_16x16x32_bf16 v[106:109], v[170:173], v[194:197], 0
	v_mfma_f32_16x16x32_bf16 v[106:109], v[166:169], v[190:193], v[106:109]
	v_mfma_f32_16x16x32_bf16 v[90:93], v[166:169], v[198:201], 0
	v_mfma_f32_16x16x32_bf16 v[90:93], v[170:173], v[206:209], v[90:93]
	v_mfma_f32_16x16x32_bf16 v[86:89], v[178:181], v[206:209], 0
	v_mfma_f32_16x16x32_bf16 v[86:89], v[174:177], v[198:201], v[86:89]
	v_mfma_f32_16x16x32_bf16 v[70:73], v[174:177], v[210:213], 0
	v_mfma_f32_16x16x32_bf16 v[70:73], v[178:181], v[214:217], v[70:73]
	v_mfma_f32_16x16x32_bf16 v[74:77], v[170:173], v[214:217], 0
	v_mfma_f32_16x16x32_bf16 v[74:77], v[166:169], v[210:213], v[74:77]
	s_setprio 0
	s_barrier
	s_add_i32 s33, s33, s39
	s_mov_b32 m0, s33
	ds_read_b128 v[182:185], v160 offset:16384
	ds_read_b128 v[186:189], v160 offset:17408
	ds_read_b128 v[190:193], v160 offset:18432
	ds_read_b128 v[194:197], v160 offset:19456
	ds_read_b128 v[198:201], v160 offset:20480
	ds_read_b128 v[206:209], v160 offset:21504
	ds_read_b128 v[210:213], v160 offset:22528
	ds_read_b128 v[214:217], v160 offset:23552
	global_load_lds_dwordx4 v0, s[28:29]
	s_add_i32 m0, s33, 0x2000
	s_add_u32 s100, s30, 0x80
	s_addc_u32 s101, s31, 0
	s_add_u32 s56, s28, 0x80000
	s_addc_u32 s57, s29, 0
	s_add_i32 s33, s58, s39
	global_load_lds_dwordx4 v14, s[28:29]
	s_mov_b32 m0, s33
	s_nop 0
	global_load_lds_dwordx4 v0, s[56:57]
	s_add_i32 m0, s33, 0x2000
	s_nop 0
	global_load_lds_dwordx4 v14, s[56:57]
	s_mov_b32 m0, s41
	s_nop 0
	global_load_lds_dwordx4 v136, s[30:31]
	s_mov_b32 m0, s42
	s_nop 0
	global_load_lds_dwordx4 v134, s[30:31]
	s_waitcnt vmcnt(8)
	s_waitcnt lgkmcnt(0)
	s_barrier
; #define PG8_STAGE(bufoff, gbase, voff) do { _Pragma("unroll") for (int _i = 0; _i < 2; ++_i) \
;         __builtin_amdgcn_global_load_lds((const unsigned*)((const char*)(gbase) + (voff)[_i]), (PG8_LAS unsigned*)(lds + (bufoff) + ldsw + _i * 8192), 16, 0, 0); } while (0)
; #define PG8_LDA(dst, b, h) do { _Pragma("unroll") for (int m = 0; m < 4; ++m) _Pragma("unroll") for (int k = 0; k < 2; ++k) dst[m][k] = *(const PG8_LAS bf16x8*)(lds + PG8_SA(b, h) + aoff + m * 2048 + k * 1024); } while (0)
; #define PG8_LDB(dst, b, h) do { _Pragma("unroll") for (int n = 0; n < 2; ++n) _Pragma("unroll") for (int k = 0; k < 2; ++k) dst[n][k] = *(const PG8_LAS bf16x8*)(lds + PG8_SB(b, h) + boff + n * 2048 + k * 1024); } while (0)
; #define PG8_MMA(ai, bj, At, Bt) do { __builtin_amdgcn_s_setprio(1); _Pragma("unroll") for (int m = 0; m < 4; ++m) _Pragma("unroll") for (int n = 0; n < 2; ++n) _Pragma("unroll") for (int k = 0; k < 2; ++k) \
;         acc[ai][bj][m][n] = __builtin_amdgcn_mfma_f32_16x16x32_bf16(Bt[n][k], At[m][k], acc[ai][bj][m][n], 0, 0, 0); __builtin_amdgcn_s_setprio(0); } while (0)
; #define PG8_WAIT_V(n) asm volatile("s_waitcnt vmcnt(" #n ")" ::: "memory")
; #define PG8_WAIT_L(n) asm volatile("s_waitcnt lgkmcnt(" #n ")" ::: "memory")
; #define PG8_BAR __builtin_amdgcn_s_barrier()
; #define PG8_SCHED __builtin_amdgcn_sched_barrier(0)
; template <class Epi, class Sched, bool ALIGN_EPI = false, bool SP2 = false>
; __device__ __forceinline__ void gemm_phase(PG8_LAS unsigned char* lds, const Gemm g, const Sched& S, const Epi& E) {
;     ...
;             PG8_WAIT_V(8); PG8_WAIT_L(0); PG8_BAR; PG8_MMA(1, 0, At, B0); PG8_MMA(1, 1, At, B1); PG8_BAR; PG8_SCHED;
;             PG8_LDB(B0, 1, 0); PG8_LDB(B1, 1, 1); PG8_SCHED; PG8_LDA(At, 1, 0); PG8_STAGE(PG8_SA(0, 1), a2 + hstep, voffA);
;             PG8_WAIT_V(8); PG8_WAIT_L(0); PG8_BAR; PG8_MMA(0, 0, At, B0); PG8_MMA(0, 1, At, B1); PG8_BAR; PG8_SCHED;
	s_setprio 1
	s_waitcnt lgkmcnt(0)
	v_mfma_f32_16x16x32_bf16 v[66:69], v[142:145], v[182:185], 0
	v_mfma_f32_16x16x32_bf16 v[66:69], v[146:149], v[186:189], v[66:69]
	v_mfma_f32_16x16x32_bf16 v[62:65], v[162:165], v[186:189], 0
	v_mfma_f32_16x16x32_bf16 v[62:65], v[150:153], v[182:185], v[62:65]
	v_mfma_f32_16x16x32_bf16 v[46:49], v[150:153], v[190:193], 0
	v_mfma_f32_16x16x32_bf16 v[46:49], v[162:165], v[194:197], v[46:49]
	v_mfma_f32_16x16x32_bf16 v[50:53], v[146:149], v[194:197], 0
	v_mfma_f32_16x16x32_bf16 v[50:53], v[142:145], v[190:193], v[50:53]
	v_mfma_f32_16x16x32_bf16 v[34:37], v[142:145], v[198:201], 0
	v_mfma_f32_16x16x32_bf16 v[34:37], v[146:149], v[206:209], v[34:37]
	v_mfma_f32_16x16x32_bf16 v[30:33], v[162:165], v[206:209], 0
	v_mfma_f32_16x16x32_bf16 v[30:33], v[150:153], v[198:201], v[30:33]
	v_mfma_f32_16x16x32_bf16 v[10:13], v[150:153], v[210:213], 0
	v_mfma_f32_16x16x32_bf16 v[10:13], v[162:165], v[214:217], v[10:13]
	v_mfma_f32_16x16x32_bf16 v[18:21], v[146:149], v[214:217], 0
	v_mfma_f32_16x16x32_bf16 v[18:21], v[142:145], v[210:213], v[18:21]
	s_setprio 0
	s_setprio 1
	v_mfma_f32_16x16x32_bf16 v[58:61], v[166:169], v[182:185], 0
	v_mfma_f32_16x16x32_bf16 v[58:61], v[170:173], v[186:189], v[58:61]
	v_mfma_f32_16x16x32_bf16 v[54:57], v[178:181], v[186:189], 0
	v_mfma_f32_16x16x32_bf16 v[54:57], v[174:177], v[182:185], v[54:57]
	v_mfma_f32_16x16x32_bf16 v[38:41], v[174:177], v[190:193], 0
	v_mfma_f32_16x16x32_bf16 v[38:41], v[178:181], v[194:197], v[38:41]
	v_mfma_f32_16x16x32_bf16 v[42:45], v[170:173], v[194:197], 0
	v_mfma_f32_16x16x32_bf16 v[42:45], v[166:169], v[190:193], v[42:45]
	v_mfma_f32_16x16x32_bf16 v[26:29], v[166:169], v[198:201], 0
	v_mfma_f32_16x16x32_bf16 v[26:29], v[170:173], v[206:209], v[26:29]
	v_mfma_f32_16x16x32_bf16 v[22:25], v[178:181], v[206:209], 0
	v_mfma_f32_16x16x32_bf16 v[22:25], v[174:177], v[198:201], v[22:25]
	v_mfma_f32_16x16x32_bf16 v[2:5], v[174:177], v[210:213], 0
	v_mfma_f32_16x16x32_bf16 v[2:5], v[178:181], v[214:217], v[2:5]
	v_mfma_f32_16x16x32_bf16 v[6:9], v[170:173], v[214:217], 0
	v_mfma_f32_16x16x32_bf16 v[6:9], v[166:169], v[210:213], v[6:9]
	s_setprio 0
	s_barrier
	s_add_i32 s33, 0, 0x18000
	v_add_u32_e32 v161, s33, v155
	s_add_i32 s56, 0, 0x1c000
	ds_read_b128 v[142:145], v161
	ds_read_b128 v[146:149], v161 offset:1024
	ds_read_b128 v[150:153], v161 offset:2048
	ds_read_b128 v[162:165], v161 offset:3072
	v_add_u32_e32 v161, s56, v155
	ds_read_b128 v[166:169], v161
	ds_read_b128 v[170:173], v161 offset:1024
	ds_read_b128 v[174:177], v161 offset:2048
	ds_read_b128 v[178:181], v161 offset:3072
	s_add_u32 s30, s30, 0x80000
	s_addc_u32 s31, s31, 0
	s_mov_b32 m0, s43
	ds_read_b128 v[182:185], v160 offset:32768
	ds_read_b128 v[186:189], v160 offset:33792
	ds_read_b128 v[190:193], v160 offset:34816
	ds_read_b128 v[194:197], v160 offset:35840
	ds_read_b128 v[198:201], v160 offset:36864
	ds_read_b128 v[206:209], v160 offset:37888
	ds_read_b128 v[210:213], v160 offset:38912
	ds_read_b128 v[214:217], v160 offset:39936
	global_load_lds_dwordx4 v136, s[30:31]
	s_mov_b32 m0, s44
	s_nop 0
	global_load_lds_dwordx4 v134, s[30:31]
	s_waitcnt vmcnt(8)
	s_waitcnt lgkmcnt(0)
	s_barrier
	s_setprio 1
	s_waitcnt lgkmcnt(0)
	v_mfma_f32_16x16x32_bf16 v[130:133], v[142:145], v[182:185], v[130:133]
	v_mfma_f32_16x16x32_bf16 v[130:133], v[146:149], v[186:189], v[130:133]
	v_mfma_f32_16x16x32_bf16 v[126:129], v[162:165], v[186:189], v[126:129]
	v_mfma_f32_16x16x32_bf16 v[126:129], v[150:153], v[182:185], v[126:129]
	v_mfma_f32_16x16x32_bf16 v[110:113], v[150:153], v[190:193], v[110:113]
	v_mfma_f32_16x16x32_bf16 v[110:113], v[162:165], v[194:197], v[110:113]
	v_mfma_f32_16x16x32_bf16 v[114:117], v[146:149], v[194:197], v[114:117]
	v_mfma_f32_16x16x32_bf16 v[114:117], v[142:145], v[190:193], v[114:117]
	v_mfma_f32_16x16x32_bf16 v[98:101], v[142:145], v[198:201], v[98:101]
	v_mfma_f32_16x16x32_bf16 v[98:101], v[146:149], v[206:209], v[98:101]
	v_mfma_f32_16x16x32_bf16 v[94:97], v[162:165], v[206:209], v[94:97]
	v_mfma_f32_16x16x32_bf16 v[94:97], v[150:153], v[198:201], v[94:97]
	v_mfma_f32_16x16x32_bf16 v[78:81], v[150:153], v[210:213], v[78:81]
	v_mfma_f32_16x16x32_bf16 v[78:81], v[162:165], v[214:217], v[78:81]
	v_mfma_f32_16x16x32_bf16 v[82:85], v[146:149], v[214:217], v[82:85]
	v_mfma_f32_16x16x32_bf16 v[82:85], v[142:145], v[210:213], v[82:85]
	s_setprio 0
	s_setprio 1
	v_mfma_f32_16x16x32_bf16 v[122:125], v[166:169], v[182:185], v[122:125]
	v_mfma_f32_16x16x32_bf16 v[122:125], v[170:173], v[186:189], v[122:125]
	v_mfma_f32_16x16x32_bf16 v[118:121], v[178:181], v[186:189], v[118:121]
	v_mfma_f32_16x16x32_bf16 v[118:121], v[174:177], v[182:185], v[118:121]
	v_mfma_f32_16x16x32_bf16 v[102:105], v[174:177], v[190:193], v[102:105]
	v_mfma_f32_16x16x32_bf16 v[102:105], v[178:181], v[194:197], v[102:105]
	v_mfma_f32_16x16x32_bf16 v[106:109], v[170:173], v[194:197], v[106:109]
	v_mfma_f32_16x16x32_bf16 v[106:109], v[166:169], v[190:193], v[106:109]
	v_mfma_f32_16x16x32_bf16 v[90:93], v[166:169], v[198:201], v[90:93]
	v_mfma_f32_16x16x32_bf16 v[90:93], v[170:173], v[206:209], v[90:93]
	v_mfma_f32_16x16x32_bf16 v[86:89], v[178:181], v[206:209], v[86:89]
	v_mfma_f32_16x16x32_bf16 v[86:89], v[174:177], v[198:201], v[86:89]
	v_mfma_f32_16x16x32_bf16 v[70:73], v[174:177], v[210:213], v[70:73]
	v_mfma_f32_16x16x32_bf16 v[70:73], v[178:181], v[214:217], v[70:73]
	v_mfma_f32_16x16x32_bf16 v[74:77], v[170:173], v[214:217], v[74:77]
	v_mfma_f32_16x16x32_bf16 v[74:77], v[166:169], v[210:213], v[74:77]
	s_setprio 0
	s_barrier
; #define PG8_STAGE(bufoff, gbase, voff) do { _Pragma("unroll") for (int _i = 0; _i < 2; ++_i) \
;         __builtin_amdgcn_global_load_lds((const unsigned*)((const char*)(gbase) + (voff)[_i]), (PG8_LAS unsigned*)(lds + (bufoff) + ldsw + _i * 8192), 16, 0, 0); } while (0)
; #define PG8_LDA(dst, b, h) do { _Pragma("unroll") for (int m = 0; m < 4; ++m) _Pragma("unroll") for (int k = 0; k < 2; ++k) dst[m][k] = *(const PG8_LAS bf16x8*)(lds + PG8_SA(b, h) + aoff + m * 2048 + k * 1024); } while (0)
; #define PG8_LDB(dst, b, h) do { _Pragma("unroll") for (int n = 0; n < 2; ++n) _Pragma("unroll") for (int k = 0; k < 2; ++k) dst[n][k] = *(const PG8_LAS bf16x8*)(lds + PG8_SB(b, h) + boff + n * 2048 + k * 1024); } while (0)
; #define PG8_MMA(ai, bj, At, Bt) do { __builtin_amdgcn_s_setprio(1); _Pragma("unroll") for (int m = 0; m < 4; ++m) _Pragma("unroll") for (int n = 0; n < 2; ++n) _Pragma("unroll") for (int k = 0; k < 2; ++k) \
;         acc[ai][bj][m][n] = __builtin_amdgcn_mfma_f32_16x16x32_bf16(Bt[n][k], At[m][k], acc[ai][bj][m][n], 0, 0, 0); __builtin_amdgcn_s_setprio(0); } while (0)
; #define PG8_WAIT_V(n) asm volatile("s_waitcnt vmcnt(" #n ")" ::: "memory")
; #define PG8_WAIT_L(n) asm volatile("s_waitcnt lgkmcnt(" #n ")" ::: "memory")
; #define PG8_BAR __builtin_amdgcn_s_barrier()
; #define PG8_SCHED __builtin_amdgcn_sched_barrier(0)
; template <class Epi, class Sched, bool ALIGN_EPI = false, bool SP2 = false>
; __device__ __forceinline__ void gemm_phase(PG8_LAS unsigned char* lds, const Gemm g, const Sched& S, const Epi& E) {
;     ...
;             PG8_LDB(B0, 0, 0); PG8_LDB(B1, 0, 1); PG8_SCHED; PG8_LDA(At, 0, 0); PG8_STAGE(PG8_SA(1, 1), a1 + hstep, voffA);
;             PG8_WAIT_V(8); PG8_WAIT_L(0); PG8_BAR; PG8_MMA(0, 0, At, B0); PG8_MMA(0, 1, At, B1); PG8_BAR; PG8_SCHED;
;     ...
;             PG8_LDA(At, 1, 1); PG8_STAGE(PG8_SB(1, 0), b3, voffB); PG8_STAGE(PG8_SB(1, 1), b3 + hstep, voffB); PG8_STAGE(PG8_SA(1, 0), a3, voffA);
;             PG8_WAIT_V(8); PG8_WAIT_L(0); PG8_BAR; PG8_MMA(1, 0, At, B0); PG8_MMA(1, 1, At, B1); PG8_BAR; PG8_SCHED;
	s_add_i32 s30, s33, s39
	s_add_i32 m0, s30, 0xffffff80
	ds_read_b128 v[182:185], v160 offset:49152
	ds_read_b128 v[186:189], v160 offset:50176
	ds_read_b128 v[190:193], v160 offset:51200
	ds_read_b128 v[194:197], v160 offset:52224
	ds_read_b128 v[198:201], v160 offset:53248
	ds_read_b128 v[206:209], v160 offset:54272
	ds_read_b128 v[210:213], v160 offset:55296
	ds_read_b128 v[214:217], v160 offset:56320
	global_load_lds_dwordx4 v0, s[28:29] offset:128
	s_add_i32 m0, s30, 0x1f80
	s_add_i32 s30, s56, s39
	global_load_lds_dwordx4 v14, s[28:29] offset:128
	s_add_u32 s28, s28, 0x80080
	s_addc_u32 s29, s29, 0
	s_mov_b32 m0, s30
	s_nop 0
	global_load_lds_dwordx4 v0, s[28:29]
	s_add_i32 m0, s30, 0x2000
	s_nop 0
	global_load_lds_dwordx4 v14, s[28:29]
	s_mov_b32 m0, s46
	s_nop 0
	global_load_lds_dwordx4 v136, s[100:101]
	s_mov_b32 m0, s47
	s_nop 0
	global_load_lds_dwordx4 v134, s[100:101]
	s_waitcnt vmcnt(8)
	s_waitcnt lgkmcnt(0)
	s_barrier
	s_setprio 1
	s_waitcnt lgkmcnt(0)
	v_mfma_f32_16x16x32_bf16 v[66:69], v[142:145], v[182:185], v[66:69]
	v_mfma_f32_16x16x32_bf16 v[66:69], v[146:149], v[186:189], v[66:69]
	v_mfma_f32_16x16x32_bf16 v[62:65], v[162:165], v[186:189], v[62:65]
	v_mfma_f32_16x16x32_bf16 v[62:65], v[150:153], v[182:185], v[62:65]
	v_mfma_f32_16x16x32_bf16 v[46:49], v[150:153], v[190:193], v[46:49]
	v_mfma_f32_16x16x32_bf16 v[46:49], v[162:165], v[194:197], v[46:49]
	v_mfma_f32_16x16x32_bf16 v[50:53], v[146:149], v[194:197], v[50:53]
	v_mfma_f32_16x16x32_bf16 v[50:53], v[142:145], v[190:193], v[50:53]
	v_mfma_f32_16x16x32_bf16 v[34:37], v[142:145], v[198:201], v[34:37]
	v_mfma_f32_16x16x32_bf16 v[34:37], v[146:149], v[206:209], v[34:37]
	v_mfma_f32_16x16x32_bf16 v[30:33], v[162:165], v[206:209], v[30:33]
	v_mfma_f32_16x16x32_bf16 v[30:33], v[150:153], v[198:201], v[30:33]
	v_mfma_f32_16x16x32_bf16 v[10:13], v[150:153], v[210:213], v[10:13]
	v_mfma_f32_16x16x32_bf16 v[10:13], v[162:165], v[214:217], v[10:13]
	v_mfma_f32_16x16x32_bf16 v[18:21], v[146:149], v[214:217], v[18:21]
	v_mfma_f32_16x16x32_bf16 v[18:21], v[142:145], v[210:213], v[18:21]
	s_setprio 0
	s_setprio 1
	v_mfma_f32_16x16x32_bf16 v[58:61], v[166:169], v[182:185], v[58:61]
	v_mfma_f32_16x16x32_bf16 v[58:61], v[170:173], v[186:189], v[58:61]
	v_mfma_f32_16x16x32_bf16 v[54:57], v[178:181], v[186:189], v[54:57]
	v_mfma_f32_16x16x32_bf16 v[54:57], v[174:177], v[182:185], v[54:57]
	v_mfma_f32_16x16x32_bf16 v[38:41], v[174:177], v[190:193], v[38:41]
	v_mfma_f32_16x16x32_bf16 v[38:41], v[178:181], v[194:197], v[38:41]
	v_mfma_f32_16x16x32_bf16 v[42:45], v[170:173], v[194:197], v[42:45]
	v_mfma_f32_16x16x32_bf16 v[42:45], v[166:169], v[190:193], v[42:45]
	v_mfma_f32_16x16x32_bf16 v[26:29], v[166:169], v[198:201], v[26:29]
	v_mfma_f32_16x16x32_bf16 v[26:29], v[170:173], v[206:209], v[26:29]
	v_mfma_f32_16x16x32_bf16 v[22:25], v[178:181], v[206:209], v[22:25]
	v_mfma_f32_16x16x32_bf16 v[22:25], v[174:177], v[198:201], v[22:25]
	v_mfma_f32_16x16x32_bf16 v[2:5], v[174:177], v[210:213], v[2:5]
	v_mfma_f32_16x16x32_bf16 v[2:5], v[178:181], v[214:217], v[2:5]
	v_mfma_f32_16x16x32_bf16 v[6:9], v[170:173], v[214:217], v[6:9]
	v_mfma_f32_16x16x32_bf16 v[6:9], v[166:169], v[210:213], v[6:9]
	s_setprio 0
	s_barrier
	s_add_i32 s55, s55, 2
	s_add_u32 s53, s53, 0x100
	s_addc_u32 s54, s54, 0
	s_add_u32 s26, s26, 0x100
	s_addc_u32 s27, s27, 0
	s_cmp_gt_u32 s55, 29
.LBB0_373:
	s_add_u32 s28, s26, 0xfff80080
	s_addc_u32 s29, s27, -1
	s_add_i32 s33, 0, 0x10000
	s_cmp_eq_u32 s55, 28
	s_cselect_b32 s31, s5, s29
	s_cselect_b32 s30, s11, s28
	v_add_u32_e32 v161, s33, v155
	s_cselect_b32 s29, s19, s54
	s_cselect_b32 s28, s21, s53
	s_add_i32 s58, 0, 0x14000
	ds_read_b128 v[142:145], v161
	ds_read_b128 v[146:149], v161 offset:1024
	ds_read_b128 v[150:153], v161 offset:2048
	ds_read_b128 v[162:165], v161 offset:3072
	v_add_u32_e32 v161, s58, v155
	ds_read_b128 v[166:169], v161
	ds_read_b128 v[170:173], v161 offset:1024
	ds_read_b128 v[174:177], v161 offset:2048
	ds_read_b128 v[178:181], v161 offset:3072
	s_add_i32 m0, s41, 0xc000
	ds_read_b128 v[182:185], v160
	ds_read_b128 v[186:189], v160 offset:1024
	ds_read_b128 v[190:193], v160 offset:2048
	ds_read_b128 v[194:197], v160 offset:3072
	ds_read_b128 v[198:201], v160 offset:4096
	ds_read_b128 v[206:209], v160 offset:5120
	ds_read_b128 v[210:213], v160 offset:6144
	ds_read_b128 v[214:217], v160 offset:7168
	global_load_lds_dwordx4 v140, s[26:27]
	s_add_i32 m0, s41, 0xe000
	s_nop 0
	global_load_lds_dwordx4 v138, s[26:27]
	s_waitcnt vmcnt(8)
	s_waitcnt lgkmcnt(0)
	s_barrier
; #define PG8_STAGE(bufoff, gbase, voff) do { _Pragma("unroll") for (int _i = 0; _i < 2; ++_i) \
;         __builtin_amdgcn_global_load_lds((const unsigned*)((const char*)(gbase) + (voff)[_i]), (PG8_LAS unsigned*)(lds + (bufoff) + ldsw + _i * 8192), 16, 0, 0); } while (0)
; #define PG8_LDA(dst, b, h) do { _Pragma("unroll") for (int m = 0; m < 4; ++m) _Pragma("unroll") for (int k = 0; k < 2; ++k) dst[m][k] = *(const PG8_LAS bf16x8*)(lds + PG8_SA(b, h) + aoff + m * 2048 + k * 1024); } while (0)
; #define PG8_MMA(ai, bj, At, Bt) do { __builtin_amdgcn_s_setprio(1); _Pragma("unroll") for (int m = 0; m < 4; ++m) _Pragma("unroll") for (int n = 0; n < 2; ++n) _Pragma("unroll") for (int k = 0; k < 2; ++k) \
;         acc[ai][bj][m][n] = __builtin_amdgcn_mfma_f32_16x16x32_bf16(Bt[n][k], At[m][k], acc[ai][bj][m][n], 0, 0, 0); __builtin_amdgcn_s_setprio(0); } while (0)
; #define PG8_WAIT_V(n) asm volatile("s_waitcnt vmcnt(" #n ")" ::: "memory")
; #define PG8_WAIT_L(n) asm volatile("s_waitcnt lgkmcnt(" #n ")" ::: "memory")
; #define PG8_BAR __builtin_amdgcn_s_barrier()
; #define PG8_SCHED __builtin_amdgcn_sched_barrier(0)
; template <class Epi, class Sched, bool ALIGN_EPI = false, bool SP2 = false>
; __device__ __forceinline__ void gemm_phase(PG8_LAS unsigned char* lds, const Gemm g, const Sched& S, const Epi& E) {
;     ...
;             PG8_WAIT_V(8); PG8_WAIT_L(0); PG8_BAR; PG8_MMA(0, 0, At, B0); PG8_MMA(0, 1, At, B1); PG8_BAR; PG8_SCHED;
;             PG8_LDA(At, 0, 1); PG8_STAGE(PG8_SB(0, 0), b2, voffB); PG8_STAGE(PG8_SB(0, 1), b2 + hstep, voffB); PG8_STAGE(PG8_SA(0, 0), a2, voffA);
;             PG8_WAIT_V(8); PG8_WAIT_L(0); PG8_BAR; PG8_MMA(1, 0, At, B0); PG8_MMA(1, 1, At, B1); PG8_BAR; PG8_SCHED;
	s_setprio 1
	s_waitcnt lgkmcnt(0)
	v_mfma_f32_16x16x32_bf16 v[130:133], v[142:145], v[182:185], v[130:133]
	v_mfma_f32_16x16x32_bf16 v[130:133], v[146:149], v[186:189], v[130:133]
	v_mfma_f32_16x16x32_bf16 v[126:129], v[162:165], v[186:189], v[126:129]
	v_mfma_f32_16x16x32_bf16 v[126:129], v[150:153], v[182:185], v[126:129]
	v_mfma_f32_16x16x32_bf16 v[110:113], v[150:153], v[190:193], v[110:113]
	v_mfma_f32_16x16x32_bf16 v[110:113], v[162:165], v[194:197], v[110:113]
	v_mfma_f32_16x16x32_bf16 v[114:117], v[146:149], v[194:197], v[114:117]
	v_mfma_f32_16x16x32_bf16 v[114:117], v[142:145], v[190:193], v[114:117]
	v_mfma_f32_16x16x32_bf16 v[98:101], v[142:145], v[198:201], v[98:101]
	v_mfma_f32_16x16x32_bf16 v[98:101], v[146:149], v[206:209], v[98:101]
	v_mfma_f32_16x16x32_bf16 v[94:97], v[162:165], v[206:209], v[94:97]
	v_mfma_f32_16x16x32_bf16 v[94:97], v[150:153], v[198:201], v[94:97]
	v_mfma_f32_16x16x32_bf16 v[78:81], v[150:153], v[210:213], v[78:81]
	v_mfma_f32_16x16x32_bf16 v[78:81], v[162:165], v[214:217], v[78:81]
	v_mfma_f32_16x16x32_bf16 v[82:85], v[146:149], v[214:217], v[82:85]
	v_mfma_f32_16x16x32_bf16 v[82:85], v[142:145], v[210:213], v[82:85]
	s_setprio 0
	s_setprio 1
	v_mfma_f32_16x16x32_bf16 v[122:125], v[166:169], v[182:185], v[122:125]
	v_mfma_f32_16x16x32_bf16 v[122:125], v[170:173], v[186:189], v[122:125]
	v_mfma_f32_16x16x32_bf16 v[118:121], v[178:181], v[186:189], v[118:121]
	v_mfma_f32_16x16x32_bf16 v[118:121], v[174:177], v[182:185], v[118:121]
	v_mfma_f32_16x16x32_bf16 v[102:105], v[174:177], v[190:193], v[102:105]
	v_mfma_f32_16x16x32_bf16 v[102:105], v[178:181], v[194:197], v[102:105]
	v_mfma_f32_16x16x32_bf16 v[106:109], v[170:173], v[194:197], v[106:109]
	v_mfma_f32_16x16x32_bf16 v[106:109], v[166:169], v[190:193], v[106:109]
	v_mfma_f32_16x16x32_bf16 v[90:93], v[166:169], v[198:201], v[90:93]
	v_mfma_f32_16x16x32_bf16 v[90:93], v[170:173], v[206:209], v[90:93]
	v_mfma_f32_16x16x32_bf16 v[86:89], v[178:181], v[206:209], v[86:89]
	v_mfma_f32_16x16x32_bf16 v[86:89], v[174:177], v[198:201], v[86:89]
	v_mfma_f32_16x16x32_bf16 v[70:73], v[174:177], v[210:213], v[70:73]
	v_mfma_f32_16x16x32_bf16 v[70:73], v[178:181], v[214:217], v[70:73]
	v_mfma_f32_16x16x32_bf16 v[74:77], v[170:173], v[214:217], v[74:77]
	v_mfma_f32_16x16x32_bf16 v[74:77], v[166:169], v[210:213], v[74:77]
	s_setprio 0
	s_barrier
	s_add_i32 s33, s33, s39
	s_mov_b32 m0, s33
	ds_read_b128 v[182:185], v160 offset:16384
	ds_read_b128 v[186:189], v160 offset:17408
	ds_read_b128 v[190:193], v160 offset:18432
	ds_read_b128 v[194:197], v160 offset:19456
	ds_read_b128 v[198:201], v160 offset:20480
	ds_read_b128 v[206:209], v160 offset:21504
	ds_read_b128 v[210:213], v160 offset:22528
	ds_read_b128 v[214:217], v160 offset:23552
	global_load_lds_dwordx4 v0, s[28:29]
	s_add_i32 m0, s33, 0x2000
	s_add_u32 s100, s30, 0x80
	s_addc_u32 s101, s31, 0
	s_add_u32 s56, s28, 0x80000
	s_addc_u32 s57, s29, 0
	s_add_i32 s33, s58, s39
	global_load_lds_dwordx4 v14, s[28:29]
	s_mov_b32 m0, s33
	s_nop 0
	global_load_lds_dwordx4 v0, s[56:57]
	s_add_i32 m0, s33, 0x2000
	s_nop 0
	global_load_lds_dwordx4 v14, s[56:57]
	s_mov_b32 m0, s41
	s_nop 0
	global_load_lds_dwordx4 v136, s[30:31]
	s_mov_b32 m0, s42
	s_nop 0
	global_load_lds_dwordx4 v134, s[30:31]
	s_waitcnt vmcnt(8)
	s_waitcnt lgkmcnt(0)
	s_barrier
	s_setprio 1
	s_waitcnt lgkmcnt(0)
	v_mfma_f32_16x16x32_bf16 v[66:69], v[142:145], v[182:185], v[66:69]
	v_mfma_f32_16x16x32_bf16 v[66:69], v[146:149], v[186:189], v[66:69]
	v_mfma_f32_16x16x32_bf16 v[62:65], v[162:165], v[186:189], v[62:65]
	v_mfma_f32_16x16x32_bf16 v[62:65], v[150:153], v[182:185], v[62:65]
	v_mfma_f32_16x16x32_bf16 v[46:49], v[150:153], v[190:193], v[46:49]
	v_mfma_f32_16x16x32_bf16 v[46:49], v[162:165], v[194:197], v[46:49]
	v_mfma_f32_16x16x32_bf16 v[50:53], v[146:149], v[194:197], v[50:53]
	v_mfma_f32_16x16x32_bf16 v[50:53], v[142:145], v[190:193], v[50:53]
	v_mfma_f32_16x16x32_bf16 v[34:37], v[142:145], v[198:201], v[34:37]
	v_mfma_f32_16x16x32_bf16 v[34:37], v[146:149], v[206:209], v[34:37]
	v_mfma_f32_16x16x32_bf16 v[30:33], v[162:165], v[206:209], v[30:33]
	v_mfma_f32_16x16x32_bf16 v[30:33], v[150:153], v[198:201], v[30:33]
	v_mfma_f32_16x16x32_bf16 v[10:13], v[150:153], v[210:213], v[10:13]
	v_mfma_f32_16x16x32_bf16 v[10:13], v[162:165], v[214:217], v[10:13]
	v_mfma_f32_16x16x32_bf16 v[18:21], v[146:149], v[214:217], v[18:21]
	v_mfma_f32_16x16x32_bf16 v[18:21], v[142:145], v[210:213], v[18:21]
	s_setprio 0
	s_setprio 1
	v_mfma_f32_16x16x32_bf16 v[58:61], v[166:169], v[182:185], v[58:61]
	v_mfma_f32_16x16x32_bf16 v[58:61], v[170:173], v[186:189], v[58:61]
	v_mfma_f32_16x16x32_bf16 v[54:57], v[178:181], v[186:189], v[54:57]
	v_mfma_f32_16x16x32_bf16 v[54:57], v[174:177], v[182:185], v[54:57]
	v_mfma_f32_16x16x32_bf16 v[38:41], v[174:177], v[190:193], v[38:41]
	v_mfma_f32_16x16x32_bf16 v[38:41], v[178:181], v[194:197], v[38:41]
	v_mfma_f32_16x16x32_bf16 v[42:45], v[170:173], v[194:197], v[42:45]
	v_mfma_f32_16x16x32_bf16 v[42:45], v[166:169], v[190:193], v[42:45]
	v_mfma_f32_16x16x32_bf16 v[26:29], v[166:169], v[198:201], v[26:29]
	v_mfma_f32_16x16x32_bf16 v[26:29], v[170:173], v[206:209], v[26:29]
	v_mfma_f32_16x16x32_bf16 v[22:25], v[178:181], v[206:209], v[22:25]
	v_mfma_f32_16x16x32_bf16 v[22:25], v[174:177], v[198:201], v[22:25]
	v_mfma_f32_16x16x32_bf16 v[2:5], v[174:177], v[210:213], v[2:5]
	v_mfma_f32_16x16x32_bf16 v[2:5], v[178:181], v[214:217], v[2:5]
	v_mfma_f32_16x16x32_bf16 v[6:9], v[170:173], v[214:217], v[6:9]
	v_mfma_f32_16x16x32_bf16 v[6:9], v[166:169], v[210:213], v[6:9]
	s_setprio 0
	s_barrier
; #define PG8_STAGE(bufoff, gbase, voff) do { _Pragma("unroll") for (int _i = 0; _i < 2; ++_i) \
;         __builtin_amdgcn_global_load_lds((const unsigned*)((const char*)(gbase) + (voff)[_i]), (PG8_LAS unsigned*)(lds + (bufoff) + ldsw + _i * 8192), 16, 0, 0); } while (0)
; #define PG8_LDA(dst, b, h) do { _Pragma("unroll") for (int m = 0; m < 4; ++m) _Pragma("unroll") for (int k = 0; k < 2; ++k) dst[m][k] = *(const PG8_LAS bf16x8*)(lds + PG8_SA(b, h) + aoff + m * 2048 + k * 1024); } while (0)
; #define PG8_LDB(dst, b, h) do { _Pragma("unroll") for (int n = 0; n < 2; ++n) _Pragma("unroll") for (int k = 0; k < 2; ++k) dst[n][k] = *(const PG8_LAS bf16x8*)(lds + PG8_SB(b, h) + boff + n * 2048 + k * 1024); } while (0)
; #define PG8_MMA(ai, bj, At, Bt) do { __builtin_amdgcn_s_setprio(1); _Pragma("unroll") for (int m = 0; m < 4; ++m) _Pragma("unroll") for (int n = 0; n < 2; ++n) _Pragma("unroll") for (int k = 0; k < 2; ++k) \
;         acc[ai][bj][m][n] = __builtin_amdgcn_mfma_f32_16x16x32_bf16(Bt[n][k], At[m][k], acc[ai][bj][m][n], 0, 0, 0); __builtin_amdgcn_s_setprio(0); } while (0)
; #define PG8_WAIT_V(n) asm volatile("s_waitcnt vmcnt(" #n ")" ::: "memory")
; #define PG8_WAIT_L(n) asm volatile("s_waitcnt lgkmcnt(" #n ")" ::: "memory")
; #define PG8_BAR __builtin_amdgcn_s_barrier()
; #define PG8_SCHED __builtin_amdgcn_sched_barrier(0)
; template <class Epi, class Sched, bool ALIGN_EPI = false, bool SP2 = false>
; __device__ __forceinline__ void gemm_phase(PG8_LAS unsigned char* lds, const Gemm g, const Sched& S, const Epi& E) {
;     ...
;             PG8_LDB(B0, 1, 0); PG8_LDB(B1, 1, 1); PG8_SCHED; PG8_LDA(At, 1, 0); PG8_STAGE(PG8_SA(0, 1), a2 + hstep, voffA);
;             PG8_WAIT_V(8); PG8_WAIT_L(0); PG8_BAR; PG8_MMA(0, 0, At, B0); PG8_MMA(0, 1, At, B1); PG8_BAR; PG8_SCHED;
;             PG8_LDA(At, 1, 1); PG8_STAGE(PG8_SB(1, 0), b3, voffB); PG8_STAGE(PG8_SB(1, 1), b3 + hstep, voffB); PG8_STAGE(PG8_SA(1, 0), a3, voffA);
;             PG8_WAIT_V(8); PG8_WAIT_L(0); PG8_BAR; PG8_MMA(1, 0, At, B0); PG8_MMA(1, 1, At, B1); PG8_BAR; PG8_SCHED;
;     ...
;         if constexpr (ALIGN_EPI) { if (wr == 0) PG8_BAR; }
	s_add_i32 s33, 0, 0x18000
	v_add_u32_e32 v161, s33, v155
	s_add_i32 s56, 0, 0x1c000
	ds_read_b128 v[142:145], v161
	ds_read_b128 v[146:149], v161 offset:1024
	ds_read_b128 v[150:153], v161 offset:2048
	ds_read_b128 v[162:165], v161 offset:3072
	v_add_u32_e32 v161, s56, v155
	ds_read_b128 v[166:169], v161
	ds_read_b128 v[170:173], v161 offset:1024
	ds_read_b128 v[174:177], v161 offset:2048
	ds_read_b128 v[178:181], v161 offset:3072
	s_add_u32 s30, s30, 0x80000
	s_addc_u32 s31, s31, 0
	s_mov_b32 m0, s43
	ds_read_b128 v[182:185], v160 offset:32768
	ds_read_b128 v[186:189], v160 offset:33792
	ds_read_b128 v[190:193], v160 offset:34816
	ds_read_b128 v[194:197], v160 offset:35840
	ds_read_b128 v[198:201], v160 offset:36864
	ds_read_b128 v[206:209], v160 offset:37888
	ds_read_b128 v[210:213], v160 offset:38912
	ds_read_b128 v[214:217], v160 offset:39936
	global_load_lds_dwordx4 v136, s[30:31]
	s_mov_b32 m0, s44
	s_nop 0
	global_load_lds_dwordx4 v134, s[30:31]
	s_waitcnt vmcnt(8)
	s_waitcnt lgkmcnt(0)
	s_barrier
	s_setprio 1
	s_waitcnt lgkmcnt(0)
	v_mfma_f32_16x16x32_bf16 v[130:133], v[142:145], v[182:185], v[130:133]
	v_mfma_f32_16x16x32_bf16 v[130:133], v[146:149], v[186:189], v[130:133]
	v_mfma_f32_16x16x32_bf16 v[126:129], v[162:165], v[186:189], v[126:129]
	v_mfma_f32_16x16x32_bf16 v[126:129], v[150:153], v[182:185], v[126:129]
	v_mfma_f32_16x16x32_bf16 v[110:113], v[150:153], v[190:193], v[110:113]
	v_mfma_f32_16x16x32_bf16 v[110:113], v[162:165], v[194:197], v[110:113]
	v_mfma_f32_16x16x32_bf16 v[114:117], v[146:149], v[194:197], v[114:117]
	v_mfma_f32_16x16x32_bf16 v[114:117], v[142:145], v[190:193], v[114:117]
	v_mfma_f32_16x16x32_bf16 v[98:101], v[142:145], v[198:201], v[98:101]
	v_mfma_f32_16x16x32_bf16 v[98:101], v[146:149], v[206:209], v[98:101]
	v_mfma_f32_16x16x32_bf16 v[94:97], v[162:165], v[206:209], v[94:97]
	v_mfma_f32_16x16x32_bf16 v[94:97], v[150:153], v[198:201], v[94:97]
	v_mfma_f32_16x16x32_bf16 v[78:81], v[150:153], v[210:213], v[78:81]
	v_mfma_f32_16x16x32_bf16 v[78:81], v[162:165], v[214:217], v[78:81]
	v_mfma_f32_16x16x32_bf16 v[82:85], v[146:149], v[214:217], v[82:85]
	v_mfma_f32_16x16x32_bf16 v[82:85], v[142:145], v[210:213], v[82:85]
	s_setprio 0
	s_setprio 1
	v_mfma_f32_16x16x32_bf16 v[122:125], v[166:169], v[182:185], v[122:125]
	v_mfma_f32_16x16x32_bf16 v[122:125], v[170:173], v[186:189], v[122:125]
	v_mfma_f32_16x16x32_bf16 v[118:121], v[178:181], v[186:189], v[118:121]
	v_mfma_f32_16x16x32_bf16 v[118:121], v[174:177], v[182:185], v[118:121]
	v_mfma_f32_16x16x32_bf16 v[102:105], v[174:177], v[190:193], v[102:105]
	v_mfma_f32_16x16x32_bf16 v[102:105], v[178:181], v[194:197], v[102:105]
	v_mfma_f32_16x16x32_bf16 v[106:109], v[170:173], v[194:197], v[106:109]
	v_mfma_f32_16x16x32_bf16 v[106:109], v[166:169], v[190:193], v[106:109]
	v_mfma_f32_16x16x32_bf16 v[90:93], v[166:169], v[198:201], v[90:93]
	v_mfma_f32_16x16x32_bf16 v[90:93], v[170:173], v[206:209], v[90:93]
	v_mfma_f32_16x16x32_bf16 v[86:89], v[178:181], v[206:209], v[86:89]
	v_mfma_f32_16x16x32_bf16 v[86:89], v[174:177], v[198:201], v[86:89]
	v_mfma_f32_16x16x32_bf16 v[70:73], v[174:177], v[210:213], v[70:73]
	v_mfma_f32_16x16x32_bf16 v[70:73], v[178:181], v[214:217], v[70:73]
	v_mfma_f32_16x16x32_bf16 v[74:77], v[170:173], v[214:217], v[74:77]
	v_mfma_f32_16x16x32_bf16 v[74:77], v[166:169], v[210:213], v[74:77]
	s_setprio 0
	s_barrier
	s_add_i32 s30, s33, s39
	s_add_i32 m0, s30, 0xffffff80
	ds_read_b128 v[182:185], v160 offset:49152
	ds_read_b128 v[186:189], v160 offset:50176
	ds_read_b128 v[190:193], v160 offset:51200
	ds_read_b128 v[194:197], v160 offset:52224
	ds_read_b128 v[198:201], v160 offset:53248
	ds_read_b128 v[206:209], v160 offset:54272
	ds_read_b128 v[210:213], v160 offset:55296
	ds_read_b128 v[214:217], v160 offset:56320
	global_load_lds_dwordx4 v0, s[28:29] offset:128
	s_add_i32 m0, s30, 0x1f80
	s_add_i32 s30, s56, s39
	global_load_lds_dwordx4 v14, s[28:29] offset:128
	s_add_u32 s28, s28, 0x80080
	s_addc_u32 s29, s29, 0
	s_mov_b32 m0, s30
	s_nop 0
	global_load_lds_dwordx4 v0, s[28:29]
	s_add_i32 m0, s30, 0x2000
	s_nop 0
	global_load_lds_dwordx4 v14, s[28:29]
	s_mov_b32 m0, s46
	s_nop 0
	global_load_lds_dwordx4 v136, s[100:101]
	s_mov_b32 m0, s47
	s_nop 0
	global_load_lds_dwordx4 v134, s[100:101]
	s_waitcnt vmcnt(8)
	s_waitcnt lgkmcnt(0)
	s_barrier
	s_setprio 1
	s_waitcnt lgkmcnt(0)
	v_mfma_f32_16x16x32_bf16 v[66:69], v[142:145], v[182:185], v[66:69]
	v_mfma_f32_16x16x32_bf16 v[66:69], v[146:149], v[186:189], v[66:69]
	v_mfma_f32_16x16x32_bf16 v[62:65], v[162:165], v[186:189], v[62:65]
	v_mfma_f32_16x16x32_bf16 v[62:65], v[150:153], v[182:185], v[62:65]
	v_mfma_f32_16x16x32_bf16 v[46:49], v[150:153], v[190:193], v[46:49]
	v_mfma_f32_16x16x32_bf16 v[46:49], v[162:165], v[194:197], v[46:49]
	v_mfma_f32_16x16x32_bf16 v[50:53], v[146:149], v[194:197], v[50:53]
	v_mfma_f32_16x16x32_bf16 v[50:53], v[142:145], v[190:193], v[50:53]
	v_mfma_f32_16x16x32_bf16 v[34:37], v[142:145], v[198:201], v[34:37]
	v_mfma_f32_16x16x32_bf16 v[34:37], v[146:149], v[206:209], v[34:37]
	v_mfma_f32_16x16x32_bf16 v[30:33], v[162:165], v[206:209], v[30:33]
	v_mfma_f32_16x16x32_bf16 v[30:33], v[150:153], v[198:201], v[30:33]
	v_mfma_f32_16x16x32_bf16 v[10:13], v[150:153], v[210:213], v[10:13]
	v_mfma_f32_16x16x32_bf16 v[10:13], v[162:165], v[214:217], v[10:13]
	v_mfma_f32_16x16x32_bf16 v[18:21], v[146:149], v[214:217], v[18:21]
	v_mfma_f32_16x16x32_bf16 v[18:21], v[142:145], v[210:213], v[18:21]
	s_setprio 0
	s_setprio 1
	v_mfma_f32_16x16x32_bf16 v[58:61], v[166:169], v[182:185], v[58:61]
	v_mfma_f32_16x16x32_bf16 v[58:61], v[170:173], v[186:189], v[58:61]
	v_mfma_f32_16x16x32_bf16 v[54:57], v[178:181], v[186:189], v[54:57]
	v_mfma_f32_16x16x32_bf16 v[54:57], v[174:177], v[182:185], v[54:57]
	v_mfma_f32_16x16x32_bf16 v[38:41], v[174:177], v[190:193], v[38:41]
	v_mfma_f32_16x16x32_bf16 v[38:41], v[178:181], v[194:197], v[38:41]
	v_mfma_f32_16x16x32_bf16 v[42:45], v[170:173], v[194:197], v[42:45]
	v_mfma_f32_16x16x32_bf16 v[42:45], v[166:169], v[190:193], v[42:45]
	v_mfma_f32_16x16x32_bf16 v[26:29], v[166:169], v[198:201], v[26:29]
	v_mfma_f32_16x16x32_bf16 v[26:29], v[170:173], v[206:209], v[26:29]
	v_mfma_f32_16x16x32_bf16 v[22:25], v[178:181], v[206:209], v[22:25]
	v_mfma_f32_16x16x32_bf16 v[22:25], v[174:177], v[198:201], v[22:25]
	v_mfma_f32_16x16x32_bf16 v[2:5], v[174:177], v[210:213], v[2:5]
	v_mfma_f32_16x16x32_bf16 v[2:5], v[178:181], v[214:217], v[2:5]
	v_mfma_f32_16x16x32_bf16 v[6:9], v[170:173], v[214:217], v[6:9]
	v_mfma_f32_16x16x32_bf16 v[6:9], v[166:169], v[210:213], v[6:9]
	s_setprio 0
	s_barrier
	s_add_i32 s55, s55, 2
	s_add_u32 s53, s53, 0x100
	s_addc_u32 s54, s54, 0
	s_add_u32 s26, s26, 0x100
	s_addc_u32 s27, s27, 0
	s_cmp_gt_u32 s55, 29
	s_cbranch_scc0 .LBB0_373
	s_and_b64 vcc, exec, s[14:15]
	s_cbranch_vccz .LBB0_376
	s_barrier

; #define PG8_STAGE(bufoff, gbase, voff) do { _Pragma("unroll") for (int _i = 0; _i < 2; ++_i) \
;         __builtin_amdgcn_global_load_lds((const unsigned*)((const char*)(gbase) + (voff)[_i]), (PG8_LAS unsigned*)(lds + (bufoff) + ldsw + _i * 8192), 16, 0, 0); } while (0)
; #define PG8_LDA(dst, b, h) do { _Pragma("unroll") for (int m = 0; m < 4; ++m) _Pragma("unroll") for (int k = 0; k < 2; ++k) dst[m][k] = *(const PG8_LAS bf16x8*)(lds + PG8_SA(b, h) + aoff + m * 2048 + k * 1024); } while (0)
; #define PG8_LDB(dst, b, h) do { _Pragma("unroll") for (int n = 0; n < 2; ++n) _Pragma("unroll") for (int k = 0; k < 2; ++k) dst[n][k] = *(const PG8_LAS bf16x8*)(lds + PG8_SB(b, h) + boff + n * 2048 + k * 1024); } while (0)
; #define PG8_MMA(ai, bj, At, Bt) do { __builtin_amdgcn_s_setprio(1); _Pragma("unroll") for (int m = 0; m < 4; ++m) _Pragma("unroll") for (int n = 0; n < 2; ++n) _Pragma("unroll") for (int k = 0; k < 2; ++k) \
;         acc[ai][bj][m][n] = __builtin_amdgcn_mfma_f32_16x16x32_bf16(Bt[n][k], At[m][k], acc[ai][bj][m][n], 0, 0, 0); __builtin_amdgcn_s_setprio(0); } while (0)
; #define PG8_WAIT_V(n) asm volatile("s_waitcnt vmcnt(" #n ")" ::: "memory")
; #define PG8_WAIT_L(n) asm volatile("s_waitcnt lgkmcnt(" #n ")" ::: "memory")
; #define PG8_BAR __builtin_amdgcn_s_barrier()
; #define PG8_SCHED __builtin_amdgcn_sched_barrier(0)
; template <class Epi, class Sched, bool ALIGN_EPI = false, bool SP2 = false>
; __device__ __forceinline__ void gemm_phase(PG8_LAS unsigned char* lds, const Gemm g, const Sched& S, const Epi& E) {
;     ...
;             PG8_LDB(B0, 0, 0); PG8_LDB(B1, 0, 1); PG8_SCHED; PG8_LDA(At, 0, 0); PG8_STAGE(PG8_SA(1, 1), a1 + hstep, voffA);
;             PG8_WAIT_V(8); PG8_WAIT_L(0); PG8_BAR; PG8_MMA(0, 0, At, B0); PG8_MMA(0, 1, At, B1); PG8_BAR; PG8_SCHED;
;             PG8_LDA(At, 0, 1); PG8_STAGE(PG8_SB(0, 0), b2, voffB); PG8_STAGE(PG8_SB(0, 1), b2 + hstep, voffB); PG8_STAGE(PG8_SA(0, 0), a2, voffA);
;             PG8_WAIT_V(8); PG8_WAIT_L(0); PG8_BAR; PG8_MMA(1, 0, At, B0); PG8_MMA(1, 1, At, B1); PG8_BAR; PG8_SCHED;
.LBB0_481:
	s_add_u32 s50, s22, 0x100
	s_addc_u32 s51, s23, 0
	s_mov_b32 s52, -2
	s_add_u32 s22, s20, 0x100
	s_addc_u32 s23, s21, 0
	s_add_i32 s33, 0, 0x10000
	s_cmpk_eq_i32 s52, 0x54
	s_cselect_b32 s27, s5, s23
	s_cselect_b32 s26, s4, s22
	s_cselect_b32 s25, s19, s51
	s_cselect_b32 s24, s18, s50
	s_add_i32 s53, 0, 0x14000
	v_add_u32_e32 v138, s33, v199
	v_add_u32_e32 v162, s53, v199
	ds_read_b128 v[118:121], v138
	ds_read_b128 v[130:133], v138 offset:1024
	ds_read_b128 v[134:137], v138 offset:2048
	ds_read_b128 v[138:141], v138 offset:3072
	ds_read_b128 v[146:149], v162
	ds_read_b128 v[154:157], v162 offset:1024
	ds_read_b128 v[158:161], v162 offset:2048
	ds_read_b128 v[162:165], v162 offset:3072
	s_add_i32 m0, s37, 0xc000
	ds_read_b128 v[166:169], v201
	ds_read_b128 v[170:173], v201 offset:1024
	ds_read_b128 v[174:177], v201 offset:2048
	ds_read_b128 v[178:181], v201 offset:3072
	ds_read_b128 v[182:185], v201 offset:4096
	ds_read_b128 v[186:189], v201 offset:5120
	ds_read_b128 v[190:193], v201 offset:6144
	ds_read_b128 v[194:197], v201 offset:7168
	global_load_lds_dwordx4 v212, s[20:21]
	s_add_i32 m0, s37, 0xe000
	s_nop 0
	global_load_lds_dwordx4 v210, s[20:21]
	s_waitcnt vmcnt(8)
	s_waitcnt lgkmcnt(0)
	s_barrier
	s_setprio 1
	s_waitcnt lgkmcnt(0)
	v_mfma_f32_16x16x32_bf16 v[150:153], v[118:121], v[166:169], 0
	v_mfma_f32_16x16x32_bf16 v[150:153], v[130:133], v[170:173], v[150:153]
	v_mfma_f32_16x16x32_bf16 v[142:145], v[138:141], v[170:173], 0
	v_mfma_f32_16x16x32_bf16 v[142:145], v[134:137], v[166:169], v[142:145]
	v_mfma_f32_16x16x32_bf16 v[110:113], v[134:137], v[174:177], 0
	v_mfma_f32_16x16x32_bf16 v[110:113], v[138:141], v[178:181], v[110:113]
	v_mfma_f32_16x16x32_bf16 v[114:117], v[130:133], v[178:181], 0
	v_mfma_f32_16x16x32_bf16 v[114:117], v[118:121], v[174:177], v[114:117]
	v_mfma_f32_16x16x32_bf16 v[98:101], v[118:121], v[182:185], 0
	v_mfma_f32_16x16x32_bf16 v[98:101], v[130:133], v[186:189], v[98:101]
	v_mfma_f32_16x16x32_bf16 v[94:97], v[138:141], v[186:189], 0
	v_mfma_f32_16x16x32_bf16 v[94:97], v[134:137], v[182:185], v[94:97]
	v_mfma_f32_16x16x32_bf16 v[78:81], v[134:137], v[190:193], 0
	v_mfma_f32_16x16x32_bf16 v[78:81], v[138:141], v[194:197], v[78:81]
	v_mfma_f32_16x16x32_bf16 v[82:85], v[130:133], v[194:197], 0
	v_mfma_f32_16x16x32_bf16 v[82:85], v[118:121], v[190:193], v[82:85]
	s_setprio 0
	s_setprio 1
	v_mfma_f32_16x16x32_bf16 v[126:129], v[146:149], v[166:169], 0
	v_mfma_f32_16x16x32_bf16 v[126:129], v[154:157], v[170:173], v[126:129]
	v_mfma_f32_16x16x32_bf16 v[122:125], v[162:165], v[170:173], 0
	v_mfma_f32_16x16x32_bf16 v[122:125], v[158:161], v[166:169], v[122:125]
	v_mfma_f32_16x16x32_bf16 v[102:105], v[158:161], v[174:177], 0
	v_mfma_f32_16x16x32_bf16 v[102:105], v[162:165], v[178:181], v[102:105]
	v_mfma_f32_16x16x32_bf16 v[106:109], v[154:157], v[178:181], 0
	v_mfma_f32_16x16x32_bf16 v[106:109], v[146:149], v[174:177], v[106:109]
	v_mfma_f32_16x16x32_bf16 v[90:93], v[146:149], v[182:185], 0
	v_mfma_f32_16x16x32_bf16 v[90:93], v[154:157], v[186:189], v[90:93]
	v_mfma_f32_16x16x32_bf16 v[86:89], v[162:165], v[186:189], 0
	v_mfma_f32_16x16x32_bf16 v[86:89], v[158:161], v[182:185], v[86:89]
	v_mfma_f32_16x16x32_bf16 v[70:73], v[158:161], v[190:193], 0
	v_mfma_f32_16x16x32_bf16 v[70:73], v[162:165], v[194:197], v[70:73]
	v_mfma_f32_16x16x32_bf16 v[74:77], v[154:157], v[194:197], 0
	v_mfma_f32_16x16x32_bf16 v[74:77], v[146:149], v[190:193], v[74:77]
	s_setprio 0
	s_barrier
	s_add_i32 s20, s33, s36
	s_mov_b32 m0, s20
	ds_read_b128 v[166:169], v201 offset:16384
	ds_read_b128 v[170:173], v201 offset:17408
	ds_read_b128 v[174:177], v201 offset:18432
	ds_read_b128 v[178:181], v201 offset:19456
	ds_read_b128 v[182:185], v201 offset:20480
	ds_read_b128 v[186:189], v201 offset:21504
	ds_read_b128 v[190:193], v201 offset:22528
	ds_read_b128 v[194:197], v201 offset:23552
	global_load_lds_dwordx4 v0, s[24:25]
	s_add_i32 m0, s20, 0x2000
	s_add_u32 s100, s26, 0x80
	s_addc_u32 s101, s27, 0
	s_add_u32 s20, s24, 0x160000
	s_addc_u32 s21, s25, 0
	s_add_i32 s33, s53, s36
	global_load_lds_dwordx4 v208, s[24:25]
	s_mov_b32 m0, s33
	s_nop 0
	global_load_lds_dwordx4 v0, s[20:21]
	s_add_i32 m0, s33, 0x2000
	s_nop 0
	global_load_lds_dwordx4 v208, s[20:21]
	s_mov_b32 m0, s37
	s_nop 0
	global_load_lds_dwordx4 v14, s[26:27]
	s_mov_b32 m0, s38
	s_nop 0
	global_load_lds_dwordx4 v206, s[26:27]
	s_waitcnt vmcnt(8)
	s_waitcnt lgkmcnt(0)
	s_barrier
	s_setprio 1
	s_waitcnt lgkmcnt(0)
	v_mfma_f32_16x16x32_bf16 v[66:69], v[118:121], v[166:169], 0
	v_mfma_f32_16x16x32_bf16 v[66:69], v[130:133], v[170:173], v[66:69]
	v_mfma_f32_16x16x32_bf16 v[62:65], v[138:141], v[170:173], 0
	v_mfma_f32_16x16x32_bf16 v[62:65], v[134:137], v[166:169], v[62:65]
	v_mfma_f32_16x16x32_bf16 v[46:49], v[134:137], v[174:177], 0
	v_mfma_f32_16x16x32_bf16 v[46:49], v[138:141], v[178:181], v[46:49]
	v_mfma_f32_16x16x32_bf16 v[50:53], v[130:133], v[178:181], 0
	v_mfma_f32_16x16x32_bf16 v[50:53], v[118:121], v[174:177], v[50:53]
	v_mfma_f32_16x16x32_bf16 v[34:37], v[118:121], v[182:185], 0
	v_mfma_f32_16x16x32_bf16 v[34:37], v[130:133], v[186:189], v[34:37]
	v_mfma_f32_16x16x32_bf16 v[30:33], v[138:141], v[186:189], 0
	v_mfma_f32_16x16x32_bf16 v[30:33], v[134:137], v[182:185], v[30:33]
	v_mfma_f32_16x16x32_bf16 v[10:13], v[134:137], v[190:193], 0
	v_mfma_f32_16x16x32_bf16 v[10:13], v[138:141], v[194:197], v[10:13]
	v_mfma_f32_16x16x32_bf16 v[18:21], v[130:133], v[194:197], 0
	v_mfma_f32_16x16x32_bf16 v[18:21], v[118:121], v[190:193], v[18:21]
	s_setprio 0
	s_setprio 1
	v_mfma_f32_16x16x32_bf16 v[58:61], v[146:149], v[166:169], 0
	v_mfma_f32_16x16x32_bf16 v[58:61], v[154:157], v[170:173], v[58:61]
	v_mfma_f32_16x16x32_bf16 v[54:57], v[162:165], v[170:173], 0
	v_mfma_f32_16x16x32_bf16 v[54:57], v[158:161], v[166:169], v[54:57]
	v_mfma_f32_16x16x32_bf16 v[38:41], v[158:161], v[174:177], 0
	v_mfma_f32_16x16x32_bf16 v[38:41], v[162:165], v[178:181], v[38:41]
	v_mfma_f32_16x16x32_bf16 v[42:45], v[154:157], v[178:181], 0
	v_mfma_f32_16x16x32_bf16 v[42:45], v[146:149], v[174:177], v[42:45]
	v_mfma_f32_16x16x32_bf16 v[26:29], v[146:149], v[182:185], 0
	v_mfma_f32_16x16x32_bf16 v[26:29], v[154:157], v[186:189], v[26:29]
	v_mfma_f32_16x16x32_bf16 v[22:25], v[162:165], v[186:189], 0
	v_mfma_f32_16x16x32_bf16 v[22:25], v[158:161], v[182:185], v[22:25]
	v_mfma_f32_16x16x32_bf16 v[2:5], v[158:161], v[190:193], 0
	v_mfma_f32_16x16x32_bf16 v[2:5], v[162:165], v[194:197], v[2:5]
	v_mfma_f32_16x16x32_bf16 v[6:9], v[154:157], v[194:197], 0
	v_mfma_f32_16x16x32_bf16 v[6:9], v[146:149], v[190:193], v[6:9]
	s_setprio 0
	s_barrier
; #define PG8_STAGE(bufoff, gbase, voff) do { _Pragma("unroll") for (int _i = 0; _i < 2; ++_i) \
;         __builtin_amdgcn_global_load_lds((const unsigned*)((const char*)(gbase) + (voff)[_i]), (PG8_LAS unsigned*)(lds + (bufoff) + ldsw + _i * 8192), 16, 0, 0); } while (0)
; #define PG8_LDA(dst, b, h) do { _Pragma("unroll") for (int m = 0; m < 4; ++m) _Pragma("unroll") for (int k = 0; k < 2; ++k) dst[m][k] = *(const PG8_LAS bf16x8*)(lds + PG8_SA(b, h) + aoff + m * 2048 + k * 1024); } while (0)
; #define PG8_LDB(dst, b, h) do { _Pragma("unroll") for (int n = 0; n < 2; ++n) _Pragma("unroll") for (int k = 0; k < 2; ++k) dst[n][k] = *(const PG8_LAS bf16x8*)(lds + PG8_SB(b, h) + boff + n * 2048 + k * 1024); } while (0)
; #define PG8_MMA(ai, bj, At, Bt) do { __builtin_amdgcn_s_setprio(1); _Pragma("unroll") for (int m = 0; m < 4; ++m) _Pragma("unroll") for (int n = 0; n < 2; ++n) _Pragma("unroll") for (int k = 0; k < 2; ++k) \
;         acc[ai][bj][m][n] = __builtin_amdgcn_mfma_f32_16x16x32_bf16(Bt[n][k], At[m][k], acc[ai][bj][m][n], 0, 0, 0); __builtin_amdgcn_s_setprio(0); } while (0)
; #define PG8_WAIT_V(n) asm volatile("s_waitcnt vmcnt(" #n ")" ::: "memory")
; #define PG8_WAIT_L(n) asm volatile("s_waitcnt lgkmcnt(" #n ")" ::: "memory")
; #define PG8_BAR __builtin_amdgcn_s_barrier()
; #define PG8_SCHED __builtin_amdgcn_sched_barrier(0)
; template <class Epi, class Sched, bool ALIGN_EPI = false, bool SP2 = false>
; __device__ __forceinline__ void gemm_phase(PG8_LAS unsigned char* lds, const Gemm g, const Sched& S, const Epi& E) {
;     ...
;         for (int t = 0; t < nt; t += 2) {
;     ...
;             PG8_LDB(B0, 1, 0); PG8_LDB(B1, 1, 1); PG8_SCHED; PG8_LDA(At, 1, 0); PG8_STAGE(PG8_SA(0, 1), a2 + hstep, voffA);
;             PG8_WAIT_V(8); PG8_WAIT_L(0); PG8_BAR; PG8_MMA(0, 0, At, B0); PG8_MMA(0, 1, At, B1); PG8_BAR; PG8_SCHED;
;             PG8_LDA(At, 1, 1); PG8_STAGE(PG8_SB(1, 0), b3, voffB); PG8_STAGE(PG8_SB(1, 1), b3 + hstep, voffB); PG8_STAGE(PG8_SA(1, 0), a3, voffA);
;             PG8_WAIT_V(8); PG8_WAIT_L(0); PG8_BAR; PG8_MMA(1, 0, At, B0); PG8_MMA(1, 1, At, B1); PG8_BAR; PG8_SCHED;
	s_add_i32 s33, 0, 0x18000
	s_add_i32 s53, 0, 0x1c000
	v_add_u32_e32 v138, s33, v199
	v_add_u32_e32 v162, s53, v199
	ds_read_b128 v[118:121], v138
	ds_read_b128 v[130:133], v138 offset:1024
	ds_read_b128 v[134:137], v138 offset:2048
	ds_read_b128 v[138:141], v138 offset:3072
	ds_read_b128 v[146:149], v162
	ds_read_b128 v[154:157], v162 offset:1024
	ds_read_b128 v[158:161], v162 offset:2048
	ds_read_b128 v[162:165], v162 offset:3072
	s_add_u32 s20, s26, 0x160000
	s_addc_u32 s21, s27, 0
	s_mov_b32 m0, s39
	ds_read_b128 v[166:169], v201 offset:32768
	ds_read_b128 v[170:173], v201 offset:33792
	ds_read_b128 v[174:177], v201 offset:34816
	ds_read_b128 v[178:181], v201 offset:35840
	ds_read_b128 v[182:185], v201 offset:36864
	ds_read_b128 v[186:189], v201 offset:37888
	ds_read_b128 v[190:193], v201 offset:38912
	ds_read_b128 v[194:197], v201 offset:39936
	global_load_lds_dwordx4 v14, s[20:21]
	s_mov_b32 m0, s40
	s_nop 0
	global_load_lds_dwordx4 v206, s[20:21]
	s_waitcnt vmcnt(8)
	s_waitcnt lgkmcnt(0)
	s_barrier
	s_setprio 1
	s_waitcnt lgkmcnt(0)
	v_mfma_f32_16x16x32_bf16 v[150:153], v[118:121], v[166:169], v[150:153]
	v_mfma_f32_16x16x32_bf16 v[150:153], v[130:133], v[170:173], v[150:153]
	v_mfma_f32_16x16x32_bf16 v[142:145], v[138:141], v[170:173], v[142:145]
	v_mfma_f32_16x16x32_bf16 v[142:145], v[134:137], v[166:169], v[142:145]
	v_mfma_f32_16x16x32_bf16 v[110:113], v[134:137], v[174:177], v[110:113]
	v_mfma_f32_16x16x32_bf16 v[110:113], v[138:141], v[178:181], v[110:113]
	v_mfma_f32_16x16x32_bf16 v[114:117], v[130:133], v[178:181], v[114:117]
	v_mfma_f32_16x16x32_bf16 v[114:117], v[118:121], v[174:177], v[114:117]
	v_mfma_f32_16x16x32_bf16 v[98:101], v[118:121], v[182:185], v[98:101]
	v_mfma_f32_16x16x32_bf16 v[98:101], v[130:133], v[186:189], v[98:101]
	v_mfma_f32_16x16x32_bf16 v[94:97], v[138:141], v[186:189], v[94:97]
	v_mfma_f32_16x16x32_bf16 v[94:97], v[134:137], v[182:185], v[94:97]
	v_mfma_f32_16x16x32_bf16 v[78:81], v[134:137], v[190:193], v[78:81]
	v_mfma_f32_16x16x32_bf16 v[78:81], v[138:141], v[194:197], v[78:81]
	v_mfma_f32_16x16x32_bf16 v[82:85], v[130:133], v[194:197], v[82:85]
	v_mfma_f32_16x16x32_bf16 v[82:85], v[118:121], v[190:193], v[82:85]
	s_setprio 0
	s_setprio 1
	v_mfma_f32_16x16x32_bf16 v[126:129], v[146:149], v[166:169], v[126:129]
	v_mfma_f32_16x16x32_bf16 v[126:129], v[154:157], v[170:173], v[126:129]
	v_mfma_f32_16x16x32_bf16 v[122:125], v[162:165], v[170:173], v[122:125]
	v_mfma_f32_16x16x32_bf16 v[122:125], v[158:161], v[166:169], v[122:125]
	v_mfma_f32_16x16x32_bf16 v[102:105], v[158:161], v[174:177], v[102:105]
	v_mfma_f32_16x16x32_bf16 v[102:105], v[162:165], v[178:181], v[102:105]
	v_mfma_f32_16x16x32_bf16 v[106:109], v[154:157], v[178:181], v[106:109]
	v_mfma_f32_16x16x32_bf16 v[106:109], v[146:149], v[174:177], v[106:109]
	v_mfma_f32_16x16x32_bf16 v[90:93], v[146:149], v[182:185], v[90:93]
	v_mfma_f32_16x16x32_bf16 v[90:93], v[154:157], v[186:189], v[90:93]
	v_mfma_f32_16x16x32_bf16 v[86:89], v[162:165], v[186:189], v[86:89]
	v_mfma_f32_16x16x32_bf16 v[86:89], v[158:161], v[182:185], v[86:89]
	v_mfma_f32_16x16x32_bf16 v[70:73], v[158:161], v[190:193], v[70:73]
	v_mfma_f32_16x16x32_bf16 v[70:73], v[162:165], v[194:197], v[70:73]
	v_mfma_f32_16x16x32_bf16 v[74:77], v[154:157], v[194:197], v[74:77]
	v_mfma_f32_16x16x32_bf16 v[74:77], v[146:149], v[190:193], v[74:77]
	s_setprio 0
	s_barrier
	s_add_i32 s20, s33, s36
	s_add_i32 m0, s20, 0xffffff80
	ds_read_b128 v[166:169], v201 offset:49152
	ds_read_b128 v[170:173], v201 offset:50176
	ds_read_b128 v[174:177], v201 offset:51200
	ds_read_b128 v[178:181], v201 offset:52224
	ds_read_b128 v[182:185], v201 offset:53248
	ds_read_b128 v[186:189], v201 offset:54272
	ds_read_b128 v[190:193], v201 offset:55296
	ds_read_b128 v[194:197], v201 offset:56320
	global_load_lds_dwordx4 v0, s[24:25] offset:128
	s_add_i32 m0, s20, 0x1f80
	s_add_u32 s20, s24, 0x160080
	s_addc_u32 s21, s25, 0
	global_load_lds_dwordx4 v208, s[24:25] offset:128
	s_add_i32 s24, s53, s36
	s_mov_b32 m0, s24
	s_nop 0
	global_load_lds_dwordx4 v0, s[20:21]
	s_add_i32 m0, s24, 0x2000
	s_nop 0
	global_load_lds_dwordx4 v208, s[20:21]
	s_mov_b32 m0, s42
	s_nop 0
	global_load_lds_dwordx4 v14, s[100:101]
	s_mov_b32 m0, s43
	s_nop 0
	global_load_lds_dwordx4 v206, s[100:101]
	s_waitcnt vmcnt(8)
	s_waitcnt lgkmcnt(0)
	s_barrier
	s_setprio 1
	s_waitcnt lgkmcnt(0)
	v_mfma_f32_16x16x32_bf16 v[66:69], v[118:121], v[166:169], v[66:69]
	v_mfma_f32_16x16x32_bf16 v[66:69], v[130:133], v[170:173], v[66:69]
	v_mfma_f32_16x16x32_bf16 v[62:65], v[138:141], v[170:173], v[62:65]
	v_mfma_f32_16x16x32_bf16 v[62:65], v[134:137], v[166:169], v[62:65]
	v_mfma_f32_16x16x32_bf16 v[46:49], v[134:137], v[174:177], v[46:49]
	v_mfma_f32_16x16x32_bf16 v[46:49], v[138:141], v[178:181], v[46:49]
	v_mfma_f32_16x16x32_bf16 v[50:53], v[130:133], v[178:181], v[50:53]
	v_mfma_f32_16x16x32_bf16 v[50:53], v[118:121], v[174:177], v[50:53]
	v_mfma_f32_16x16x32_bf16 v[34:37], v[118:121], v[182:185], v[34:37]
	v_mfma_f32_16x16x32_bf16 v[34:37], v[130:133], v[186:189], v[34:37]
	v_mfma_f32_16x16x32_bf16 v[30:33], v[138:141], v[186:189], v[30:33]
	v_mfma_f32_16x16x32_bf16 v[30:33], v[134:137], v[182:185], v[30:33]
	v_mfma_f32_16x16x32_bf16 v[10:13], v[134:137], v[190:193], v[10:13]
	v_mfma_f32_16x16x32_bf16 v[10:13], v[138:141], v[194:197], v[10:13]
	v_mfma_f32_16x16x32_bf16 v[18:21], v[130:133], v[194:197], v[18:21]
	v_mfma_f32_16x16x32_bf16 v[18:21], v[118:121], v[190:193], v[18:21]
	s_setprio 0
	s_setprio 1
	v_mfma_f32_16x16x32_bf16 v[58:61], v[146:149], v[166:169], v[58:61]
	v_mfma_f32_16x16x32_bf16 v[58:61], v[154:157], v[170:173], v[58:61]
	v_mfma_f32_16x16x32_bf16 v[54:57], v[162:165], v[170:173], v[54:57]
	v_mfma_f32_16x16x32_bf16 v[54:57], v[158:161], v[166:169], v[54:57]
	v_mfma_f32_16x16x32_bf16 v[38:41], v[158:161], v[174:177], v[38:41]
	v_mfma_f32_16x16x32_bf16 v[38:41], v[162:165], v[178:181], v[38:41]
	v_mfma_f32_16x16x32_bf16 v[42:45], v[154:157], v[178:181], v[42:45]
	v_mfma_f32_16x16x32_bf16 v[42:45], v[146:149], v[174:177], v[42:45]
	v_mfma_f32_16x16x32_bf16 v[26:29], v[146:149], v[182:185], v[26:29]
	v_mfma_f32_16x16x32_bf16 v[26:29], v[154:157], v[186:189], v[26:29]
	v_mfma_f32_16x16x32_bf16 v[22:25], v[162:165], v[186:189], v[22:25]
	v_mfma_f32_16x16x32_bf16 v[22:25], v[158:161], v[182:185], v[22:25]
	v_mfma_f32_16x16x32_bf16 v[2:5], v[158:161], v[190:193], v[2:5]
	v_mfma_f32_16x16x32_bf16 v[2:5], v[162:165], v[194:197], v[2:5]
	v_mfma_f32_16x16x32_bf16 v[6:9], v[154:157], v[194:197], v[6:9]
	v_mfma_f32_16x16x32_bf16 v[6:9], v[146:149], v[190:193], v[6:9]
	s_setprio 0
	s_barrier
	s_add_i32 s52, s52, 2
	s_add_u32 s50, s50, 0x100
	s_addc_u32 s51, s51, 0
	s_cmpk_gt_u32 s52, 0x55
	s_mov_b64 s[20:21], s[22:23]
; #define PG8_STAGE(bufoff, gbase, voff) do { _Pragma("unroll") for (int _i = 0; _i < 2; ++_i) \
;         __builtin_amdgcn_global_load_lds((const unsigned*)((const char*)(gbase) + (voff)[_i]), (PG8_LAS unsigned*)(lds + (bufoff) + ldsw + _i * 8192), 16, 0, 0); } while (0)
; #define PG8_LDA(dst, b, h) do { _Pragma("unroll") for (int m = 0; m < 4; ++m) _Pragma("unroll") for (int k = 0; k < 2; ++k) dst[m][k] = *(const PG8_LAS bf16x8*)(lds + PG8_SA(b, h) + aoff + m * 2048 + k * 1024); } while (0)
; #define PG8_LDB(dst, b, h) do { _Pragma("unroll") for (int n = 0; n < 2; ++n) _Pragma("unroll") for (int k = 0; k < 2; ++k) dst[n][k] = *(const PG8_LAS bf16x8*)(lds + PG8_SB(b, h) + boff + n * 2048 + k * 1024); } while (0)
; #define PG8_MMA(ai, bj, At, Bt) do { __builtin_amdgcn_s_setprio(1); _Pragma("unroll") for (int m = 0; m < 4; ++m) _Pragma("unroll") for (int n = 0; n < 2; ++n) _Pragma("unroll") for (int k = 0; k < 2; ++k) \
;         acc[ai][bj][m][n] = __builtin_amdgcn_mfma_f32_16x16x32_bf16(Bt[n][k], At[m][k], acc[ai][bj][m][n], 0, 0, 0); __builtin_amdgcn_s_setprio(0); } while (0)
; #define PG8_WAIT_V(n) asm volatile("s_waitcnt vmcnt(" #n ")" ::: "memory")
; #define PG8_WAIT_L(n) asm volatile("s_waitcnt lgkmcnt(" #n ")" ::: "memory")
; #define PG8_BAR __builtin_amdgcn_s_barrier()
; #define PG8_SCHED __builtin_amdgcn_sched_barrier(0)
; template <class Epi, class Sched, bool ALIGN_EPI = false, bool SP2 = false>
; __device__ __forceinline__ void gemm_phase(PG8_LAS unsigned char* lds, const Gemm g, const Sched& S, const Epi& E) {
;     ...
;             PG8_LDB(B0, 0, 0); PG8_LDB(B1, 0, 1); PG8_SCHED; PG8_LDA(At, 0, 0); PG8_STAGE(PG8_SA(1, 1), a1 + hstep, voffA);
;             PG8_WAIT_V(8); PG8_WAIT_L(0); PG8_BAR; PG8_MMA(0, 0, At, B0); PG8_MMA(0, 1, At, B1); PG8_BAR; PG8_SCHED;
;             PG8_LDA(At, 0, 1); PG8_STAGE(PG8_SB(0, 0), b2, voffB); PG8_STAGE(PG8_SB(0, 1), b2 + hstep, voffB); PG8_STAGE(PG8_SA(0, 0), a2, voffA);
;             PG8_WAIT_V(8); PG8_WAIT_L(0); PG8_BAR; PG8_MMA(1, 0, At, B0); PG8_MMA(1, 1, At, B1); PG8_BAR; PG8_SCHED;
.LBB0_482:
	s_add_u32 s22, s20, 0x100
	s_addc_u32 s23, s21, 0
	s_add_i32 s33, 0, 0x10000
	s_cmpk_eq_i32 s52, 0x54
	s_cselect_b32 s27, s5, s23
	s_cselect_b32 s26, s4, s22
	s_cselect_b32 s25, s19, s51
	s_cselect_b32 s24, s18, s50
	s_add_i32 s53, 0, 0x14000
	v_add_u32_e32 v138, s33, v199
	v_add_u32_e32 v162, s53, v199
	ds_read_b128 v[118:121], v138
	ds_read_b128 v[130:133], v138 offset:1024
	ds_read_b128 v[134:137], v138 offset:2048
	ds_read_b128 v[138:141], v138 offset:3072
	ds_read_b128 v[146:149], v162
	ds_read_b128 v[154:157], v162 offset:1024
	ds_read_b128 v[158:161], v162 offset:2048
	ds_read_b128 v[162:165], v162 offset:3072
	s_add_i32 m0, s37, 0xc000
	ds_read_b128 v[166:169], v201
	ds_read_b128 v[170:173], v201 offset:1024
	ds_read_b128 v[174:177], v201 offset:2048
	ds_read_b128 v[178:181], v201 offset:3072
	ds_read_b128 v[182:185], v201 offset:4096
	ds_read_b128 v[186:189], v201 offset:5120
	ds_read_b128 v[190:193], v201 offset:6144
	ds_read_b128 v[194:197], v201 offset:7168
	global_load_lds_dwordx4 v212, s[20:21]
	s_add_i32 m0, s37, 0xe000
	s_nop 0
	global_load_lds_dwordx4 v210, s[20:21]
	s_waitcnt vmcnt(8)
	s_waitcnt lgkmcnt(0)
	s_barrier
	s_setprio 1
	s_waitcnt lgkmcnt(0)
	v_mfma_f32_16x16x32_bf16 v[150:153], v[118:121], v[166:169], v[150:153]
	v_mfma_f32_16x16x32_bf16 v[150:153], v[130:133], v[170:173], v[150:153]
	v_mfma_f32_16x16x32_bf16 v[142:145], v[138:141], v[170:173], v[142:145]
	v_mfma_f32_16x16x32_bf16 v[142:145], v[134:137], v[166:169], v[142:145]
	v_mfma_f32_16x16x32_bf16 v[110:113], v[134:137], v[174:177], v[110:113]
	v_mfma_f32_16x16x32_bf16 v[110:113], v[138:141], v[178:181], v[110:113]
	v_mfma_f32_16x16x32_bf16 v[114:117], v[130:133], v[178:181], v[114:117]
	v_mfma_f32_16x16x32_bf16 v[114:117], v[118:121], v[174:177], v[114:117]
	v_mfma_f32_16x16x32_bf16 v[98:101], v[118:121], v[182:185], v[98:101]
	v_mfma_f32_16x16x32_bf16 v[98:101], v[130:133], v[186:189], v[98:101]
	v_mfma_f32_16x16x32_bf16 v[94:97], v[138:141], v[186:189], v[94:97]
	v_mfma_f32_16x16x32_bf16 v[94:97], v[134:137], v[182:185], v[94:97]
	v_mfma_f32_16x16x32_bf16 v[78:81], v[134:137], v[190:193], v[78:81]
	v_mfma_f32_16x16x32_bf16 v[78:81], v[138:141], v[194:197], v[78:81]
	v_mfma_f32_16x16x32_bf16 v[82:85], v[130:133], v[194:197], v[82:85]
	v_mfma_f32_16x16x32_bf16 v[82:85], v[118:121], v[190:193], v[82:85]
	s_setprio 0
	s_setprio 1
	v_mfma_f32_16x16x32_bf16 v[126:129], v[146:149], v[166:169], v[126:129]
	v_mfma_f32_16x16x32_bf16 v[126:129], v[154:157], v[170:173], v[126:129]
	v_mfma_f32_16x16x32_bf16 v[122:125], v[162:165], v[170:173], v[122:125]
	v_mfma_f32_16x16x32_bf16 v[122:125], v[158:161], v[166:169], v[122:125]
	v_mfma_f32_16x16x32_bf16 v[102:105], v[158:161], v[174:177], v[102:105]
	v_mfma_f32_16x16x32_bf16 v[102:105], v[162:165], v[178:181], v[102:105]
	v_mfma_f32_16x16x32_bf16 v[106:109], v[154:157], v[178:181], v[106:109]
	v_mfma_f32_16x16x32_bf16 v[106:109], v[146:149], v[174:177], v[106:109]
	v_mfma_f32_16x16x32_bf16 v[90:93], v[146:149], v[182:185], v[90:93]
	v_mfma_f32_16x16x32_bf16 v[90:93], v[154:157], v[186:189], v[90:93]
	v_mfma_f32_16x16x32_bf16 v[86:89], v[162:165], v[186:189], v[86:89]
	v_mfma_f32_16x16x32_bf16 v[86:89], v[158:161], v[182:185], v[86:89]
	v_mfma_f32_16x16x32_bf16 v[70:73], v[158:161], v[190:193], v[70:73]
	v_mfma_f32_16x16x32_bf16 v[70:73], v[162:165], v[194:197], v[70:73]
	v_mfma_f32_16x16x32_bf16 v[74:77], v[154:157], v[194:197], v[74:77]
	v_mfma_f32_16x16x32_bf16 v[74:77], v[146:149], v[190:193], v[74:77]
	s_setprio 0
	s_barrier
	s_add_i32 s20, s33, s36
	s_mov_b32 m0, s20
	ds_read_b128 v[166:169], v201 offset:16384
	ds_read_b128 v[170:173], v201 offset:17408
	ds_read_b128 v[174:177], v201 offset:18432
	ds_read_b128 v[178:181], v201 offset:19456
	ds_read_b128 v[182:185], v201 offset:20480
	ds_read_b128 v[186:189], v201 offset:21504
	ds_read_b128 v[190:193], v201 offset:22528
	ds_read_b128 v[194:197], v201 offset:23552
	global_load_lds_dwordx4 v0, s[24:25]
	s_add_i32 m0, s20, 0x2000
	s_add_u32 s100, s26, 0x80
	s_addc_u32 s101, s27, 0
	s_add_u32 s20, s24, 0x160000
	s_addc_u32 s21, s25, 0
	s_add_i32 s33, s53, s36
	global_load_lds_dwordx4 v208, s[24:25]
	s_mov_b32 m0, s33
	s_nop 0
	global_load_lds_dwordx4 v0, s[20:21]
	s_add_i32 m0, s33, 0x2000
	s_nop 0
	global_load_lds_dwordx4 v208, s[20:21]
	s_mov_b32 m0, s37
	s_nop 0
	global_load_lds_dwordx4 v14, s[26:27]
	s_mov_b32 m0, s38
	s_nop 0
	global_load_lds_dwordx4 v206, s[26:27]
	s_waitcnt vmcnt(8)
	s_waitcnt lgkmcnt(0)
	s_barrier
	s_setprio 1
	s_waitcnt lgkmcnt(0)
	v_mfma_f32_16x16x32_bf16 v[66:69], v[118:121], v[166:169], v[66:69]
	v_mfma_f32_16x16x32_bf16 v[66:69], v[130:133], v[170:173], v[66:69]
	v_mfma_f32_16x16x32_bf16 v[62:65], v[138:141], v[170:173], v[62:65]
	v_mfma_f32_16x16x32_bf16 v[62:65], v[134:137], v[166:169], v[62:65]
	v_mfma_f32_16x16x32_bf16 v[46:49], v[134:137], v[174:177], v[46:49]
	v_mfma_f32_16x16x32_bf16 v[46:49], v[138:141], v[178:181], v[46:49]
	v_mfma_f32_16x16x32_bf16 v[50:53], v[130:133], v[178:181], v[50:53]
	v_mfma_f32_16x16x32_bf16 v[50:53], v[118:121], v[174:177], v[50:53]
	v_mfma_f32_16x16x32_bf16 v[34:37], v[118:121], v[182:185], v[34:37]
	v_mfma_f32_16x16x32_bf16 v[34:37], v[130:133], v[186:189], v[34:37]
	v_mfma_f32_16x16x32_bf16 v[30:33], v[138:141], v[186:189], v[30:33]
	v_mfma_f32_16x16x32_bf16 v[30:33], v[134:137], v[182:185], v[30:33]
	v_mfma_f32_16x16x32_bf16 v[10:13], v[134:137], v[190:193], v[10:13]
	v_mfma_f32_16x16x32_bf16 v[10:13], v[138:141], v[194:197], v[10:13]
	v_mfma_f32_16x16x32_bf16 v[18:21], v[130:133], v[194:197], v[18:21]
	v_mfma_f32_16x16x32_bf16 v[18:21], v[118:121], v[190:193], v[18:21]
	s_setprio 0
	s_setprio 1
	v_mfma_f32_16x16x32_bf16 v[58:61], v[146:149], v[166:169], v[58:61]
	v_mfma_f32_16x16x32_bf16 v[58:61], v[154:157], v[170:173], v[58:61]
	v_mfma_f32_16x16x32_bf16 v[54:57], v[162:165], v[170:173], v[54:57]
	v_mfma_f32_16x16x32_bf16 v[54:57], v[158:161], v[166:169], v[54:57]
	v_mfma_f32_16x16x32_bf16 v[38:41], v[158:161], v[174:177], v[38:41]
	v_mfma_f32_16x16x32_bf16 v[38:41], v[162:165], v[178:181], v[38:41]
	v_mfma_f32_16x16x32_bf16 v[42:45], v[154:157], v[178:181], v[42:45]
	v_mfma_f32_16x16x32_bf16 v[42:45], v[146:149], v[174:177], v[42:45]
	v_mfma_f32_16x16x32_bf16 v[26:29], v[146:149], v[182:185], v[26:29]
	v_mfma_f32_16x16x32_bf16 v[26:29], v[154:157], v[186:189], v[26:29]
	v_mfma_f32_16x16x32_bf16 v[22:25], v[162:165], v[186:189], v[22:25]
	v_mfma_f32_16x16x32_bf16 v[22:25], v[158:161], v[182:185], v[22:25]
	v_mfma_f32_16x16x32_bf16 v[2:5], v[158:161], v[190:193], v[2:5]
	v_mfma_f32_16x16x32_bf16 v[2:5], v[162:165], v[194:197], v[2:5]
	v_mfma_f32_16x16x32_bf16 v[6:9], v[154:157], v[194:197], v[6:9]
	v_mfma_f32_16x16x32_bf16 v[6:9], v[146:149], v[190:193], v[6:9]
	s_setprio 0
	s_barrier
; #define PG8_STAGE(bufoff, gbase, voff) do { _Pragma("unroll") for (int _i = 0; _i < 2; ++_i) \
;         __builtin_amdgcn_global_load_lds((const unsigned*)((const char*)(gbase) + (voff)[_i]), (PG8_LAS unsigned*)(lds + (bufoff) + ldsw + _i * 8192), 16, 0, 0); } while (0)
; #define PG8_LDA(dst, b, h) do { _Pragma("unroll") for (int m = 0; m < 4; ++m) _Pragma("unroll") for (int k = 0; k < 2; ++k) dst[m][k] = *(const PG8_LAS bf16x8*)(lds + PG8_SA(b, h) + aoff + m * 2048 + k * 1024); } while (0)
; #define PG8_LDB(dst, b, h) do { _Pragma("unroll") for (int n = 0; n < 2; ++n) _Pragma("unroll") for (int k = 0; k < 2; ++k) dst[n][k] = *(const PG8_LAS bf16x8*)(lds + PG8_SB(b, h) + boff + n * 2048 + k * 1024); } while (0)
; #define PG8_MMA(ai, bj, At, Bt) do { __builtin_amdgcn_s_setprio(1); _Pragma("unroll") for (int m = 0; m < 4; ++m) _Pragma("unroll") for (int n = 0; n < 2; ++n) _Pragma("unroll") for (int k = 0; k < 2; ++k) \
;         acc[ai][bj][m][n] = __builtin_amdgcn_mfma_f32_16x16x32_bf16(Bt[n][k], At[m][k], acc[ai][bj][m][n], 0, 0, 0); __builtin_amdgcn_s_setprio(0); } while (0)
; #define PG8_WAIT_V(n) asm volatile("s_waitcnt vmcnt(" #n ")" ::: "memory")
; #define PG8_WAIT_L(n) asm volatile("s_waitcnt lgkmcnt(" #n ")" ::: "memory")
; #define PG8_BAR __builtin_amdgcn_s_barrier()
; #define PG8_SCHED __builtin_amdgcn_sched_barrier(0)
; template <class Epi, class Sched, bool ALIGN_EPI = false, bool SP2 = false>
; __device__ __forceinline__ void gemm_phase(PG8_LAS unsigned char* lds, const Gemm g, const Sched& S, const Epi& E) {
;     ...
;             PG8_LDB(B0, 1, 0); PG8_LDB(B1, 1, 1); PG8_SCHED; PG8_LDA(At, 1, 0); PG8_STAGE(PG8_SA(0, 1), a2 + hstep, voffA);
;             PG8_WAIT_V(8); PG8_WAIT_L(0); PG8_BAR; PG8_MMA(0, 0, At, B0); PG8_MMA(0, 1, At, B1); PG8_BAR; PG8_SCHED;
;             PG8_LDA(At, 1, 1); PG8_STAGE(PG8_SB(1, 0), b3, voffB); PG8_STAGE(PG8_SB(1, 1), b3 + hstep, voffB); PG8_STAGE(PG8_SA(1, 0), a3, voffA);
;             PG8_WAIT_V(8); PG8_WAIT_L(0); PG8_BAR; PG8_MMA(1, 0, At, B0); PG8_MMA(1, 1, At, B1); PG8_BAR; PG8_SCHED;
;     ...
;         if constexpr (ALIGN_EPI) { if (wr == 0) PG8_BAR; }
	s_add_i32 s33, 0, 0x18000
	s_add_i32 s53, 0, 0x1c000
	v_add_u32_e32 v138, s33, v199
	v_add_u32_e32 v162, s53, v199
	ds_read_b128 v[118:121], v138
	ds_read_b128 v[130:133], v138 offset:1024
	ds_read_b128 v[134:137], v138 offset:2048
	ds_read_b128 v[138:141], v138 offset:3072
	ds_read_b128 v[146:149], v162
	ds_read_b128 v[154:157], v162 offset:1024
	ds_read_b128 v[158:161], v162 offset:2048
	ds_read_b128 v[162:165], v162 offset:3072
	s_add_u32 s20, s26, 0x160000
	s_addc_u32 s21, s27, 0
	s_mov_b32 m0, s39
	ds_read_b128 v[166:169], v201 offset:32768
	ds_read_b128 v[170:173], v201 offset:33792
	ds_read_b128 v[174:177], v201 offset:34816
	ds_read_b128 v[178:181], v201 offset:35840
	ds_read_b128 v[182:185], v201 offset:36864
	ds_read_b128 v[186:189], v201 offset:37888
	ds_read_b128 v[190:193], v201 offset:38912
	ds_read_b128 v[194:197], v201 offset:39936
	global_load_lds_dwordx4 v14, s[20:21]
	s_mov_b32 m0, s40
	s_nop 0
	global_load_lds_dwordx4 v206, s[20:21]
	s_waitcnt vmcnt(8)
	s_waitcnt lgkmcnt(0)
	s_barrier
	s_setprio 1
	s_waitcnt lgkmcnt(0)
	v_mfma_f32_16x16x32_bf16 v[150:153], v[118:121], v[166:169], v[150:153]
	v_mfma_f32_16x16x32_bf16 v[150:153], v[130:133], v[170:173], v[150:153]
	v_mfma_f32_16x16x32_bf16 v[142:145], v[138:141], v[170:173], v[142:145]
	v_mfma_f32_16x16x32_bf16 v[142:145], v[134:137], v[166:169], v[142:145]
	v_mfma_f32_16x16x32_bf16 v[110:113], v[134:137], v[174:177], v[110:113]
	v_mfma_f32_16x16x32_bf16 v[110:113], v[138:141], v[178:181], v[110:113]
	v_mfma_f32_16x16x32_bf16 v[114:117], v[130:133], v[178:181], v[114:117]
	v_mfma_f32_16x16x32_bf16 v[114:117], v[118:121], v[174:177], v[114:117]
	v_mfma_f32_16x16x32_bf16 v[98:101], v[118:121], v[182:185], v[98:101]
	v_mfma_f32_16x16x32_bf16 v[98:101], v[130:133], v[186:189], v[98:101]
	v_mfma_f32_16x16x32_bf16 v[94:97], v[138:141], v[186:189], v[94:97]
	v_mfma_f32_16x16x32_bf16 v[94:97], v[134:137], v[182:185], v[94:97]
	v_mfma_f32_16x16x32_bf16 v[78:81], v[134:137], v[190:193], v[78:81]
	v_mfma_f32_16x16x32_bf16 v[78:81], v[138:141], v[194:197], v[78:81]
	v_mfma_f32_16x16x32_bf16 v[82:85], v[130:133], v[194:197], v[82:85]
	v_mfma_f32_16x16x32_bf16 v[82:85], v[118:121], v[190:193], v[82:85]
	s_setprio 0
	s_setprio 1
	v_mfma_f32_16x16x32_bf16 v[126:129], v[146:149], v[166:169], v[126:129]
	v_mfma_f32_16x16x32_bf16 v[126:129], v[154:157], v[170:173], v[126:129]
	v_mfma_f32_16x16x32_bf16 v[122:125], v[162:165], v[170:173], v[122:125]
	v_mfma_f32_16x16x32_bf16 v[122:125], v[158:161], v[166:169], v[122:125]
	v_mfma_f32_16x16x32_bf16 v[102:105], v[158:161], v[174:177], v[102:105]
	v_mfma_f32_16x16x32_bf16 v[102:105], v[162:165], v[178:181], v[102:105]
	v_mfma_f32_16x16x32_bf16 v[106:109], v[154:157], v[178:181], v[106:109]
	v_mfma_f32_16x16x32_bf16 v[106:109], v[146:149], v[174:177], v[106:109]
	v_mfma_f32_16x16x32_bf16 v[90:93], v[146:149], v[182:185], v[90:93]
	v_mfma_f32_16x16x32_bf16 v[90:93], v[154:157], v[186:189], v[90:93]
	v_mfma_f32_16x16x32_bf16 v[86:89], v[162:165], v[186:189], v[86:89]
	v_mfma_f32_16x16x32_bf16 v[86:89], v[158:161], v[182:185], v[86:89]
	v_mfma_f32_16x16x32_bf16 v[70:73], v[158:161], v[190:193], v[70:73]
	v_mfma_f32_16x16x32_bf16 v[70:73], v[162:165], v[194:197], v[70:73]
	v_mfma_f32_16x16x32_bf16 v[74:77], v[154:157], v[194:197], v[74:77]
	v_mfma_f32_16x16x32_bf16 v[74:77], v[146:149], v[190:193], v[74:77]
	s_setprio 0
	s_barrier
	s_add_i32 s20, s33, s36
	s_add_i32 m0, s20, 0xffffff80
	ds_read_b128 v[166:169], v201 offset:49152
	ds_read_b128 v[170:173], v201 offset:50176
	ds_read_b128 v[174:177], v201 offset:51200
	ds_read_b128 v[178:181], v201 offset:52224
	ds_read_b128 v[182:185], v201 offset:53248
	ds_read_b128 v[186:189], v201 offset:54272
	ds_read_b128 v[190:193], v201 offset:55296
	ds_read_b128 v[194:197], v201 offset:56320
	global_load_lds_dwordx4 v0, s[24:25] offset:128
	s_add_i32 m0, s20, 0x1f80
	s_add_u32 s20, s24, 0x160080
	s_addc_u32 s21, s25, 0
	global_load_lds_dwordx4 v208, s[24:25] offset:128
	s_add_i32 s24, s53, s36
	s_mov_b32 m0, s24
	s_nop 0
	global_load_lds_dwordx4 v0, s[20:21]
	s_add_i32 m0, s24, 0x2000
	s_nop 0
	global_load_lds_dwordx4 v208, s[20:21]
	s_mov_b32 m0, s42
	s_nop 0
	global_load_lds_dwordx4 v14, s[100:101]
	s_mov_b32 m0, s43
	s_nop 0
	global_load_lds_dwordx4 v206, s[100:101]
	s_waitcnt vmcnt(8)
	s_waitcnt lgkmcnt(0)
	s_barrier
	s_setprio 1
	s_waitcnt lgkmcnt(0)
	v_mfma_f32_16x16x32_bf16 v[66:69], v[118:121], v[166:169], v[66:69]
	v_mfma_f32_16x16x32_bf16 v[66:69], v[130:133], v[170:173], v[66:69]
	v_mfma_f32_16x16x32_bf16 v[62:65], v[138:141], v[170:173], v[62:65]
	v_mfma_f32_16x16x32_bf16 v[62:65], v[134:137], v[166:169], v[62:65]
	v_mfma_f32_16x16x32_bf16 v[46:49], v[134:137], v[174:177], v[46:49]
	v_mfma_f32_16x16x32_bf16 v[46:49], v[138:141], v[178:181], v[46:49]
	v_mfma_f32_16x16x32_bf16 v[50:53], v[130:133], v[178:181], v[50:53]
	v_mfma_f32_16x16x32_bf16 v[50:53], v[118:121], v[174:177], v[50:53]
	v_mfma_f32_16x16x32_bf16 v[34:37], v[118:121], v[182:185], v[34:37]
	v_mfma_f32_16x16x32_bf16 v[34:37], v[130:133], v[186:189], v[34:37]
	v_mfma_f32_16x16x32_bf16 v[30:33], v[138:141], v[186:189], v[30:33]
	v_mfma_f32_16x16x32_bf16 v[30:33], v[134:137], v[182:185], v[30:33]
	v_mfma_f32_16x16x32_bf16 v[10:13], v[134:137], v[190:193], v[10:13]
	v_mfma_f32_16x16x32_bf16 v[10:13], v[138:141], v[194:197], v[10:13]
	v_mfma_f32_16x16x32_bf16 v[18:21], v[130:133], v[194:197], v[18:21]
	v_mfma_f32_16x16x32_bf16 v[18:21], v[118:121], v[190:193], v[18:21]
	s_setprio 0
	s_setprio 1
	v_mfma_f32_16x16x32_bf16 v[58:61], v[146:149], v[166:169], v[58:61]
	v_mfma_f32_16x16x32_bf16 v[58:61], v[154:157], v[170:173], v[58:61]
	v_mfma_f32_16x16x32_bf16 v[54:57], v[162:165], v[170:173], v[54:57]
	v_mfma_f32_16x16x32_bf16 v[54:57], v[158:161], v[166:169], v[54:57]
	v_mfma_f32_16x16x32_bf16 v[38:41], v[158:161], v[174:177], v[38:41]
	v_mfma_f32_16x16x32_bf16 v[38:41], v[162:165], v[178:181], v[38:41]
	v_mfma_f32_16x16x32_bf16 v[42:45], v[154:157], v[178:181], v[42:45]
	v_mfma_f32_16x16x32_bf16 v[42:45], v[146:149], v[174:177], v[42:45]
	v_mfma_f32_16x16x32_bf16 v[26:29], v[146:149], v[182:185], v[26:29]
	v_mfma_f32_16x16x32_bf16 v[26:29], v[154:157], v[186:189], v[26:29]
	v_mfma_f32_16x16x32_bf16 v[22:25], v[162:165], v[186:189], v[22:25]
	v_mfma_f32_16x16x32_bf16 v[22:25], v[158:161], v[182:185], v[22:25]
	v_mfma_f32_16x16x32_bf16 v[2:5], v[158:161], v[190:193], v[2:5]
	v_mfma_f32_16x16x32_bf16 v[2:5], v[162:165], v[194:197], v[2:5]
	v_mfma_f32_16x16x32_bf16 v[6:9], v[154:157], v[194:197], v[6:9]
	v_mfma_f32_16x16x32_bf16 v[6:9], v[146:149], v[190:193], v[6:9]
	s_setprio 0
	s_barrier
	s_add_i32 s52, s52, 2
	s_add_u32 s50, s50, 0x100
	s_addc_u32 s51, s51, 0
	s_cmpk_gt_u32 s52, 0x55
	s_mov_b64 s[20:21], s[22:23]
	s_cbranch_scc0 .LBB0_482
	s_and_b64 vcc, exec, s[14:15]
	s_cbranch_vccz .LBB0_485
	s_barrier

; #define PG8_STAGE(bufoff, gbase, voff) do { _Pragma("unroll") for (int _i = 0; _i < 2; ++_i) \
;         __builtin_amdgcn_global_load_lds((const unsigned*)((const char*)(gbase) + (voff)[_i]), (PG8_LAS unsigned*)(lds + (bufoff) + ldsw + _i * 8192), 16, 0, 0); } while (0)
; #define PG8_LDA(dst, b, h) do { _Pragma("unroll") for (int m = 0; m < 4; ++m) _Pragma("unroll") for (int k = 0; k < 2; ++k) dst[m][k] = *(const PG8_LAS bf16x8*)(lds + PG8_SA(b, h) + aoff + m * 2048 + k * 1024); } while (0)
; #define PG8_LDB(dst, b, h) do { _Pragma("unroll") for (int n = 0; n < 2; ++n) _Pragma("unroll") for (int k = 0; k < 2; ++k) dst[n][k] = *(const PG8_LAS bf16x8*)(lds + PG8_SB(b, h) + boff + n * 2048 + k * 1024); } while (0)
; #define PG8_WAIT_V(n) asm volatile("s_waitcnt vmcnt(" #n ")" ::: "memory")
; #define PG8_WAIT_L(n) asm volatile("s_waitcnt lgkmcnt(" #n ")" ::: "memory")
; #define PG8_BAR __builtin_amdgcn_s_barrier()
; #define PG8_SCHED __builtin_amdgcn_sched_barrier(0)
; template <class Epi, class Sched, bool ALIGN_EPI = false, bool SP2 = false>
; __device__ __forceinline__ void gemm_phase(PG8_LAS unsigned char* lds, const Gemm g, const Sched& S, const Epi& E) {
;     ...
;     for (;;) {
;         const bool has_next = S.next(ui + 1, nxt);
;         const char* nA = has_next ? (const char*)g.A + (size_t)nxt.pm * tstep : cA; const char* nB = has_next ? (const char*)g.Bt + (size_t)nxt.pn * tstep : cB;
;         for (int t = 0; t < nt; t += 2) {
;             const bool last = (t == nt - 2);
;             const char* a1 = cA + (size_t)(t + 1) * kstep;
;             const char* a2 = last ? nA : cA + (size_t)(t + 2) * kstep; const char* b2 = last ? nB : cB + (size_t)(t + 2) * kstep;
;             const char* a3 = a2 + kstep; const char* b3 = b2 + kstep;
;             if (last && has_next) S.a_ready(nxt);
;             if constexpr (Epi::MID) { if (t == nt / 2) E.mid(acc, cur, wr, wc, fr, fq); }
;             if constexpr (SP2) {
;             PG8_LDB(B0, 0, 0); PG8_LDB(B1, 0, 1); PG8_SCHED; PG8_LDA(At, 0, 0); PG8_STAGE(PG8_SA(1, 1), a1 + hstep, voffA);
;             PG8_WAIT_V(8); PG8_WAIT_L(0); PG8_BAR; PG8_MMA(0, 0, At, B0); PG8_MMA(0, 1, At, B1); PG8_BAR; PG8_SCHED;
;             PG8_LDA(At, 0, 1); PG8_STAGE(PG8_SB(0, 0), b2, voffB); PG8_STAGE(PG8_SB(0, 1), b2 + hstep, voffB); PG8_STAGE(PG8_SA(0, 0), a2, voffA);
.LBB0_587:
	s_ashr_i32 s35, s34, 31
	s_lshl_b64 s[36:37], s[34:35], 20
	s_add_u32 s36, s6, s36
	s_addc_u32 s37, s7, s37
	s_and_b64 s[38:39], s[2:3], exec
	s_cselect_b32 s5, s37, s45
	s_cselect_b32 s13, s36, s44
	s_ashr_i32 s31, s30, 31
	s_lshl_b64 s[38:39], s[30:31], 20
	s_add_u32 s38, s59, s38
	s_addc_u32 s39, s60, s39
	s_and_b64 s[46:47], s[2:3], exec
	s_cselect_b32 s31, s39, s41
	s_cselect_b32 s35, s38, s40
	s_add_u32 s43, s40, 0x100
	s_addc_u32 s48, s41, 0
	s_add_u32 s40, s44, 0x80080
	s_addc_u32 s41, s45, 0
	s_mov_b32 s49, -2
	s_add_u32 s33, s40, 0xfff80080
	s_addc_u32 s44, s41, -1
	s_add_i32 s50, 0, 0x10000
	s_cmp_eq_u32 s49, 28
	s_cselect_b32 s47, s5, s44
	s_cselect_b32 s46, s13, s33
	v_add_u32_e32 v0, s50, v153
	s_cselect_b32 s45, s31, s48
	s_cselect_b32 s44, s35, s43
	s_add_i32 s33, 0, 0x14000
	ds_read_b128 v[134:137], v0
	ds_read_b128 v[138:141], v0 offset:1024
	ds_read_b128 v[142:145], v0 offset:2048
	s_waitcnt lgkmcnt(0)
	ds_read_b128 v[168:171], v0 offset:3072
	v_add_u32_e32 v0, s33, v153
	ds_read_b128 v[172:175], v0
	ds_read_b128 v[176:179], v0 offset:1024
	ds_read_b128 v[180:183], v0 offset:2048
	ds_read_b128 v[184:187], v0 offset:3072
	s_add_i32 m0, s62, 0xc000
	ds_read_b128 v[188:191], v194
	ds_read_b128 v[196:199], v194 offset:1024
	ds_read_b128 v[200:203], v194 offset:2048
	ds_read_b128 v[206:209], v194 offset:3072
	ds_read_b128 v[210:213], v194 offset:4096
	ds_read_b128 v[214:217], v194 offset:5120
	ds_read_b128 v[218:221], v194 offset:6144
	ds_read_b128 v[222:225], v194 offset:7168
	global_load_lds_dwordx4 v166, s[40:41]
	s_add_i32 m0, s62, 0xe000
	s_nop 0
	global_load_lds_dwordx4 v164, s[40:41]
	s_waitcnt vmcnt(8)
	s_waitcnt lgkmcnt(0)
	s_barrier
	s_setprio 1
	s_waitcnt lgkmcnt(0)
	v_mfma_f32_16x16x32_bf16 v[74:77], v[134:137], v[188:191], 0
	v_mfma_f32_16x16x32_bf16 v[74:77], v[138:141], v[196:199], v[74:77]
	v_mfma_f32_16x16x32_bf16 v[62:65], v[168:171], v[196:199], 0
	v_mfma_f32_16x16x32_bf16 v[62:65], v[142:145], v[188:191], v[62:65]
	v_mfma_f32_16x16x32_bf16 v[54:57], v[142:145], v[200:203], 0
	v_mfma_f32_16x16x32_bf16 v[54:57], v[168:171], v[206:209], v[54:57]
	v_mfma_f32_16x16x32_bf16 v[58:61], v[138:141], v[206:209], 0
	v_mfma_f32_16x16x32_bf16 v[58:61], v[134:137], v[200:203], v[58:61]
	v_mfma_f32_16x16x32_bf16 v[50:53], v[134:137], v[210:213], 0
	v_mfma_f32_16x16x32_bf16 v[50:53], v[138:141], v[214:217], v[50:53]
	v_mfma_f32_16x16x32_bf16 v[46:49], v[168:171], v[214:217], 0
	v_mfma_f32_16x16x32_bf16 v[46:49], v[142:145], v[210:213], v[46:49]
	v_mfma_f32_16x16x32_bf16 v[38:41], v[142:145], v[218:221], 0
	v_mfma_f32_16x16x32_bf16 v[38:41], v[168:171], v[222:225], v[38:41]
	v_mfma_f32_16x16x32_bf16 v[42:45], v[138:141], v[222:225], 0
	v_mfma_f32_16x16x32_bf16 v[42:45], v[134:137], v[218:221], v[42:45]
	s_setprio 0
	s_setprio 1
	v_mfma_f32_16x16x32_bf16 v[130:133], v[172:175], v[188:191], 0
	v_mfma_f32_16x16x32_bf16 v[130:133], v[176:179], v[196:199], v[130:133]
	v_mfma_f32_16x16x32_bf16 v[126:129], v[184:187], v[196:199], 0
	v_mfma_f32_16x16x32_bf16 v[126:129], v[180:183], v[188:191], v[126:129]
	v_mfma_f32_16x16x32_bf16 v[118:121], v[180:183], v[200:203], 0
	v_mfma_f32_16x16x32_bf16 v[118:121], v[184:187], v[206:209], v[118:121]
	v_mfma_f32_16x16x32_bf16 v[122:125], v[176:179], v[206:209], 0
	v_mfma_f32_16x16x32_bf16 v[122:125], v[172:175], v[200:203], v[122:125]
	v_mfma_f32_16x16x32_bf16 v[114:117], v[172:175], v[210:213], 0
	v_mfma_f32_16x16x32_bf16 v[114:117], v[176:179], v[214:217], v[114:117]
	v_mfma_f32_16x16x32_bf16 v[110:113], v[184:187], v[214:217], 0
	v_mfma_f32_16x16x32_bf16 v[110:113], v[180:183], v[210:213], v[110:113]
	v_mfma_f32_16x16x32_bf16 v[102:105], v[180:183], v[218:221], 0
	v_mfma_f32_16x16x32_bf16 v[102:105], v[184:187], v[222:225], v[102:105]
	v_mfma_f32_16x16x32_bf16 v[106:109], v[176:179], v[222:225], 0
	v_mfma_f32_16x16x32_bf16 v[106:109], v[172:175], v[218:221], v[106:109]
	s_setprio 0
	s_barrier
	s_add_i32 s50, s50, s61
	s_mov_b32 m0, s50
	ds_read_b128 v[188:191], v194 offset:16384
	ds_read_b128 v[196:199], v194 offset:17408
	ds_read_b128 v[200:203], v194 offset:18432
	ds_read_b128 v[206:209], v194 offset:19456
	ds_read_b128 v[210:213], v194 offset:20480
	ds_read_b128 v[214:217], v194 offset:21504
	ds_read_b128 v[218:221], v194 offset:22528
	ds_read_b128 v[222:225], v194 offset:23552
	global_load_lds_dwordx4 v146, s[44:45]
	s_add_i32 m0, s50, 0x2000
	s_add_u32 s100, s46, 0x80
	s_addc_u32 s101, s47, 0
	s_add_u32 s50, s44, 0x80000
	s_addc_u32 s51, s45, 0
	s_add_i32 s33, s33, s61
	global_load_lds_dwordx4 v150, s[44:45]
	s_mov_b32 m0, s33
	s_nop 0
	global_load_lds_dwordx4 v146, s[50:51]
	s_add_i32 m0, s33, 0x2000
	s_nop 0
	global_load_lds_dwordx4 v150, s[50:51]
	s_mov_b32 m0, s62
	s_nop 0
	global_load_lds_dwordx4 v14, s[46:47]
	s_mov_b32 m0, s63
	s_nop 0
	global_load_lds_dwordx4 v148, s[46:47]
	s_waitcnt vmcnt(8)
	s_waitcnt lgkmcnt(0)
	s_barrier
; #define PG8_STAGE(bufoff, gbase, voff) do { _Pragma("unroll") for (int _i = 0; _i < 2; ++_i) \
;         __builtin_amdgcn_global_load_lds((const unsigned*)((const char*)(gbase) + (voff)[_i]), (PG8_LAS unsigned*)(lds + (bufoff) + ldsw + _i * 8192), 16, 0, 0); } while (0)
; #define PG8_LDA(dst, b, h) do { _Pragma("unroll") for (int m = 0; m < 4; ++m) _Pragma("unroll") for (int k = 0; k < 2; ++k) dst[m][k] = *(const PG8_LAS bf16x8*)(lds + PG8_SA(b, h) + aoff + m * 2048 + k * 1024); } while (0)
; #define PG8_LDB(dst, b, h) do { _Pragma("unroll") for (int n = 0; n < 2; ++n) _Pragma("unroll") for (int k = 0; k < 2; ++k) dst[n][k] = *(const PG8_LAS bf16x8*)(lds + PG8_SB(b, h) + boff + n * 2048 + k * 1024); } while (0)
; #define PG8_MMA(ai, bj, At, Bt) do { __builtin_amdgcn_s_setprio(1); _Pragma("unroll") for (int m = 0; m < 4; ++m) _Pragma("unroll") for (int n = 0; n < 2; ++n) _Pragma("unroll") for (int k = 0; k < 2; ++k) \
;         acc[ai][bj][m][n] = __builtin_amdgcn_mfma_f32_16x16x32_bf16(Bt[n][k], At[m][k], acc[ai][bj][m][n], 0, 0, 0); __builtin_amdgcn_s_setprio(0); } while (0)
; #define PG8_WAIT_V(n) asm volatile("s_waitcnt vmcnt(" #n ")" ::: "memory")
; #define PG8_WAIT_L(n) asm volatile("s_waitcnt lgkmcnt(" #n ")" ::: "memory")
; #define PG8_BAR __builtin_amdgcn_s_barrier()
; #define PG8_SCHED __builtin_amdgcn_sched_barrier(0)
; template <class Epi, class Sched, bool ALIGN_EPI = false, bool SP2 = false>
; __device__ __forceinline__ void gemm_phase(PG8_LAS unsigned char* lds, const Gemm g, const Sched& S, const Epi& E) {
;     ...
;             PG8_WAIT_V(8); PG8_WAIT_L(0); PG8_BAR; PG8_MMA(1, 0, At, B0); PG8_MMA(1, 1, At, B1); PG8_BAR; PG8_SCHED;
;             PG8_LDB(B0, 1, 0); PG8_LDB(B1, 1, 1); PG8_SCHED; PG8_LDA(At, 1, 0); PG8_STAGE(PG8_SA(0, 1), a2 + hstep, voffA);
;             PG8_WAIT_V(8); PG8_WAIT_L(0); PG8_BAR; PG8_MMA(0, 0, At, B0); PG8_MMA(0, 1, At, B1); PG8_BAR; PG8_SCHED;
	s_setprio 1
	s_waitcnt lgkmcnt(0)
	v_mfma_f32_16x16x32_bf16 v[34:37], v[134:137], v[188:191], 0
	v_mfma_f32_16x16x32_bf16 v[34:37], v[138:141], v[196:199], v[34:37]
	v_mfma_f32_16x16x32_bf16 v[30:33], v[168:171], v[196:199], 0
	v_mfma_f32_16x16x32_bf16 v[30:33], v[142:145], v[188:191], v[30:33]
	v_mfma_f32_16x16x32_bf16 v[22:25], v[142:145], v[200:203], 0
	v_mfma_f32_16x16x32_bf16 v[22:25], v[168:171], v[206:209], v[22:25]
	v_mfma_f32_16x16x32_bf16 v[26:29], v[138:141], v[206:209], 0
	v_mfma_f32_16x16x32_bf16 v[26:29], v[134:137], v[200:203], v[26:29]
	v_mfma_f32_16x16x32_bf16 v[18:21], v[134:137], v[210:213], 0
	v_mfma_f32_16x16x32_bf16 v[18:21], v[138:141], v[214:217], v[18:21]
	v_mfma_f32_16x16x32_bf16 v[10:13], v[168:171], v[214:217], 0
	v_mfma_f32_16x16x32_bf16 v[10:13], v[142:145], v[210:213], v[10:13]
	v_mfma_f32_16x16x32_bf16 v[2:5], v[142:145], v[218:221], 0
	v_mfma_f32_16x16x32_bf16 v[2:5], v[168:171], v[222:225], v[2:5]
	v_mfma_f32_16x16x32_bf16 v[6:9], v[138:141], v[222:225], 0
	v_mfma_f32_16x16x32_bf16 v[6:9], v[134:137], v[218:221], v[6:9]
	s_setprio 0
	s_setprio 1
	v_mfma_f32_16x16x32_bf16 v[98:101], v[172:175], v[188:191], 0
	v_mfma_f32_16x16x32_bf16 v[98:101], v[176:179], v[196:199], v[98:101]
	v_mfma_f32_16x16x32_bf16 v[94:97], v[184:187], v[196:199], 0
	v_mfma_f32_16x16x32_bf16 v[94:97], v[180:183], v[188:191], v[94:97]
	v_mfma_f32_16x16x32_bf16 v[86:89], v[180:183], v[200:203], 0
	v_mfma_f32_16x16x32_bf16 v[86:89], v[184:187], v[206:209], v[86:89]
	v_mfma_f32_16x16x32_bf16 v[90:93], v[176:179], v[206:209], 0
	v_mfma_f32_16x16x32_bf16 v[90:93], v[172:175], v[200:203], v[90:93]
	v_mfma_f32_16x16x32_bf16 v[82:85], v[172:175], v[210:213], 0
	v_mfma_f32_16x16x32_bf16 v[82:85], v[176:179], v[214:217], v[82:85]
	v_mfma_f32_16x16x32_bf16 v[78:81], v[184:187], v[214:217], 0
	v_mfma_f32_16x16x32_bf16 v[78:81], v[180:183], v[210:213], v[78:81]
	v_mfma_f32_16x16x32_bf16 v[66:69], v[180:183], v[218:221], 0
	v_mfma_f32_16x16x32_bf16 v[66:69], v[184:187], v[222:225], v[66:69]
	v_mfma_f32_16x16x32_bf16 v[70:73], v[176:179], v[222:225], 0
	v_mfma_f32_16x16x32_bf16 v[70:73], v[172:175], v[218:221], v[70:73]
	s_setprio 0
	s_barrier
	s_add_i32 s33, 0, 0x18000
	v_add_u32_e32 v0, s33, v153
	s_add_i32 s50, 0, 0x1c000
	ds_read_b128 v[134:137], v0
	ds_read_b128 v[138:141], v0 offset:1024
	ds_read_b128 v[142:145], v0 offset:2048
	ds_read_b128 v[168:171], v0 offset:3072
	v_add_u32_e32 v0, s50, v153
	ds_read_b128 v[172:175], v0
	ds_read_b128 v[176:179], v0 offset:1024
	ds_read_b128 v[180:183], v0 offset:2048
	ds_read_b128 v[184:187], v0 offset:3072
	s_add_u32 s46, s46, 0x80000
	s_addc_u32 s47, s47, 0
	s_mov_b32 m0, s64
	ds_read_b128 v[188:191], v194 offset:32768
	ds_read_b128 v[196:199], v194 offset:33792
	ds_read_b128 v[200:203], v194 offset:34816
	ds_read_b128 v[206:209], v194 offset:35840
	ds_read_b128 v[210:213], v194 offset:36864
	ds_read_b128 v[214:217], v194 offset:37888
	ds_read_b128 v[218:221], v194 offset:38912
	ds_read_b128 v[222:225], v194 offset:39936
	global_load_lds_dwordx4 v14, s[46:47]
	s_mov_b32 m0, s65
	s_nop 0
	global_load_lds_dwordx4 v148, s[46:47]
	s_waitcnt vmcnt(8)
	s_waitcnt lgkmcnt(0)
	s_barrier
	s_setprio 1
	s_waitcnt lgkmcnt(0)
	v_mfma_f32_16x16x32_bf16 v[74:77], v[134:137], v[188:191], v[74:77]
	v_mfma_f32_16x16x32_bf16 v[74:77], v[138:141], v[196:199], v[74:77]
	v_mfma_f32_16x16x32_bf16 v[62:65], v[168:171], v[196:199], v[62:65]
	v_mfma_f32_16x16x32_bf16 v[62:65], v[142:145], v[188:191], v[62:65]
	v_mfma_f32_16x16x32_bf16 v[54:57], v[142:145], v[200:203], v[54:57]
	v_mfma_f32_16x16x32_bf16 v[54:57], v[168:171], v[206:209], v[54:57]
	v_mfma_f32_16x16x32_bf16 v[58:61], v[138:141], v[206:209], v[58:61]
	v_mfma_f32_16x16x32_bf16 v[58:61], v[134:137], v[200:203], v[58:61]
	v_mfma_f32_16x16x32_bf16 v[50:53], v[134:137], v[210:213], v[50:53]
	v_mfma_f32_16x16x32_bf16 v[50:53], v[138:141], v[214:217], v[50:53]
	v_mfma_f32_16x16x32_bf16 v[46:49], v[168:171], v[214:217], v[46:49]
	v_mfma_f32_16x16x32_bf16 v[46:49], v[142:145], v[210:213], v[46:49]
	v_mfma_f32_16x16x32_bf16 v[38:41], v[142:145], v[218:221], v[38:41]
	v_mfma_f32_16x16x32_bf16 v[38:41], v[168:171], v[222:225], v[38:41]
	v_mfma_f32_16x16x32_bf16 v[42:45], v[138:141], v[222:225], v[42:45]
	v_mfma_f32_16x16x32_bf16 v[42:45], v[134:137], v[218:221], v[42:45]
	s_setprio 0
	s_setprio 1
	v_mfma_f32_16x16x32_bf16 v[130:133], v[172:175], v[188:191], v[130:133]
	v_mfma_f32_16x16x32_bf16 v[130:133], v[176:179], v[196:199], v[130:133]
	v_mfma_f32_16x16x32_bf16 v[126:129], v[184:187], v[196:199], v[126:129]
	v_mfma_f32_16x16x32_bf16 v[126:129], v[180:183], v[188:191], v[126:129]
	v_mfma_f32_16x16x32_bf16 v[118:121], v[180:183], v[200:203], v[118:121]
	v_mfma_f32_16x16x32_bf16 v[118:121], v[184:187], v[206:209], v[118:121]
	v_mfma_f32_16x16x32_bf16 v[122:125], v[176:179], v[206:209], v[122:125]
	v_mfma_f32_16x16x32_bf16 v[122:125], v[172:175], v[200:203], v[122:125]
	v_mfma_f32_16x16x32_bf16 v[114:117], v[172:175], v[210:213], v[114:117]
	v_mfma_f32_16x16x32_bf16 v[114:117], v[176:179], v[214:217], v[114:117]
	v_mfma_f32_16x16x32_bf16 v[110:113], v[184:187], v[214:217], v[110:113]
	v_mfma_f32_16x16x32_bf16 v[110:113], v[180:183], v[210:213], v[110:113]
	v_mfma_f32_16x16x32_bf16 v[102:105], v[180:183], v[218:221], v[102:105]
	v_mfma_f32_16x16x32_bf16 v[102:105], v[184:187], v[222:225], v[102:105]
	v_mfma_f32_16x16x32_bf16 v[106:109], v[176:179], v[222:225], v[106:109]
	v_mfma_f32_16x16x32_bf16 v[106:109], v[172:175], v[218:221], v[106:109]
	s_setprio 0
	s_barrier
; #define PG8_STAGE(bufoff, gbase, voff) do { _Pragma("unroll") for (int _i = 0; _i < 2; ++_i) \
;         __builtin_amdgcn_global_load_lds((const unsigned*)((const char*)(gbase) + (voff)[_i]), (PG8_LAS unsigned*)(lds + (bufoff) + ldsw + _i * 8192), 16, 0, 0); } while (0)
; #define PG8_LDA(dst, b, h) do { _Pragma("unroll") for (int m = 0; m < 4; ++m) _Pragma("unroll") for (int k = 0; k < 2; ++k) dst[m][k] = *(const PG8_LAS bf16x8*)(lds + PG8_SA(b, h) + aoff + m * 2048 + k * 1024); } while (0)
; #define PG8_LDB(dst, b, h) do { _Pragma("unroll") for (int n = 0; n < 2; ++n) _Pragma("unroll") for (int k = 0; k < 2; ++k) dst[n][k] = *(const PG8_LAS bf16x8*)(lds + PG8_SB(b, h) + boff + n * 2048 + k * 1024); } while (0)
; #define PG8_MMA(ai, bj, At, Bt) do { __builtin_amdgcn_s_setprio(1); _Pragma("unroll") for (int m = 0; m < 4; ++m) _Pragma("unroll") for (int n = 0; n < 2; ++n) _Pragma("unroll") for (int k = 0; k < 2; ++k) \
;         acc[ai][bj][m][n] = __builtin_amdgcn_mfma_f32_16x16x32_bf16(Bt[n][k], At[m][k], acc[ai][bj][m][n], 0, 0, 0); __builtin_amdgcn_s_setprio(0); } while (0)
; #define PG8_WAIT_V(n) asm volatile("s_waitcnt vmcnt(" #n ")" ::: "memory")
; #define PG8_WAIT_L(n) asm volatile("s_waitcnt lgkmcnt(" #n ")" ::: "memory")
; #define PG8_BAR __builtin_amdgcn_s_barrier()
; #define PG8_SCHED __builtin_amdgcn_sched_barrier(0)
; template <class Epi, class Sched, bool ALIGN_EPI = false, bool SP2 = false>
; __device__ __forceinline__ void gemm_phase(PG8_LAS unsigned char* lds, const Gemm g, const Sched& S, const Epi& E) {
;     ...
;             PG8_LDB(B0, 0, 0); PG8_LDB(B1, 0, 1); PG8_SCHED; PG8_LDA(At, 0, 0); PG8_STAGE(PG8_SA(1, 1), a1 + hstep, voffA);
;             PG8_WAIT_V(8); PG8_WAIT_L(0); PG8_BAR; PG8_MMA(0, 0, At, B0); PG8_MMA(0, 1, At, B1); PG8_BAR; PG8_SCHED;
;     ...
;             PG8_LDA(At, 1, 1); PG8_STAGE(PG8_SB(1, 0), b3, voffB); PG8_STAGE(PG8_SB(1, 1), b3 + hstep, voffB); PG8_STAGE(PG8_SA(1, 0), a3, voffA);
;             PG8_WAIT_V(8); PG8_WAIT_L(0); PG8_BAR; PG8_MMA(1, 0, At, B0); PG8_MMA(1, 1, At, B1); PG8_BAR; PG8_SCHED;
	s_add_i32 s33, s33, s61
	s_add_i32 m0, s33, 0xffffff80
	ds_read_b128 v[188:191], v194 offset:49152
	ds_read_b128 v[196:199], v194 offset:50176
	ds_read_b128 v[200:203], v194 offset:51200
	ds_read_b128 v[206:209], v194 offset:52224
	ds_read_b128 v[210:213], v194 offset:53248
	ds_read_b128 v[214:217], v194 offset:54272
	ds_read_b128 v[218:221], v194 offset:55296
	ds_read_b128 v[222:225], v194 offset:56320
	global_load_lds_dwordx4 v146, s[44:45] offset:128
	s_add_i32 m0, s33, 0x1f80
	s_add_i32 s33, s50, s61
	global_load_lds_dwordx4 v150, s[44:45] offset:128
	s_add_u32 s44, s44, 0x80080
	s_addc_u32 s45, s45, 0
	s_mov_b32 m0, s33
	s_nop 0
	global_load_lds_dwordx4 v146, s[44:45]
	s_add_i32 m0, s33, 0x2000
	s_nop 0
	global_load_lds_dwordx4 v150, s[44:45]
	s_mov_b32 m0, s68
	s_nop 0
	global_load_lds_dwordx4 v14, s[100:101]
	s_mov_b32 m0, s69
	s_nop 0
	global_load_lds_dwordx4 v148, s[100:101]
	s_waitcnt vmcnt(8)
	s_waitcnt lgkmcnt(0)
	s_barrier
	s_setprio 1
	s_waitcnt lgkmcnt(0)
	v_mfma_f32_16x16x32_bf16 v[34:37], v[134:137], v[188:191], v[34:37]
	v_mfma_f32_16x16x32_bf16 v[34:37], v[138:141], v[196:199], v[34:37]
	v_mfma_f32_16x16x32_bf16 v[30:33], v[168:171], v[196:199], v[30:33]
	v_mfma_f32_16x16x32_bf16 v[30:33], v[142:145], v[188:191], v[30:33]
	v_mfma_f32_16x16x32_bf16 v[22:25], v[142:145], v[200:203], v[22:25]
	v_mfma_f32_16x16x32_bf16 v[22:25], v[168:171], v[206:209], v[22:25]
	v_mfma_f32_16x16x32_bf16 v[26:29], v[138:141], v[206:209], v[26:29]
	v_mfma_f32_16x16x32_bf16 v[26:29], v[134:137], v[200:203], v[26:29]
	v_mfma_f32_16x16x32_bf16 v[18:21], v[134:137], v[210:213], v[18:21]
	v_mfma_f32_16x16x32_bf16 v[18:21], v[138:141], v[214:217], v[18:21]
	v_mfma_f32_16x16x32_bf16 v[10:13], v[168:171], v[214:217], v[10:13]
	v_mfma_f32_16x16x32_bf16 v[10:13], v[142:145], v[210:213], v[10:13]
	v_mfma_f32_16x16x32_bf16 v[2:5], v[142:145], v[218:221], v[2:5]
	v_mfma_f32_16x16x32_bf16 v[2:5], v[168:171], v[222:225], v[2:5]
	v_mfma_f32_16x16x32_bf16 v[6:9], v[138:141], v[222:225], v[6:9]
	v_mfma_f32_16x16x32_bf16 v[6:9], v[134:137], v[218:221], v[6:9]
	s_setprio 0
	s_setprio 1
	v_mfma_f32_16x16x32_bf16 v[98:101], v[172:175], v[188:191], v[98:101]
	v_mfma_f32_16x16x32_bf16 v[98:101], v[176:179], v[196:199], v[98:101]
	v_mfma_f32_16x16x32_bf16 v[94:97], v[184:187], v[196:199], v[94:97]
	v_mfma_f32_16x16x32_bf16 v[94:97], v[180:183], v[188:191], v[94:97]
	v_mfma_f32_16x16x32_bf16 v[86:89], v[180:183], v[200:203], v[86:89]
	v_mfma_f32_16x16x32_bf16 v[86:89], v[184:187], v[206:209], v[86:89]
	v_mfma_f32_16x16x32_bf16 v[90:93], v[176:179], v[206:209], v[90:93]
	v_mfma_f32_16x16x32_bf16 v[90:93], v[172:175], v[200:203], v[90:93]
	v_mfma_f32_16x16x32_bf16 v[82:85], v[172:175], v[210:213], v[82:85]
	v_mfma_f32_16x16x32_bf16 v[82:85], v[176:179], v[214:217], v[82:85]
	v_mfma_f32_16x16x32_bf16 v[78:81], v[184:187], v[214:217], v[78:81]
	v_mfma_f32_16x16x32_bf16 v[78:81], v[180:183], v[210:213], v[78:81]
	v_mfma_f32_16x16x32_bf16 v[66:69], v[180:183], v[218:221], v[66:69]
	v_mfma_f32_16x16x32_bf16 v[66:69], v[184:187], v[222:225], v[66:69]
	v_mfma_f32_16x16x32_bf16 v[70:73], v[176:179], v[222:225], v[70:73]
	v_mfma_f32_16x16x32_bf16 v[70:73], v[172:175], v[218:221], v[70:73]
	s_setprio 0
	s_barrier
	s_add_i32 s49, s49, 2
	s_add_u32 s43, s43, 0x100
	s_addc_u32 s48, s48, 0
	s_add_u32 s40, s40, 0x100
	s_addc_u32 s41, s41, 0
	s_cmp_gt_u32 s49, 29
.LBB0_588:
	s_add_u32 s33, s40, 0xfff80080
	s_addc_u32 s44, s41, -1
	s_add_i32 s50, 0, 0x10000
	s_cmp_eq_u32 s49, 28
	s_cselect_b32 s47, s5, s44
	s_cselect_b32 s46, s13, s33
	v_add_u32_e32 v0, s50, v153
	s_cselect_b32 s45, s31, s48
	s_cselect_b32 s44, s35, s43
	s_add_i32 s33, 0, 0x14000
	ds_read_b128 v[134:137], v0
	ds_read_b128 v[138:141], v0 offset:1024
	ds_read_b128 v[142:145], v0 offset:2048
	s_waitcnt lgkmcnt(0)
	ds_read_b128 v[168:171], v0 offset:3072
	v_add_u32_e32 v0, s33, v153
	ds_read_b128 v[172:175], v0
	ds_read_b128 v[176:179], v0 offset:1024
	ds_read_b128 v[180:183], v0 offset:2048
	ds_read_b128 v[184:187], v0 offset:3072
	s_add_i32 m0, s62, 0xc000
	ds_read_b128 v[188:191], v194
	ds_read_b128 v[196:199], v194 offset:1024
	ds_read_b128 v[200:203], v194 offset:2048
	ds_read_b128 v[206:209], v194 offset:3072
	ds_read_b128 v[210:213], v194 offset:4096
	ds_read_b128 v[214:217], v194 offset:5120
	ds_read_b128 v[218:221], v194 offset:6144
	ds_read_b128 v[222:225], v194 offset:7168
	global_load_lds_dwordx4 v166, s[40:41]
	s_add_i32 m0, s62, 0xe000
	s_nop 0
	global_load_lds_dwordx4 v164, s[40:41]
	s_waitcnt vmcnt(8)
	s_waitcnt lgkmcnt(0)
	s_barrier
; #define PG8_STAGE(bufoff, gbase, voff) do { _Pragma("unroll") for (int _i = 0; _i < 2; ++_i) \
;         __builtin_amdgcn_global_load_lds((const unsigned*)((const char*)(gbase) + (voff)[_i]), (PG8_LAS unsigned*)(lds + (bufoff) + ldsw + _i * 8192), 16, 0, 0); } while (0)
; #define PG8_LDA(dst, b, h) do { _Pragma("unroll") for (int m = 0; m < 4; ++m) _Pragma("unroll") for (int k = 0; k < 2; ++k) dst[m][k] = *(const PG8_LAS bf16x8*)(lds + PG8_SA(b, h) + aoff + m * 2048 + k * 1024); } while (0)
; #define PG8_MMA(ai, bj, At, Bt) do { __builtin_amdgcn_s_setprio(1); _Pragma("unroll") for (int m = 0; m < 4; ++m) _Pragma("unroll") for (int n = 0; n < 2; ++n) _Pragma("unroll") for (int k = 0; k < 2; ++k) \
;         acc[ai][bj][m][n] = __builtin_amdgcn_mfma_f32_16x16x32_bf16(Bt[n][k], At[m][k], acc[ai][bj][m][n], 0, 0, 0); __builtin_amdgcn_s_setprio(0); } while (0)
; #define PG8_WAIT_V(n) asm volatile("s_waitcnt vmcnt(" #n ")" ::: "memory")
; #define PG8_WAIT_L(n) asm volatile("s_waitcnt lgkmcnt(" #n ")" ::: "memory")
; #define PG8_BAR __builtin_amdgcn_s_barrier()
; #define PG8_SCHED __builtin_amdgcn_sched_barrier(0)
; template <class Epi, class Sched, bool ALIGN_EPI = false, bool SP2 = false>
; __device__ __forceinline__ void gemm_phase(PG8_LAS unsigned char* lds, const Gemm g, const Sched& S, const Epi& E) {
;     ...
;             PG8_WAIT_V(8); PG8_WAIT_L(0); PG8_BAR; PG8_MMA(0, 0, At, B0); PG8_MMA(0, 1, At, B1); PG8_BAR; PG8_SCHED;
;             PG8_LDA(At, 0, 1); PG8_STAGE(PG8_SB(0, 0), b2, voffB); PG8_STAGE(PG8_SB(0, 1), b2 + hstep, voffB); PG8_STAGE(PG8_SA(0, 0), a2, voffA);
;             PG8_WAIT_V(8); PG8_WAIT_L(0); PG8_BAR; PG8_MMA(1, 0, At, B0); PG8_MMA(1, 1, At, B1); PG8_BAR; PG8_SCHED;
	s_setprio 1
	s_waitcnt lgkmcnt(0)
	v_mfma_f32_16x16x32_bf16 v[74:77], v[134:137], v[188:191], v[74:77]
	v_mfma_f32_16x16x32_bf16 v[74:77], v[138:141], v[196:199], v[74:77]
	v_mfma_f32_16x16x32_bf16 v[62:65], v[168:171], v[196:199], v[62:65]
	v_mfma_f32_16x16x32_bf16 v[62:65], v[142:145], v[188:191], v[62:65]
	v_mfma_f32_16x16x32_bf16 v[54:57], v[142:145], v[200:203], v[54:57]
	v_mfma_f32_16x16x32_bf16 v[54:57], v[168:171], v[206:209], v[54:57]
	v_mfma_f32_16x16x32_bf16 v[58:61], v[138:141], v[206:209], v[58:61]
	v_mfma_f32_16x16x32_bf16 v[58:61], v[134:137], v[200:203], v[58:61]
	v_mfma_f32_16x16x32_bf16 v[50:53], v[134:137], v[210:213], v[50:53]
	v_mfma_f32_16x16x32_bf16 v[50:53], v[138:141], v[214:217], v[50:53]
	v_mfma_f32_16x16x32_bf16 v[46:49], v[168:171], v[214:217], v[46:49]
	v_mfma_f32_16x16x32_bf16 v[46:49], v[142:145], v[210:213], v[46:49]
	v_mfma_f32_16x16x32_bf16 v[38:41], v[142:145], v[218:221], v[38:41]
	v_mfma_f32_16x16x32_bf16 v[38:41], v[168:171], v[222:225], v[38:41]
	v_mfma_f32_16x16x32_bf16 v[42:45], v[138:141], v[222:225], v[42:45]
	v_mfma_f32_16x16x32_bf16 v[42:45], v[134:137], v[218:221], v[42:45]
	s_setprio 0
	s_setprio 1
	v_mfma_f32_16x16x32_bf16 v[130:133], v[172:175], v[188:191], v[130:133]
	v_mfma_f32_16x16x32_bf16 v[130:133], v[176:179], v[196:199], v[130:133]
	v_mfma_f32_16x16x32_bf16 v[126:129], v[184:187], v[196:199], v[126:129]
	v_mfma_f32_16x16x32_bf16 v[126:129], v[180:183], v[188:191], v[126:129]
	v_mfma_f32_16x16x32_bf16 v[118:121], v[180:183], v[200:203], v[118:121]
	v_mfma_f32_16x16x32_bf16 v[118:121], v[184:187], v[206:209], v[118:121]
	v_mfma_f32_16x16x32_bf16 v[122:125], v[176:179], v[206:209], v[122:125]
	v_mfma_f32_16x16x32_bf16 v[122:125], v[172:175], v[200:203], v[122:125]
	v_mfma_f32_16x16x32_bf16 v[114:117], v[172:175], v[210:213], v[114:117]
	v_mfma_f32_16x16x32_bf16 v[114:117], v[176:179], v[214:217], v[114:117]
	v_mfma_f32_16x16x32_bf16 v[110:113], v[184:187], v[214:217], v[110:113]
	v_mfma_f32_16x16x32_bf16 v[110:113], v[180:183], v[210:213], v[110:113]
	v_mfma_f32_16x16x32_bf16 v[102:105], v[180:183], v[218:221], v[102:105]
	v_mfma_f32_16x16x32_bf16 v[102:105], v[184:187], v[222:225], v[102:105]
	v_mfma_f32_16x16x32_bf16 v[106:109], v[176:179], v[222:225], v[106:109]
	v_mfma_f32_16x16x32_bf16 v[106:109], v[172:175], v[218:221], v[106:109]
	s_setprio 0
	s_barrier
	s_add_i32 s50, s50, s61
	s_mov_b32 m0, s50
	ds_read_b128 v[188:191], v194 offset:16384
	ds_read_b128 v[196:199], v194 offset:17408
	ds_read_b128 v[200:203], v194 offset:18432
	ds_read_b128 v[206:209], v194 offset:19456
	ds_read_b128 v[210:213], v194 offset:20480
	ds_read_b128 v[214:217], v194 offset:21504
	ds_read_b128 v[218:221], v194 offset:22528
	ds_read_b128 v[222:225], v194 offset:23552
	global_load_lds_dwordx4 v146, s[44:45]
	s_add_i32 m0, s50, 0x2000
	s_add_u32 s100, s46, 0x80
	s_addc_u32 s101, s47, 0
	s_add_u32 s50, s44, 0x80000
	s_addc_u32 s51, s45, 0
	s_add_i32 s33, s33, s61
	global_load_lds_dwordx4 v150, s[44:45]
	s_mov_b32 m0, s33
	s_nop 0
	global_load_lds_dwordx4 v146, s[50:51]
	s_add_i32 m0, s33, 0x2000
	s_nop 0
	global_load_lds_dwordx4 v150, s[50:51]
	s_mov_b32 m0, s62
	s_nop 0
	global_load_lds_dwordx4 v14, s[46:47]
	s_mov_b32 m0, s63
	s_nop 0
	global_load_lds_dwordx4 v148, s[46:47]
	s_waitcnt vmcnt(8)
	s_waitcnt lgkmcnt(0)
	s_barrier
	s_setprio 1
	s_waitcnt lgkmcnt(0)
	v_mfma_f32_16x16x32_bf16 v[34:37], v[134:137], v[188:191], v[34:37]
	v_mfma_f32_16x16x32_bf16 v[34:37], v[138:141], v[196:199], v[34:37]
	v_mfma_f32_16x16x32_bf16 v[30:33], v[168:171], v[196:199], v[30:33]
	v_mfma_f32_16x16x32_bf16 v[30:33], v[142:145], v[188:191], v[30:33]
	v_mfma_f32_16x16x32_bf16 v[22:25], v[142:145], v[200:203], v[22:25]
	v_mfma_f32_16x16x32_bf16 v[22:25], v[168:171], v[206:209], v[22:25]
	v_mfma_f32_16x16x32_bf16 v[26:29], v[138:141], v[206:209], v[26:29]
	v_mfma_f32_16x16x32_bf16 v[26:29], v[134:137], v[200:203], v[26:29]
	v_mfma_f32_16x16x32_bf16 v[18:21], v[134:137], v[210:213], v[18:21]
	v_mfma_f32_16x16x32_bf16 v[18:21], v[138:141], v[214:217], v[18:21]
	v_mfma_f32_16x16x32_bf16 v[10:13], v[168:171], v[214:217], v[10:13]
	v_mfma_f32_16x16x32_bf16 v[10:13], v[142:145], v[210:213], v[10:13]
	v_mfma_f32_16x16x32_bf16 v[2:5], v[142:145], v[218:221], v[2:5]
	v_mfma_f32_16x16x32_bf16 v[2:5], v[168:171], v[222:225], v[2:5]
	v_mfma_f32_16x16x32_bf16 v[6:9], v[138:141], v[222:225], v[6:9]
	v_mfma_f32_16x16x32_bf16 v[6:9], v[134:137], v[218:221], v[6:9]
	s_setprio 0
	s_setprio 1
	v_mfma_f32_16x16x32_bf16 v[98:101], v[172:175], v[188:191], v[98:101]
	v_mfma_f32_16x16x32_bf16 v[98:101], v[176:179], v[196:199], v[98:101]
	v_mfma_f32_16x16x32_bf16 v[94:97], v[184:187], v[196:199], v[94:97]
	v_mfma_f32_16x16x32_bf16 v[94:97], v[180:183], v[188:191], v[94:97]
	v_mfma_f32_16x16x32_bf16 v[86:89], v[180:183], v[200:203], v[86:89]
	v_mfma_f32_16x16x32_bf16 v[86:89], v[184:187], v[206:209], v[86:89]
	v_mfma_f32_16x16x32_bf16 v[90:93], v[176:179], v[206:209], v[90:93]
	v_mfma_f32_16x16x32_bf16 v[90:93], v[172:175], v[200:203], v[90:93]
	v_mfma_f32_16x16x32_bf16 v[82:85], v[172:175], v[210:213], v[82:85]
	v_mfma_f32_16x16x32_bf16 v[82:85], v[176:179], v[214:217], v[82:85]
	v_mfma_f32_16x16x32_bf16 v[78:81], v[184:187], v[214:217], v[78:81]
	v_mfma_f32_16x16x32_bf16 v[78:81], v[180:183], v[210:213], v[78:81]
	v_mfma_f32_16x16x32_bf16 v[66:69], v[180:183], v[218:221], v[66:69]
	v_mfma_f32_16x16x32_bf16 v[66:69], v[184:187], v[222:225], v[66:69]
	v_mfma_f32_16x16x32_bf16 v[70:73], v[176:179], v[222:225], v[70:73]
	v_mfma_f32_16x16x32_bf16 v[70:73], v[172:175], v[218:221], v[70:73]
	s_setprio 0
	s_barrier
; #define PG8_STAGE(bufoff, gbase, voff) do { _Pragma("unroll") for (int _i = 0; _i < 2; ++_i) \
;         __builtin_amdgcn_global_load_lds((const unsigned*)((const char*)(gbase) + (voff)[_i]), (PG8_LAS unsigned*)(lds + (bufoff) + ldsw + _i * 8192), 16, 0, 0); } while (0)
; #define PG8_LDA(dst, b, h) do { _Pragma("unroll") for (int m = 0; m < 4; ++m) _Pragma("unroll") for (int k = 0; k < 2; ++k) dst[m][k] = *(const PG8_LAS bf16x8*)(lds + PG8_SA(b, h) + aoff + m * 2048 + k * 1024); } while (0)
; #define PG8_LDB(dst, b, h) do { _Pragma("unroll") for (int n = 0; n < 2; ++n) _Pragma("unroll") for (int k = 0; k < 2; ++k) dst[n][k] = *(const PG8_LAS bf16x8*)(lds + PG8_SB(b, h) + boff + n * 2048 + k * 1024); } while (0)
; #define PG8_MMA(ai, bj, At, Bt) do { __builtin_amdgcn_s_setprio(1); _Pragma("unroll") for (int m = 0; m < 4; ++m) _Pragma("unroll") for (int n = 0; n < 2; ++n) _Pragma("unroll") for (int k = 0; k < 2; ++k) \
;         acc[ai][bj][m][n] = __builtin_amdgcn_mfma_f32_16x16x32_bf16(Bt[n][k], At[m][k], acc[ai][bj][m][n], 0, 0, 0); __builtin_amdgcn_s_setprio(0); } while (0)
; #define PG8_WAIT_V(n) asm volatile("s_waitcnt vmcnt(" #n ")" ::: "memory")
; #define PG8_WAIT_L(n) asm volatile("s_waitcnt lgkmcnt(" #n ")" ::: "memory")
; #define PG8_BAR __builtin_amdgcn_s_barrier()
; #define PG8_SCHED __builtin_amdgcn_sched_barrier(0)
; template <class Epi, class Sched, bool ALIGN_EPI = false, bool SP2 = false>
; __device__ __forceinline__ void gemm_phase(PG8_LAS unsigned char* lds, const Gemm g, const Sched& S, const Epi& E) {
;     ...
;             PG8_LDB(B0, 1, 0); PG8_LDB(B1, 1, 1); PG8_SCHED; PG8_LDA(At, 1, 0); PG8_STAGE(PG8_SA(0, 1), a2 + hstep, voffA);
;             PG8_WAIT_V(8); PG8_WAIT_L(0); PG8_BAR; PG8_MMA(0, 0, At, B0); PG8_MMA(0, 1, At, B1); PG8_BAR; PG8_SCHED;
;             PG8_LDA(At, 1, 1); PG8_STAGE(PG8_SB(1, 0), b3, voffB); PG8_STAGE(PG8_SB(1, 1), b3 + hstep, voffB); PG8_STAGE(PG8_SA(1, 0), a3, voffA);
;             PG8_WAIT_V(8); PG8_WAIT_L(0); PG8_BAR; PG8_MMA(1, 0, At, B0); PG8_MMA(1, 1, At, B1); PG8_BAR; PG8_SCHED;
	s_add_i32 s33, 0, 0x18000
	v_add_u32_e32 v0, s33, v153
	s_add_i32 s50, 0, 0x1c000
	ds_read_b128 v[134:137], v0
	ds_read_b128 v[138:141], v0 offset:1024
	ds_read_b128 v[142:145], v0 offset:2048
	ds_read_b128 v[168:171], v0 offset:3072
	v_add_u32_e32 v0, s50, v153
	ds_read_b128 v[172:175], v0
	ds_read_b128 v[176:179], v0 offset:1024
	ds_read_b128 v[180:183], v0 offset:2048
	ds_read_b128 v[184:187], v0 offset:3072
	s_add_u32 s46, s46, 0x80000
	s_addc_u32 s47, s47, 0
	s_mov_b32 m0, s64
	ds_read_b128 v[188:191], v194 offset:32768
	ds_read_b128 v[196:199], v194 offset:33792
	ds_read_b128 v[200:203], v194 offset:34816
	ds_read_b128 v[206:209], v194 offset:35840
	ds_read_b128 v[210:213], v194 offset:36864
	ds_read_b128 v[214:217], v194 offset:37888
	ds_read_b128 v[218:221], v194 offset:38912
	ds_read_b128 v[222:225], v194 offset:39936
	global_load_lds_dwordx4 v14, s[46:47]
	s_mov_b32 m0, s65
	s_nop 0
	global_load_lds_dwordx4 v148, s[46:47]
	s_waitcnt vmcnt(8)
	s_waitcnt lgkmcnt(0)
	s_barrier
	s_setprio 1
	s_waitcnt lgkmcnt(0)
	v_mfma_f32_16x16x32_bf16 v[74:77], v[134:137], v[188:191], v[74:77]
	v_mfma_f32_16x16x32_bf16 v[74:77], v[138:141], v[196:199], v[74:77]
	v_mfma_f32_16x16x32_bf16 v[62:65], v[168:171], v[196:199], v[62:65]
	v_mfma_f32_16x16x32_bf16 v[62:65], v[142:145], v[188:191], v[62:65]
	v_mfma_f32_16x16x32_bf16 v[54:57], v[142:145], v[200:203], v[54:57]
	v_mfma_f32_16x16x32_bf16 v[54:57], v[168:171], v[206:209], v[54:57]
	v_mfma_f32_16x16x32_bf16 v[58:61], v[138:141], v[206:209], v[58:61]
	v_mfma_f32_16x16x32_bf16 v[58:61], v[134:137], v[200:203], v[58:61]
	v_mfma_f32_16x16x32_bf16 v[50:53], v[134:137], v[210:213], v[50:53]
	v_mfma_f32_16x16x32_bf16 v[50:53], v[138:141], v[214:217], v[50:53]
	v_mfma_f32_16x16x32_bf16 v[46:49], v[168:171], v[214:217], v[46:49]
	v_mfma_f32_16x16x32_bf16 v[46:49], v[142:145], v[210:213], v[46:49]
	v_mfma_f32_16x16x32_bf16 v[38:41], v[142:145], v[218:221], v[38:41]
	v_mfma_f32_16x16x32_bf16 v[38:41], v[168:171], v[222:225], v[38:41]
	v_mfma_f32_16x16x32_bf16 v[42:45], v[138:141], v[222:225], v[42:45]
	v_mfma_f32_16x16x32_bf16 v[42:45], v[134:137], v[218:221], v[42:45]
	s_setprio 0
	s_setprio 1
	v_mfma_f32_16x16x32_bf16 v[130:133], v[172:175], v[188:191], v[130:133]
	v_mfma_f32_16x16x32_bf16 v[130:133], v[176:179], v[196:199], v[130:133]
	v_mfma_f32_16x16x32_bf16 v[126:129], v[184:187], v[196:199], v[126:129]
	v_mfma_f32_16x16x32_bf16 v[126:129], v[180:183], v[188:191], v[126:129]
	v_mfma_f32_16x16x32_bf16 v[118:121], v[180:183], v[200:203], v[118:121]
	v_mfma_f32_16x16x32_bf16 v[118:121], v[184:187], v[206:209], v[118:121]
	v_mfma_f32_16x16x32_bf16 v[122:125], v[176:179], v[206:209], v[122:125]
	v_mfma_f32_16x16x32_bf16 v[122:125], v[172:175], v[200:203], v[122:125]
	v_mfma_f32_16x16x32_bf16 v[114:117], v[172:175], v[210:213], v[114:117]
	v_mfma_f32_16x16x32_bf16 v[114:117], v[176:179], v[214:217], v[114:117]
	v_mfma_f32_16x16x32_bf16 v[110:113], v[184:187], v[214:217], v[110:113]
	v_mfma_f32_16x16x32_bf16 v[110:113], v[180:183], v[210:213], v[110:113]
	v_mfma_f32_16x16x32_bf16 v[102:105], v[180:183], v[218:221], v[102:105]
	v_mfma_f32_16x16x32_bf16 v[102:105], v[184:187], v[222:225], v[102:105]
	v_mfma_f32_16x16x32_bf16 v[106:109], v[176:179], v[222:225], v[106:109]
	v_mfma_f32_16x16x32_bf16 v[106:109], v[172:175], v[218:221], v[106:109]
	s_setprio 0
	s_barrier
	s_add_i32 s33, s33, s61
	s_add_i32 m0, s33, 0xffffff80
	ds_read_b128 v[188:191], v194 offset:49152
	ds_read_b128 v[196:199], v194 offset:50176
	ds_read_b128 v[200:203], v194 offset:51200
	ds_read_b128 v[206:209], v194 offset:52224
	ds_read_b128 v[210:213], v194 offset:53248
	ds_read_b128 v[214:217], v194 offset:54272
	ds_read_b128 v[218:221], v194 offset:55296
	ds_read_b128 v[222:225], v194 offset:56320
	global_load_lds_dwordx4 v146, s[44:45] offset:128
	s_add_i32 m0, s33, 0x1f80
	s_add_i32 s33, s50, s61
	global_load_lds_dwordx4 v150, s[44:45] offset:128
	s_add_u32 s44, s44, 0x80080
	s_addc_u32 s45, s45, 0
	s_mov_b32 m0, s33
	s_nop 0
	global_load_lds_dwordx4 v146, s[44:45]
	s_add_i32 m0, s33, 0x2000
	s_nop 0
	global_load_lds_dwordx4 v150, s[44:45]
	s_mov_b32 m0, s68
	s_nop 0
	global_load_lds_dwordx4 v14, s[100:101]
	s_mov_b32 m0, s69
	s_nop 0
	global_load_lds_dwordx4 v148, s[100:101]
	s_waitcnt vmcnt(8)
	s_waitcnt lgkmcnt(0)
	s_barrier
	s_setprio 1
	s_waitcnt lgkmcnt(0)
	v_mfma_f32_16x16x32_bf16 v[34:37], v[134:137], v[188:191], v[34:37]
	v_mfma_f32_16x16x32_bf16 v[34:37], v[138:141], v[196:199], v[34:37]
	v_mfma_f32_16x16x32_bf16 v[30:33], v[168:171], v[196:199], v[30:33]
	v_mfma_f32_16x16x32_bf16 v[30:33], v[142:145], v[188:191], v[30:33]
	v_mfma_f32_16x16x32_bf16 v[22:25], v[142:145], v[200:203], v[22:25]
	v_mfma_f32_16x16x32_bf16 v[22:25], v[168:171], v[206:209], v[22:25]
	v_mfma_f32_16x16x32_bf16 v[26:29], v[138:141], v[206:209], v[26:29]
	v_mfma_f32_16x16x32_bf16 v[26:29], v[134:137], v[200:203], v[26:29]
	v_mfma_f32_16x16x32_bf16 v[18:21], v[134:137], v[210:213], v[18:21]
	v_mfma_f32_16x16x32_bf16 v[18:21], v[138:141], v[214:217], v[18:21]
	v_mfma_f32_16x16x32_bf16 v[10:13], v[168:171], v[214:217], v[10:13]
	v_mfma_f32_16x16x32_bf16 v[10:13], v[142:145], v[210:213], v[10:13]
	v_mfma_f32_16x16x32_bf16 v[2:5], v[142:145], v[218:221], v[2:5]
	v_mfma_f32_16x16x32_bf16 v[2:5], v[168:171], v[222:225], v[2:5]
	v_mfma_f32_16x16x32_bf16 v[6:9], v[138:141], v[222:225], v[6:9]
	v_mfma_f32_16x16x32_bf16 v[6:9], v[134:137], v[218:221], v[6:9]
	s_setprio 0
	s_setprio 1
	v_mfma_f32_16x16x32_bf16 v[98:101], v[172:175], v[188:191], v[98:101]
	v_mfma_f32_16x16x32_bf16 v[98:101], v[176:179], v[196:199], v[98:101]
	v_mfma_f32_16x16x32_bf16 v[94:97], v[184:187], v[196:199], v[94:97]
	v_mfma_f32_16x16x32_bf16 v[94:97], v[180:183], v[188:191], v[94:97]
	v_mfma_f32_16x16x32_bf16 v[86:89], v[180:183], v[200:203], v[86:89]
	v_mfma_f32_16x16x32_bf16 v[86:89], v[184:187], v[206:209], v[86:89]
	v_mfma_f32_16x16x32_bf16 v[90:93], v[176:179], v[206:209], v[90:93]
	v_mfma_f32_16x16x32_bf16 v[90:93], v[172:175], v[200:203], v[90:93]
	v_mfma_f32_16x16x32_bf16 v[82:85], v[172:175], v[210:213], v[82:85]
	v_mfma_f32_16x16x32_bf16 v[82:85], v[176:179], v[214:217], v[82:85]
	v_mfma_f32_16x16x32_bf16 v[78:81], v[184:187], v[214:217], v[78:81]
	v_mfma_f32_16x16x32_bf16 v[78:81], v[180:183], v[210:213], v[78:81]
	v_mfma_f32_16x16x32_bf16 v[66:69], v[180:183], v[218:221], v[66:69]
	v_mfma_f32_16x16x32_bf16 v[66:69], v[184:187], v[222:225], v[66:69]
	v_mfma_f32_16x16x32_bf16 v[70:73], v[176:179], v[222:225], v[70:73]
	v_mfma_f32_16x16x32_bf16 v[70:73], v[172:175], v[218:221], v[70:73]
	s_setprio 0
	s_barrier
	s_add_i32 s49, s49, 2
	s_add_u32 s43, s43, 0x100
	s_addc_u32 s48, s48, 0
	s_add_u32 s40, s40, 0x100
	s_addc_u32 s41, s41, 0
	s_cmp_gt_u32 s49, 29
	s_cbranch_scc0 .LBB0_588
	s_and_b64 vcc, exec, s[18:19]
	s_cbranch_vccz .LBB0_591
	s_barrier

; #define LAS __attribute__((address_space(3)))
; __global__ void __launch_bounds__(NWAVES * 64, 2) hymba_fwd(Args args) {
;     ...
;             if (IDLE_CONV_K > 0 && P.G == 256 && bxl >= 128) { __syncthreads(); LAS unsigned char* scr = P.lds + RING_OFF + P.wave * 16384; const int iw = (bxl - 128) * NWAVES + P.wave;
;                 for (int k = 0; k < IDLE_CONV_K; ++k) convert_item(P, w, ll, GU2_BASE + iw + k * 128 * NWAVES, scr); }
.LBB0_742:
	s_addk_i32 s19, 0x800
	s_addk_i32 s14, 0x400
	s_add_i32 s21, s21, 0x10000
	s_cmpk_lg_i32 s19, 0x3000
	s_cbranch_scc0 .LBB0_822

; #define PG8_STAGE(bufoff, gbase, voff) do { _Pragma("unroll") for (int _i = 0; _i < 2; ++_i) \
;         __builtin_amdgcn_global_load_lds((const unsigned*)((const char*)(gbase) + (voff)[_i]), (PG8_LAS unsigned*)(lds + (bufoff) + ldsw + _i * 8192), 16, 0, 0); } while (0)
; #define PG8_LDA(dst, b, h) do { _Pragma("unroll") for (int m = 0; m < 4; ++m) _Pragma("unroll") for (int k = 0; k < 2; ++k) dst[m][k] = *(const PG8_LAS bf16x8*)(lds + PG8_SA(b, h) + aoff + m * 2048 + k * 1024); } while (0)
; #define PG8_LDB(dst, b, h) do { _Pragma("unroll") for (int n = 0; n < 2; ++n) _Pragma("unroll") for (int k = 0; k < 2; ++k) dst[n][k] = *(const PG8_LAS bf16x8*)(lds + PG8_SB(b, h) + boff + n * 2048 + k * 1024); } while (0)
; #define PG8_WAIT_V(n) asm volatile("s_waitcnt vmcnt(" #n ")" ::: "memory")
; #define PG8_WAIT_L(n) asm volatile("s_waitcnt lgkmcnt(" #n ")" ::: "memory")
; #define PG8_BAR __builtin_amdgcn_s_barrier()
; #define PG8_SCHED __builtin_amdgcn_sched_barrier(0)
; template <class Epi, class Sched, bool ALIGN_EPI = false, bool SP2 = false>
; __device__ __forceinline__ void gemm_phase(PG8_LAS unsigned char* lds, const Gemm g, const Sched& S, const Epi& E) {
;     ...
;         const char* nA = has_next ? (const char*)g.A + (size_t)nxt.pm * tstep : cA; const char* nB = has_next ? (const char*)g.Bt + (size_t)nxt.pn * tstep : cB;
;         for (int t = 0; t < nt; t += 2) {
;             const bool last = (t == nt - 2);
;             const char* a1 = cA + (size_t)(t + 1) * kstep;
;             const char* a2 = last ? nA : cA + (size_t)(t + 2) * kstep; const char* b2 = last ? nB : cB + (size_t)(t + 2) * kstep;
;             const char* a3 = a2 + kstep; const char* b3 = b2 + kstep;
;             if (last && has_next) S.a_ready(nxt);
;             if constexpr (Epi::MID) { if (t == nt / 2) E.mid(acc, cur, wr, wc, fr, fq); }
;             if constexpr (SP2) {
;             PG8_LDB(B0, 0, 0); PG8_LDB(B1, 0, 1); PG8_SCHED; PG8_LDA(At, 0, 0); PG8_STAGE(PG8_SA(1, 1), a1 + hstep, voffA);
;             PG8_WAIT_V(8); PG8_WAIT_L(0); PG8_BAR; PG8_MMA(0, 0, At, B0); PG8_MMA(0, 1, At, B1); PG8_BAR; PG8_SCHED;
;             PG8_LDA(At, 0, 1); PG8_STAGE(PG8_SB(0, 0), b2, voffB); PG8_STAGE(PG8_SB(0, 1), b2 + hstep, voffB); PG8_STAGE(PG8_SA(0, 0), a2, voffA);
;             PG8_WAIT_V(8); PG8_WAIT_L(0); PG8_BAR; PG8_MMA(1, 0, At, B0); PG8_MMA(1, 1, At, B1); PG8_BAR; PG8_SCHED;
.LBB0_1222:
	s_ashr_i32 s21, s20, 31
	s_lshl_b64 s[22:23], s[20:21], 20
	s_add_u32 s22, s8, s22
	s_addc_u32 s23, s9, s23
	s_and_b64 s[24:25], s[2:3], exec
	s_cselect_b32 s5, s23, s29
	s_cselect_b32 s11, s22, s28
	s_ashr_i32 s19, s18, 31
	s_lshl_b64 s[24:25], s[18:19], 20
	s_add_u32 s24, s36, s24
	s_addc_u32 s25, s37, s25
	s_and_b64 s[30:31], s[2:3], exec
	s_cselect_b32 s19, s25, s27
	s_cselect_b32 s21, s24, s26
	s_add_u32 s54, s26, 0x100
	s_addc_u32 s55, s27, 0
	s_add_u32 s26, s28, 0x80080
	s_addc_u32 s27, s29, 0
	s_mov_b32 s56, -2
	s_add_u32 s28, s26, 0xfff80080
	s_addc_u32 s29, s27, -1
	s_add_i32 s33, 0, 0x10000
	s_cmp_eq_u32 s56, 28
	s_cselect_b32 s31, s5, s29
	s_cselect_b32 s30, s11, s28
	v_add_u32_e32 v161, s33, v155
	s_cselect_b32 s29, s19, s55
	s_cselect_b32 s28, s21, s54
	s_add_i32 s57, 0, 0x14000
	ds_read_b128 v[142:145], v161
	ds_read_b128 v[146:149], v161 offset:1024
	ds_read_b128 v[150:153], v161 offset:2048
	ds_read_b128 v[162:165], v161 offset:3072
	v_add_u32_e32 v161, s57, v155
	ds_read_b128 v[166:169], v161
	ds_read_b128 v[170:173], v161 offset:1024
	ds_read_b128 v[174:177], v161 offset:2048
	ds_read_b128 v[178:181], v161 offset:3072
	s_add_i32 m0, s42, 0xc000
	ds_read_b128 v[182:185], v160
	ds_read_b128 v[186:189], v160 offset:1024
	ds_read_b128 v[190:193], v160 offset:2048
	ds_read_b128 v[194:197], v160 offset:3072
	ds_read_b128 v[198:201], v160 offset:4096
	ds_read_b128 v[206:209], v160 offset:5120
	ds_read_b128 v[210:213], v160 offset:6144
	ds_read_b128 v[214:217], v160 offset:7168
	global_load_lds_dwordx4 v140, s[26:27]
	s_add_i32 m0, s42, 0xe000
	s_nop 0
	global_load_lds_dwordx4 v138, s[26:27]
	s_waitcnt vmcnt(8)
	s_waitcnt lgkmcnt(0)
	s_barrier
	s_setprio 1
	s_waitcnt lgkmcnt(0)
	v_mfma_f32_16x16x32_bf16 v[130:133], v[142:145], v[182:185], 0
	v_mfma_f32_16x16x32_bf16 v[130:133], v[146:149], v[186:189], v[130:133]
	v_mfma_f32_16x16x32_bf16 v[126:129], v[162:165], v[186:189], 0
	v_mfma_f32_16x16x32_bf16 v[126:129], v[150:153], v[182:185], v[126:129]
	v_mfma_f32_16x16x32_bf16 v[110:113], v[150:153], v[190:193], 0
	v_mfma_f32_16x16x32_bf16 v[110:113], v[162:165], v[194:197], v[110:113]
	v_mfma_f32_16x16x32_bf16 v[114:117], v[146:149], v[194:197], 0
	v_mfma_f32_16x16x32_bf16 v[114:117], v[142:145], v[190:193], v[114:117]
	v_mfma_f32_16x16x32_bf16 v[98:101], v[142:145], v[198:201], 0
	v_mfma_f32_16x16x32_bf16 v[98:101], v[146:149], v[206:209], v[98:101]
	v_mfma_f32_16x16x32_bf16 v[94:97], v[162:165], v[206:209], 0
	v_mfma_f32_16x16x32_bf16 v[94:97], v[150:153], v[198:201], v[94:97]
	v_mfma_f32_16x16x32_bf16 v[78:81], v[150:153], v[210:213], 0
	v_mfma_f32_16x16x32_bf16 v[78:81], v[162:165], v[214:217], v[78:81]
	v_mfma_f32_16x16x32_bf16 v[82:85], v[146:149], v[214:217], 0
	v_mfma_f32_16x16x32_bf16 v[82:85], v[142:145], v[210:213], v[82:85]
	s_setprio 0
	s_setprio 1
	v_mfma_f32_16x16x32_bf16 v[122:125], v[166:169], v[182:185], 0
	v_mfma_f32_16x16x32_bf16 v[122:125], v[170:173], v[186:189], v[122:125]
	v_mfma_f32_16x16x32_bf16 v[118:121], v[178:181], v[186:189], 0
	v_mfma_f32_16x16x32_bf16 v[118:121], v[174:177], v[182:185], v[118:121]
	v_mfma_f32_16x16x32_bf16 v[102:105], v[174:177], v[190:193], 0
	v_mfma_f32_16x16x32_bf16 v[102:105], v[178:181], v[194:197], v[102:105]
	v_mfma_f32_16x16x32_bf16 v[106:109], v[170:173], v[194:197], 0
	v_mfma_f32_16x16x32_bf16 v[106:109], v[166:169], v[190:193], v[106:109]
	v_mfma_f32_16x16x32_bf16 v[90:93], v[166:169], v[198:201], 0
	v_mfma_f32_16x16x32_bf16 v[90:93], v[170:173], v[206:209], v[90:93]
	v_mfma_f32_16x16x32_bf16 v[86:89], v[178:181], v[206:209], 0
	v_mfma_f32_16x16x32_bf16 v[86:89], v[174:177], v[198:201], v[86:89]
	v_mfma_f32_16x16x32_bf16 v[70:73], v[174:177], v[210:213], 0
	v_mfma_f32_16x16x32_bf16 v[70:73], v[178:181], v[214:217], v[70:73]
	v_mfma_f32_16x16x32_bf16 v[74:77], v[170:173], v[214:217], 0
	v_mfma_f32_16x16x32_bf16 v[74:77], v[166:169], v[210:213], v[74:77]
	s_setprio 0
	s_barrier
	s_add_i32 s33, s33, s40
	s_mov_b32 m0, s33
	ds_read_b128 v[182:185], v160 offset:16384
	ds_read_b128 v[186:189], v160 offset:17408
	ds_read_b128 v[190:193], v160 offset:18432
	ds_read_b128 v[194:197], v160 offset:19456
	ds_read_b128 v[198:201], v160 offset:20480
	ds_read_b128 v[206:209], v160 offset:21504
	ds_read_b128 v[210:213], v160 offset:22528
	ds_read_b128 v[214:217], v160 offset:23552
	global_load_lds_dwordx4 v0, s[28:29]
	s_add_i32 m0, s33, 0x2000
	s_add_u32 s100, s30, 0x80
	s_addc_u32 s101, s31, 0
	s_add_u32 s58, s28, 0x80000
	s_addc_u32 s59, s29, 0
	s_add_i32 s33, s57, s40
	global_load_lds_dwordx4 v14, s[28:29]
	s_mov_b32 m0, s33
	s_nop 0
	global_load_lds_dwordx4 v0, s[58:59]
	s_add_i32 m0, s33, 0x2000
	s_nop 0
	global_load_lds_dwordx4 v14, s[58:59]
	s_mov_b32 m0, s42
	s_nop 0
	global_load_lds_dwordx4 v136, s[30:31]
	s_mov_b32 m0, s43
	s_nop 0
	global_load_lds_dwordx4 v134, s[30:31]
	s_waitcnt vmcnt(8)
	s_waitcnt lgkmcnt(0)
	s_barrier
; #define PG8_STAGE(bufoff, gbase, voff) do { _Pragma("unroll") for (int _i = 0; _i < 2; ++_i) \
;         __builtin_amdgcn_global_load_lds((const unsigned*)((const char*)(gbase) + (voff)[_i]), (PG8_LAS unsigned*)(lds + (bufoff) + ldsw + _i * 8192), 16, 0, 0); } while (0)
; #define PG8_LDA(dst, b, h) do { _Pragma("unroll") for (int m = 0; m < 4; ++m) _Pragma("unroll") for (int k = 0; k < 2; ++k) dst[m][k] = *(const PG8_LAS bf16x8*)(lds + PG8_SA(b, h) + aoff + m * 2048 + k * 1024); } while (0)
; #define PG8_LDB(dst, b, h) do { _Pragma("unroll") for (int n = 0; n < 2; ++n) _Pragma("unroll") for (int k = 0; k < 2; ++k) dst[n][k] = *(const PG8_LAS bf16x8*)(lds + PG8_SB(b, h) + boff + n * 2048 + k * 1024); } while (0)
; #define PG8_MMA(ai, bj, At, Bt) do { __builtin_amdgcn_s_setprio(1); _Pragma("unroll") for (int m = 0; m < 4; ++m) _Pragma("unroll") for (int n = 0; n < 2; ++n) _Pragma("unroll") for (int k = 0; k < 2; ++k) \
;         acc[ai][bj][m][n] = __builtin_amdgcn_mfma_f32_16x16x32_bf16(Bt[n][k], At[m][k], acc[ai][bj][m][n], 0, 0, 0); __builtin_amdgcn_s_setprio(0); } while (0)
; #define PG8_WAIT_V(n) asm volatile("s_waitcnt vmcnt(" #n ")" ::: "memory")
; #define PG8_WAIT_L(n) asm volatile("s_waitcnt lgkmcnt(" #n ")" ::: "memory")
; #define PG8_BAR __builtin_amdgcn_s_barrier()
; #define PG8_SCHED __builtin_amdgcn_sched_barrier(0)
; template <class Epi, class Sched, bool ALIGN_EPI = false, bool SP2 = false>
; __device__ __forceinline__ void gemm_phase(PG8_LAS unsigned char* lds, const Gemm g, const Sched& S, const Epi& E) {
;     ...
;             PG8_WAIT_V(8); PG8_WAIT_L(0); PG8_BAR; PG8_MMA(1, 0, At, B0); PG8_MMA(1, 1, At, B1); PG8_BAR; PG8_SCHED;
;             PG8_LDB(B0, 1, 0); PG8_LDB(B1, 1, 1); PG8_SCHED; PG8_LDA(At, 1, 0); PG8_STAGE(PG8_SA(0, 1), a2 + hstep, voffA);
;             PG8_WAIT_V(8); PG8_WAIT_L(0); PG8_BAR; PG8_MMA(0, 0, At, B0); PG8_MMA(0, 1, At, B1); PG8_BAR; PG8_SCHED;
	s_setprio 1
	s_waitcnt lgkmcnt(0)
	v_mfma_f32_16x16x32_bf16 v[66:69], v[142:145], v[182:185], 0
	v_mfma_f32_16x16x32_bf16 v[66:69], v[146:149], v[186:189], v[66:69]
	v_mfma_f32_16x16x32_bf16 v[62:65], v[162:165], v[186:189], 0
	v_mfma_f32_16x16x32_bf16 v[62:65], v[150:153], v[182:185], v[62:65]
	v_mfma_f32_16x16x32_bf16 v[46:49], v[150:153], v[190:193], 0
	v_mfma_f32_16x16x32_bf16 v[46:49], v[162:165], v[194:197], v[46:49]
	v_mfma_f32_16x16x32_bf16 v[50:53], v[146:149], v[194:197], 0
	v_mfma_f32_16x16x32_bf16 v[50:53], v[142:145], v[190:193], v[50:53]
	v_mfma_f32_16x16x32_bf16 v[34:37], v[142:145], v[198:201], 0
	v_mfma_f32_16x16x32_bf16 v[34:37], v[146:149], v[206:209], v[34:37]
	v_mfma_f32_16x16x32_bf16 v[30:33], v[162:165], v[206:209], 0
	v_mfma_f32_16x16x32_bf16 v[30:33], v[150:153], v[198:201], v[30:33]
	v_mfma_f32_16x16x32_bf16 v[10:13], v[150:153], v[210:213], 0
	v_mfma_f32_16x16x32_bf16 v[10:13], v[162:165], v[214:217], v[10:13]
	v_mfma_f32_16x16x32_bf16 v[18:21], v[146:149], v[214:217], 0
	v_mfma_f32_16x16x32_bf16 v[18:21], v[142:145], v[210:213], v[18:21]
	s_setprio 0
	s_setprio 1
	v_mfma_f32_16x16x32_bf16 v[58:61], v[166:169], v[182:185], 0
	v_mfma_f32_16x16x32_bf16 v[58:61], v[170:173], v[186:189], v[58:61]
	v_mfma_f32_16x16x32_bf16 v[54:57], v[178:181], v[186:189], 0
	v_mfma_f32_16x16x32_bf16 v[54:57], v[174:177], v[182:185], v[54:57]
	v_mfma_f32_16x16x32_bf16 v[38:41], v[174:177], v[190:193], 0
	v_mfma_f32_16x16x32_bf16 v[38:41], v[178:181], v[194:197], v[38:41]
	v_mfma_f32_16x16x32_bf16 v[42:45], v[170:173], v[194:197], 0
	v_mfma_f32_16x16x32_bf16 v[42:45], v[166:169], v[190:193], v[42:45]
	v_mfma_f32_16x16x32_bf16 v[26:29], v[166:169], v[198:201], 0
	v_mfma_f32_16x16x32_bf16 v[26:29], v[170:173], v[206:209], v[26:29]
	v_mfma_f32_16x16x32_bf16 v[22:25], v[178:181], v[206:209], 0
	v_mfma_f32_16x16x32_bf16 v[22:25], v[174:177], v[198:201], v[22:25]
	v_mfma_f32_16x16x32_bf16 v[2:5], v[174:177], v[210:213], 0
	v_mfma_f32_16x16x32_bf16 v[2:5], v[178:181], v[214:217], v[2:5]
	v_mfma_f32_16x16x32_bf16 v[6:9], v[170:173], v[214:217], 0
	v_mfma_f32_16x16x32_bf16 v[6:9], v[166:169], v[210:213], v[6:9]
	s_setprio 0
	s_barrier
	s_add_i32 s33, 0, 0x18000
	v_add_u32_e32 v161, s33, v155
	s_add_i32 s57, 0, 0x1c000
	ds_read_b128 v[142:145], v161
	ds_read_b128 v[146:149], v161 offset:1024
	ds_read_b128 v[150:153], v161 offset:2048
	ds_read_b128 v[162:165], v161 offset:3072
	v_add_u32_e32 v161, s57, v155
	ds_read_b128 v[166:169], v161
	ds_read_b128 v[170:173], v161 offset:1024
	ds_read_b128 v[174:177], v161 offset:2048
	ds_read_b128 v[178:181], v161 offset:3072
	s_add_u32 s30, s30, 0x80000
	s_addc_u32 s31, s31, 0
	s_mov_b32 m0, s44
	ds_read_b128 v[182:185], v160 offset:32768
	ds_read_b128 v[186:189], v160 offset:33792
	ds_read_b128 v[190:193], v160 offset:34816
	ds_read_b128 v[194:197], v160 offset:35840
	ds_read_b128 v[198:201], v160 offset:36864
	ds_read_b128 v[206:209], v160 offset:37888
	ds_read_b128 v[210:213], v160 offset:38912
	ds_read_b128 v[214:217], v160 offset:39936
	global_load_lds_dwordx4 v136, s[30:31]
	s_mov_b32 m0, s45
	s_nop 0
	global_load_lds_dwordx4 v134, s[30:31]
	s_waitcnt vmcnt(8)
	s_waitcnt lgkmcnt(0)
	s_barrier
	s_setprio 1
	s_waitcnt lgkmcnt(0)
	v_mfma_f32_16x16x32_bf16 v[130:133], v[142:145], v[182:185], v[130:133]
	v_mfma_f32_16x16x32_bf16 v[130:133], v[146:149], v[186:189], v[130:133]
	v_mfma_f32_16x16x32_bf16 v[126:129], v[162:165], v[186:189], v[126:129]
	v_mfma_f32_16x16x32_bf16 v[126:129], v[150:153], v[182:185], v[126:129]
	v_mfma_f32_16x16x32_bf16 v[110:113], v[150:153], v[190:193], v[110:113]
	v_mfma_f32_16x16x32_bf16 v[110:113], v[162:165], v[194:197], v[110:113]
	v_mfma_f32_16x16x32_bf16 v[114:117], v[146:149], v[194:197], v[114:117]
	v_mfma_f32_16x16x32_bf16 v[114:117], v[142:145], v[190:193], v[114:117]
	v_mfma_f32_16x16x32_bf16 v[98:101], v[142:145], v[198:201], v[98:101]
	v_mfma_f32_16x16x32_bf16 v[98:101], v[146:149], v[206:209], v[98:101]
	v_mfma_f32_16x16x32_bf16 v[94:97], v[162:165], v[206:209], v[94:97]
	v_mfma_f32_16x16x32_bf16 v[94:97], v[150:153], v[198:201], v[94:97]
	v_mfma_f32_16x16x32_bf16 v[78:81], v[150:153], v[210:213], v[78:81]
	v_mfma_f32_16x16x32_bf16 v[78:81], v[162:165], v[214:217], v[78:81]
	v_mfma_f32_16x16x32_bf16 v[82:85], v[146:149], v[214:217], v[82:85]
	v_mfma_f32_16x16x32_bf16 v[82:85], v[142:145], v[210:213], v[82:85]
	s_setprio 0
	s_setprio 1
	v_mfma_f32_16x16x32_bf16 v[122:125], v[166:169], v[182:185], v[122:125]
	v_mfma_f32_16x16x32_bf16 v[122:125], v[170:173], v[186:189], v[122:125]
	v_mfma_f32_16x16x32_bf16 v[118:121], v[178:181], v[186:189], v[118:121]
	v_mfma_f32_16x16x32_bf16 v[118:121], v[174:177], v[182:185], v[118:121]
	v_mfma_f32_16x16x32_bf16 v[102:105], v[174:177], v[190:193], v[102:105]
	v_mfma_f32_16x16x32_bf16 v[102:105], v[178:181], v[194:197], v[102:105]
	v_mfma_f32_16x16x32_bf16 v[106:109], v[170:173], v[194:197], v[106:109]
	v_mfma_f32_16x16x32_bf16 v[106:109], v[166:169], v[190:193], v[106:109]
	v_mfma_f32_16x16x32_bf16 v[90:93], v[166:169], v[198:201], v[90:93]
	v_mfma_f32_16x16x32_bf16 v[90:93], v[170:173], v[206:209], v[90:93]
	v_mfma_f32_16x16x32_bf16 v[86:89], v[178:181], v[206:209], v[86:89]
	v_mfma_f32_16x16x32_bf16 v[86:89], v[174:177], v[198:201], v[86:89]
	v_mfma_f32_16x16x32_bf16 v[70:73], v[174:177], v[210:213], v[70:73]
	v_mfma_f32_16x16x32_bf16 v[70:73], v[178:181], v[214:217], v[70:73]
	v_mfma_f32_16x16x32_bf16 v[74:77], v[170:173], v[214:217], v[74:77]
	v_mfma_f32_16x16x32_bf16 v[74:77], v[166:169], v[210:213], v[74:77]
	s_setprio 0
	s_barrier
; #define PG8_STAGE(bufoff, gbase, voff) do { _Pragma("unroll") for (int _i = 0; _i < 2; ++_i) \
;         __builtin_amdgcn_global_load_lds((const unsigned*)((const char*)(gbase) + (voff)[_i]), (PG8_LAS unsigned*)(lds + (bufoff) + ldsw + _i * 8192), 16, 0, 0); } while (0)
; #define PG8_LDA(dst, b, h) do { _Pragma("unroll") for (int m = 0; m < 4; ++m) _Pragma("unroll") for (int k = 0; k < 2; ++k) dst[m][k] = *(const PG8_LAS bf16x8*)(lds + PG8_SA(b, h) + aoff + m * 2048 + k * 1024); } while (0)
; #define PG8_LDB(dst, b, h) do { _Pragma("unroll") for (int n = 0; n < 2; ++n) _Pragma("unroll") for (int k = 0; k < 2; ++k) dst[n][k] = *(const PG8_LAS bf16x8*)(lds + PG8_SB(b, h) + boff + n * 2048 + k * 1024); } while (0)
; #define PG8_MMA(ai, bj, At, Bt) do { __builtin_amdgcn_s_setprio(1); _Pragma("unroll") for (int m = 0; m < 4; ++m) _Pragma("unroll") for (int n = 0; n < 2; ++n) _Pragma("unroll") for (int k = 0; k < 2; ++k) \
;         acc[ai][bj][m][n] = __builtin_amdgcn_mfma_f32_16x16x32_bf16(Bt[n][k], At[m][k], acc[ai][bj][m][n], 0, 0, 0); __builtin_amdgcn_s_setprio(0); } while (0)
; #define PG8_WAIT_V(n) asm volatile("s_waitcnt vmcnt(" #n ")" ::: "memory")
; template <class Epi, class Sched, bool ALIGN_EPI = false, bool SP2 = false>
; __device__ __forceinline__ void gemm_phase(PG8_LAS unsigned char* lds, const Gemm g, const Sched& S, const Epi& E) {
;     ...
;             PG8_LDB(B0, 0, 0); PG8_LDB(B1, 0, 1); PG8_SCHED; PG8_LDA(At, 0, 0); PG8_STAGE(PG8_SA(1, 1), a1 + hstep, voffA);
;             PG8_WAIT_V(8); PG8_WAIT_L(0); PG8_BAR; PG8_MMA(0, 0, At, B0); PG8_MMA(0, 1, At, B1); PG8_BAR; PG8_SCHED;
;             PG8_LDA(At, 0, 1); PG8_STAGE(PG8_SB(0, 0), b2, voffB); PG8_STAGE(PG8_SB(0, 1), b2 + hstep, voffB); PG8_STAGE(PG8_SA(0, 0), a2, voffA);
;             PG8_WAIT_V(8); PG8_WAIT_L(0); PG8_BAR; PG8_MMA(1, 0, At, B0); PG8_MMA(1, 1, At, B1); PG8_BAR; PG8_SCHED;
;             PG8_LDB(B0, 1, 0); PG8_LDB(B1, 1, 1); PG8_SCHED; PG8_LDA(At, 1, 0); PG8_STAGE(PG8_SA(0, 1), a2 + hstep, voffA);
;             PG8_WAIT_V(8); PG8_WAIT_L(0); PG8_BAR; PG8_MMA(0, 0, At, B0); PG8_MMA(0, 1, At, B1); PG8_BAR; PG8_SCHED;
;             PG8_LDA(At, 1, 1); PG8_STAGE(PG8_SB(1, 0), b3, voffB); PG8_STAGE(PG8_SB(1, 1), b3 + hstep, voffB); PG8_STAGE(PG8_SA(1, 0), a3, voffA);
;             PG8_WAIT_V(8); PG8_WAIT_L(0); PG8_BAR; PG8_MMA(1, 0, At, B0); PG8_MMA(1, 1, At, B1); PG8_BAR; PG8_SCHED;
	s_add_i32 s30, s33, s40
	s_add_i32 m0, s30, 0xffffff80
	ds_read_b128 v[182:185], v160 offset:49152
	ds_read_b128 v[186:189], v160 offset:50176
	ds_read_b128 v[190:193], v160 offset:51200
	ds_read_b128 v[194:197], v160 offset:52224
	ds_read_b128 v[198:201], v160 offset:53248
	ds_read_b128 v[206:209], v160 offset:54272
	ds_read_b128 v[210:213], v160 offset:55296
	ds_read_b128 v[214:217], v160 offset:56320
	global_load_lds_dwordx4 v0, s[28:29] offset:128
	s_add_i32 m0, s30, 0x1f80
	s_add_i32 s30, s57, s40
	global_load_lds_dwordx4 v14, s[28:29] offset:128
	s_add_u32 s28, s28, 0x80080
	s_addc_u32 s29, s29, 0
	s_mov_b32 m0, s30
	s_nop 0
	global_load_lds_dwordx4 v0, s[28:29]
	s_add_i32 m0, s30, 0x2000
	s_nop 0
	global_load_lds_dwordx4 v14, s[28:29]
	s_mov_b32 m0, s47
	s_nop 0
	global_load_lds_dwordx4 v136, s[100:101]
	s_mov_b32 m0, s48
	s_nop 0
	global_load_lds_dwordx4 v134, s[100:101]
	s_waitcnt vmcnt(8)
	s_waitcnt lgkmcnt(0)
	s_barrier
	s_setprio 1
	s_waitcnt lgkmcnt(0)
	v_mfma_f32_16x16x32_bf16 v[66:69], v[142:145], v[182:185], v[66:69]
	v_mfma_f32_16x16x32_bf16 v[66:69], v[146:149], v[186:189], v[66:69]
	v_mfma_f32_16x16x32_bf16 v[62:65], v[162:165], v[186:189], v[62:65]
	v_mfma_f32_16x16x32_bf16 v[62:65], v[150:153], v[182:185], v[62:65]
	v_mfma_f32_16x16x32_bf16 v[46:49], v[150:153], v[190:193], v[46:49]
	v_mfma_f32_16x16x32_bf16 v[46:49], v[162:165], v[194:197], v[46:49]
	v_mfma_f32_16x16x32_bf16 v[50:53], v[146:149], v[194:197], v[50:53]
	v_mfma_f32_16x16x32_bf16 v[50:53], v[142:145], v[190:193], v[50:53]
	v_mfma_f32_16x16x32_bf16 v[34:37], v[142:145], v[198:201], v[34:37]
	v_mfma_f32_16x16x32_bf16 v[34:37], v[146:149], v[206:209], v[34:37]
	v_mfma_f32_16x16x32_bf16 v[30:33], v[162:165], v[206:209], v[30:33]
	v_mfma_f32_16x16x32_bf16 v[30:33], v[150:153], v[198:201], v[30:33]
	v_mfma_f32_16x16x32_bf16 v[10:13], v[150:153], v[210:213], v[10:13]
	v_mfma_f32_16x16x32_bf16 v[10:13], v[162:165], v[214:217], v[10:13]
	v_mfma_f32_16x16x32_bf16 v[18:21], v[146:149], v[214:217], v[18:21]
	v_mfma_f32_16x16x32_bf16 v[18:21], v[142:145], v[210:213], v[18:21]
	s_setprio 0
	s_setprio 1
	v_mfma_f32_16x16x32_bf16 v[58:61], v[166:169], v[182:185], v[58:61]
	v_mfma_f32_16x16x32_bf16 v[58:61], v[170:173], v[186:189], v[58:61]
	v_mfma_f32_16x16x32_bf16 v[54:57], v[178:181], v[186:189], v[54:57]
	v_mfma_f32_16x16x32_bf16 v[54:57], v[174:177], v[182:185], v[54:57]
	v_mfma_f32_16x16x32_bf16 v[38:41], v[174:177], v[190:193], v[38:41]
	v_mfma_f32_16x16x32_bf16 v[38:41], v[178:181], v[194:197], v[38:41]
	v_mfma_f32_16x16x32_bf16 v[42:45], v[170:173], v[194:197], v[42:45]
	v_mfma_f32_16x16x32_bf16 v[42:45], v[166:169], v[190:193], v[42:45]
	v_mfma_f32_16x16x32_bf16 v[26:29], v[166:169], v[198:201], v[26:29]
	v_mfma_f32_16x16x32_bf16 v[26:29], v[170:173], v[206:209], v[26:29]
	v_mfma_f32_16x16x32_bf16 v[22:25], v[178:181], v[206:209], v[22:25]
	v_mfma_f32_16x16x32_bf16 v[22:25], v[174:177], v[198:201], v[22:25]
	v_mfma_f32_16x16x32_bf16 v[2:5], v[174:177], v[210:213], v[2:5]
	v_mfma_f32_16x16x32_bf16 v[2:5], v[178:181], v[214:217], v[2:5]
	v_mfma_f32_16x16x32_bf16 v[6:9], v[170:173], v[214:217], v[6:9]
	v_mfma_f32_16x16x32_bf16 v[6:9], v[166:169], v[210:213], v[6:9]
	s_setprio 0
	s_barrier
	s_add_i32 s56, s56, 2
	s_add_u32 s54, s54, 0x100
	s_addc_u32 s55, s55, 0
	s_add_u32 s26, s26, 0x100
	s_addc_u32 s27, s27, 0
	s_cmp_gt_u32 s56, 29
.LBB0_1223:
	s_add_u32 s28, s26, 0xfff80080
	s_addc_u32 s29, s27, -1
	s_add_i32 s33, 0, 0x10000
	s_cmp_eq_u32 s56, 28
	s_cselect_b32 s31, s5, s29
	s_cselect_b32 s30, s11, s28
	v_add_u32_e32 v161, s33, v155
	s_cselect_b32 s29, s19, s55
	s_cselect_b32 s28, s21, s54
	s_add_i32 s57, 0, 0x14000
	ds_read_b128 v[142:145], v161
	ds_read_b128 v[146:149], v161 offset:1024
	ds_read_b128 v[150:153], v161 offset:2048
	ds_read_b128 v[162:165], v161 offset:3072
	v_add_u32_e32 v161, s57, v155
	ds_read_b128 v[166:169], v161
	ds_read_b128 v[170:173], v161 offset:1024
	ds_read_b128 v[174:177], v161 offset:2048
	ds_read_b128 v[178:181], v161 offset:3072
	s_add_i32 m0, s42, 0xc000
	ds_read_b128 v[182:185], v160
	ds_read_b128 v[186:189], v160 offset:1024
	ds_read_b128 v[190:193], v160 offset:2048
	ds_read_b128 v[194:197], v160 offset:3072
	ds_read_b128 v[198:201], v160 offset:4096
	ds_read_b128 v[206:209], v160 offset:5120
	ds_read_b128 v[210:213], v160 offset:6144
	ds_read_b128 v[214:217], v160 offset:7168
	global_load_lds_dwordx4 v140, s[26:27]
	s_add_i32 m0, s42, 0xe000
	s_nop 0
	global_load_lds_dwordx4 v138, s[26:27]
	s_waitcnt vmcnt(8)
	s_waitcnt lgkmcnt(0)
	s_barrier
; #define PG8_STAGE(bufoff, gbase, voff) do { _Pragma("unroll") for (int _i = 0; _i < 2; ++_i) \
;         __builtin_amdgcn_global_load_lds((const unsigned*)((const char*)(gbase) + (voff)[_i]), (PG8_LAS unsigned*)(lds + (bufoff) + ldsw + _i * 8192), 16, 0, 0); } while (0)
; #define PG8_LDA(dst, b, h) do { _Pragma("unroll") for (int m = 0; m < 4; ++m) _Pragma("unroll") for (int k = 0; k < 2; ++k) dst[m][k] = *(const PG8_LAS bf16x8*)(lds + PG8_SA(b, h) + aoff + m * 2048 + k * 1024); } while (0)
; #define PG8_MMA(ai, bj, At, Bt) do { __builtin_amdgcn_s_setprio(1); _Pragma("unroll") for (int m = 0; m < 4; ++m) _Pragma("unroll") for (int n = 0; n < 2; ++n) _Pragma("unroll") for (int k = 0; k < 2; ++k) \
;         acc[ai][bj][m][n] = __builtin_amdgcn_mfma_f32_16x16x32_bf16(Bt[n][k], At[m][k], acc[ai][bj][m][n], 0, 0, 0); __builtin_amdgcn_s_setprio(0); } while (0)
; #define PG8_WAIT_V(n) asm volatile("s_waitcnt vmcnt(" #n ")" ::: "memory")
; #define PG8_WAIT_L(n) asm volatile("s_waitcnt lgkmcnt(" #n ")" ::: "memory")
; #define PG8_BAR __builtin_amdgcn_s_barrier()
; #define PG8_SCHED __builtin_amdgcn_sched_barrier(0)
; template <class Epi, class Sched, bool ALIGN_EPI = false, bool SP2 = false>
; __device__ __forceinline__ void gemm_phase(PG8_LAS unsigned char* lds, const Gemm g, const Sched& S, const Epi& E) {
;     ...
;             PG8_WAIT_V(8); PG8_WAIT_L(0); PG8_BAR; PG8_MMA(0, 0, At, B0); PG8_MMA(0, 1, At, B1); PG8_BAR; PG8_SCHED;
;             PG8_LDA(At, 0, 1); PG8_STAGE(PG8_SB(0, 0), b2, voffB); PG8_STAGE(PG8_SB(0, 1), b2 + hstep, voffB); PG8_STAGE(PG8_SA(0, 0), a2, voffA);
;             PG8_WAIT_V(8); PG8_WAIT_L(0); PG8_BAR; PG8_MMA(1, 0, At, B0); PG8_MMA(1, 1, At, B1); PG8_BAR; PG8_SCHED;
	s_setprio 1
	s_waitcnt lgkmcnt(0)
	v_mfma_f32_16x16x32_bf16 v[130:133], v[142:145], v[182:185], v[130:133]
	v_mfma_f32_16x16x32_bf16 v[130:133], v[146:149], v[186:189], v[130:133]
	v_mfma_f32_16x16x32_bf16 v[126:129], v[162:165], v[186:189], v[126:129]
	v_mfma_f32_16x16x32_bf16 v[126:129], v[150:153], v[182:185], v[126:129]
	v_mfma_f32_16x16x32_bf16 v[110:113], v[150:153], v[190:193], v[110:113]
	v_mfma_f32_16x16x32_bf16 v[110:113], v[162:165], v[194:197], v[110:113]
	v_mfma_f32_16x16x32_bf16 v[114:117], v[146:149], v[194:197], v[114:117]
	v_mfma_f32_16x16x32_bf16 v[114:117], v[142:145], v[190:193], v[114:117]
	v_mfma_f32_16x16x32_bf16 v[98:101], v[142:145], v[198:201], v[98:101]
	v_mfma_f32_16x16x32_bf16 v[98:101], v[146:149], v[206:209], v[98:101]
	v_mfma_f32_16x16x32_bf16 v[94:97], v[162:165], v[206:209], v[94:97]
	v_mfma_f32_16x16x32_bf16 v[94:97], v[150:153], v[198:201], v[94:97]
	v_mfma_f32_16x16x32_bf16 v[78:81], v[150:153], v[210:213], v[78:81]
	v_mfma_f32_16x16x32_bf16 v[78:81], v[162:165], v[214:217], v[78:81]
	v_mfma_f32_16x16x32_bf16 v[82:85], v[146:149], v[214:217], v[82:85]
	v_mfma_f32_16x16x32_bf16 v[82:85], v[142:145], v[210:213], v[82:85]
	s_setprio 0
	s_setprio 1
	v_mfma_f32_16x16x32_bf16 v[122:125], v[166:169], v[182:185], v[122:125]
	v_mfma_f32_16x16x32_bf16 v[122:125], v[170:173], v[186:189], v[122:125]
	v_mfma_f32_16x16x32_bf16 v[118:121], v[178:181], v[186:189], v[118:121]
	v_mfma_f32_16x16x32_bf16 v[118:121], v[174:177], v[182:185], v[118:121]
	v_mfma_f32_16x16x32_bf16 v[102:105], v[174:177], v[190:193], v[102:105]
	v_mfma_f32_16x16x32_bf16 v[102:105], v[178:181], v[194:197], v[102:105]
	v_mfma_f32_16x16x32_bf16 v[106:109], v[170:173], v[194:197], v[106:109]
	v_mfma_f32_16x16x32_bf16 v[106:109], v[166:169], v[190:193], v[106:109]
	v_mfma_f32_16x16x32_bf16 v[90:93], v[166:169], v[198:201], v[90:93]
	v_mfma_f32_16x16x32_bf16 v[90:93], v[170:173], v[206:209], v[90:93]
	v_mfma_f32_16x16x32_bf16 v[86:89], v[178:181], v[206:209], v[86:89]
	v_mfma_f32_16x16x32_bf16 v[86:89], v[174:177], v[198:201], v[86:89]
	v_mfma_f32_16x16x32_bf16 v[70:73], v[174:177], v[210:213], v[70:73]
	v_mfma_f32_16x16x32_bf16 v[70:73], v[178:181], v[214:217], v[70:73]
	v_mfma_f32_16x16x32_bf16 v[74:77], v[170:173], v[214:217], v[74:77]
	v_mfma_f32_16x16x32_bf16 v[74:77], v[166:169], v[210:213], v[74:77]
	s_setprio 0
	s_barrier
	s_add_i32 s33, s33, s40
	s_mov_b32 m0, s33
	ds_read_b128 v[182:185], v160 offset:16384
	ds_read_b128 v[186:189], v160 offset:17408
	ds_read_b128 v[190:193], v160 offset:18432
	ds_read_b128 v[194:197], v160 offset:19456
	ds_read_b128 v[198:201], v160 offset:20480
	ds_read_b128 v[206:209], v160 offset:21504
	ds_read_b128 v[210:213], v160 offset:22528
	ds_read_b128 v[214:217], v160 offset:23552
	global_load_lds_dwordx4 v0, s[28:29]
	s_add_i32 m0, s33, 0x2000
	s_add_u32 s100, s30, 0x80
	s_addc_u32 s101, s31, 0
	s_add_u32 s58, s28, 0x80000
	s_addc_u32 s59, s29, 0
	s_add_i32 s33, s57, s40
	global_load_lds_dwordx4 v14, s[28:29]
	s_mov_b32 m0, s33
	s_nop 0
	global_load_lds_dwordx4 v0, s[58:59]
	s_add_i32 m0, s33, 0x2000
	s_nop 0
	global_load_lds_dwordx4 v14, s[58:59]
	s_mov_b32 m0, s42
	s_nop 0
	global_load_lds_dwordx4 v136, s[30:31]
	s_mov_b32 m0, s43
	s_nop 0
	global_load_lds_dwordx4 v134, s[30:31]
	s_waitcnt vmcnt(8)
	s_waitcnt lgkmcnt(0)
	s_barrier
	s_setprio 1
	s_waitcnt lgkmcnt(0)
	v_mfma_f32_16x16x32_bf16 v[66:69], v[142:145], v[182:185], v[66:69]
	v_mfma_f32_16x16x32_bf16 v[66:69], v[146:149], v[186:189], v[66:69]
	v_mfma_f32_16x16x32_bf16 v[62:65], v[162:165], v[186:189], v[62:65]
	v_mfma_f32_16x16x32_bf16 v[62:65], v[150:153], v[182:185], v[62:65]
	v_mfma_f32_16x16x32_bf16 v[46:49], v[150:153], v[190:193], v[46:49]
	v_mfma_f32_16x16x32_bf16 v[46:49], v[162:165], v[194:197], v[46:49]
	v_mfma_f32_16x16x32_bf16 v[50:53], v[146:149], v[194:197], v[50:53]
	v_mfma_f32_16x16x32_bf16 v[50:53], v[142:145], v[190:193], v[50:53]
	v_mfma_f32_16x16x32_bf16 v[34:37], v[142:145], v[198:201], v[34:37]
	v_mfma_f32_16x16x32_bf16 v[34:37], v[146:149], v[206:209], v[34:37]
	v_mfma_f32_16x16x32_bf16 v[30:33], v[162:165], v[206:209], v[30:33]
	v_mfma_f32_16x16x32_bf16 v[30:33], v[150:153], v[198:201], v[30:33]
	v_mfma_f32_16x16x32_bf16 v[10:13], v[150:153], v[210:213], v[10:13]
	v_mfma_f32_16x16x32_bf16 v[10:13], v[162:165], v[214:217], v[10:13]
	v_mfma_f32_16x16x32_bf16 v[18:21], v[146:149], v[214:217], v[18:21]
	v_mfma_f32_16x16x32_bf16 v[18:21], v[142:145], v[210:213], v[18:21]
	s_setprio 0
	s_setprio 1
	v_mfma_f32_16x16x32_bf16 v[58:61], v[166:169], v[182:185], v[58:61]
	v_mfma_f32_16x16x32_bf16 v[58:61], v[170:173], v[186:189], v[58:61]
	v_mfma_f32_16x16x32_bf16 v[54:57], v[178:181], v[186:189], v[54:57]
	v_mfma_f32_16x16x32_bf16 v[54:57], v[174:177], v[182:185], v[54:57]
	v_mfma_f32_16x16x32_bf16 v[38:41], v[174:177], v[190:193], v[38:41]
	v_mfma_f32_16x16x32_bf16 v[38:41], v[178:181], v[194:197], v[38:41]
	v_mfma_f32_16x16x32_bf16 v[42:45], v[170:173], v[194:197], v[42:45]
	v_mfma_f32_16x16x32_bf16 v[42:45], v[166:169], v[190:193], v[42:45]
	v_mfma_f32_16x16x32_bf16 v[26:29], v[166:169], v[198:201], v[26:29]
	v_mfma_f32_16x16x32_bf16 v[26:29], v[170:173], v[206:209], v[26:29]
	v_mfma_f32_16x16x32_bf16 v[22:25], v[178:181], v[206:209], v[22:25]
	v_mfma_f32_16x16x32_bf16 v[22:25], v[174:177], v[198:201], v[22:25]
	v_mfma_f32_16x16x32_bf16 v[2:5], v[174:177], v[210:213], v[2:5]
	v_mfma_f32_16x16x32_bf16 v[2:5], v[178:181], v[214:217], v[2:5]
	v_mfma_f32_16x16x32_bf16 v[6:9], v[170:173], v[214:217], v[6:9]
	v_mfma_f32_16x16x32_bf16 v[6:9], v[166:169], v[210:213], v[6:9]
	s_setprio 0
	s_barrier
; #define PG8_STAGE(bufoff, gbase, voff) do { _Pragma("unroll") for (int _i = 0; _i < 2; ++_i) \
;         __builtin_amdgcn_global_load_lds((const unsigned*)((const char*)(gbase) + (voff)[_i]), (PG8_LAS unsigned*)(lds + (bufoff) + ldsw + _i * 8192), 16, 0, 0); } while (0)
; #define PG8_LDA(dst, b, h) do { _Pragma("unroll") for (int m = 0; m < 4; ++m) _Pragma("unroll") for (int k = 0; k < 2; ++k) dst[m][k] = *(const PG8_LAS bf16x8*)(lds + PG8_SA(b, h) + aoff + m * 2048 + k * 1024); } while (0)
; #define PG8_LDB(dst, b, h) do { _Pragma("unroll") for (int n = 0; n < 2; ++n) _Pragma("unroll") for (int k = 0; k < 2; ++k) dst[n][k] = *(const PG8_LAS bf16x8*)(lds + PG8_SB(b, h) + boff + n * 2048 + k * 1024); } while (0)
; #define PG8_MMA(ai, bj, At, Bt) do { __builtin_amdgcn_s_setprio(1); _Pragma("unroll") for (int m = 0; m < 4; ++m) _Pragma("unroll") for (int n = 0; n < 2; ++n) _Pragma("unroll") for (int k = 0; k < 2; ++k) \
;         acc[ai][bj][m][n] = __builtin_amdgcn_mfma_f32_16x16x32_bf16(Bt[n][k], At[m][k], acc[ai][bj][m][n], 0, 0, 0); __builtin_amdgcn_s_setprio(0); } while (0)
; #define PG8_WAIT_V(n) asm volatile("s_waitcnt vmcnt(" #n ")" ::: "memory")
; #define PG8_WAIT_L(n) asm volatile("s_waitcnt lgkmcnt(" #n ")" ::: "memory")
; #define PG8_BAR __builtin_amdgcn_s_barrier()
; #define PG8_SCHED __builtin_amdgcn_sched_barrier(0)
; template <class Epi, class Sched, bool ALIGN_EPI = false, bool SP2 = false>
; __device__ __forceinline__ void gemm_phase(PG8_LAS unsigned char* lds, const Gemm g, const Sched& S, const Epi& E) {
;     ...
;             PG8_LDB(B0, 1, 0); PG8_LDB(B1, 1, 1); PG8_SCHED; PG8_LDA(At, 1, 0); PG8_STAGE(PG8_SA(0, 1), a2 + hstep, voffA);
;             PG8_WAIT_V(8); PG8_WAIT_L(0); PG8_BAR; PG8_MMA(0, 0, At, B0); PG8_MMA(0, 1, At, B1); PG8_BAR; PG8_SCHED;
;             PG8_LDA(At, 1, 1); PG8_STAGE(PG8_SB(1, 0), b3, voffB); PG8_STAGE(PG8_SB(1, 1), b3 + hstep, voffB); PG8_STAGE(PG8_SA(1, 0), a3, voffA);
;             PG8_WAIT_V(8); PG8_WAIT_L(0); PG8_BAR; PG8_MMA(1, 0, At, B0); PG8_MMA(1, 1, At, B1); PG8_BAR; PG8_SCHED;
	s_add_i32 s33, 0, 0x18000
	v_add_u32_e32 v161, s33, v155
	s_add_i32 s57, 0, 0x1c000
	ds_read_b128 v[142:145], v161
	ds_read_b128 v[146:149], v161 offset:1024
	ds_read_b128 v[150:153], v161 offset:2048
	ds_read_b128 v[162:165], v161 offset:3072
	v_add_u32_e32 v161, s57, v155
	ds_read_b128 v[166:169], v161
	ds_read_b128 v[170:173], v161 offset:1024
	ds_read_b128 v[174:177], v161 offset:2048
	ds_read_b128 v[178:181], v161 offset:3072
	s_add_u32 s30, s30, 0x80000
	s_addc_u32 s31, s31, 0
	s_mov_b32 m0, s44
	ds_read_b128 v[182:185], v160 offset:32768
	ds_read_b128 v[186:189], v160 offset:33792
	ds_read_b128 v[190:193], v160 offset:34816
	ds_read_b128 v[194:197], v160 offset:35840
	ds_read_b128 v[198:201], v160 offset:36864
	ds_read_b128 v[206:209], v160 offset:37888
	ds_read_b128 v[210:213], v160 offset:38912
	ds_read_b128 v[214:217], v160 offset:39936
	global_load_lds_dwordx4 v136, s[30:31]
	s_mov_b32 m0, s45
	s_nop 0
	global_load_lds_dwordx4 v134, s[30:31]
	s_waitcnt vmcnt(8)
	s_waitcnt lgkmcnt(0)
	s_barrier
	s_setprio 1
	s_waitcnt lgkmcnt(0)
	v_mfma_f32_16x16x32_bf16 v[130:133], v[142:145], v[182:185], v[130:133]
	v_mfma_f32_16x16x32_bf16 v[130:133], v[146:149], v[186:189], v[130:133]
	v_mfma_f32_16x16x32_bf16 v[126:129], v[162:165], v[186:189], v[126:129]
	v_mfma_f32_16x16x32_bf16 v[126:129], v[150:153], v[182:185], v[126:129]
	v_mfma_f32_16x16x32_bf16 v[110:113], v[150:153], v[190:193], v[110:113]
	v_mfma_f32_16x16x32_bf16 v[110:113], v[162:165], v[194:197], v[110:113]
	v_mfma_f32_16x16x32_bf16 v[114:117], v[146:149], v[194:197], v[114:117]
	v_mfma_f32_16x16x32_bf16 v[114:117], v[142:145], v[190:193], v[114:117]
	v_mfma_f32_16x16x32_bf16 v[98:101], v[142:145], v[198:201], v[98:101]
	v_mfma_f32_16x16x32_bf16 v[98:101], v[146:149], v[206:209], v[98:101]
	v_mfma_f32_16x16x32_bf16 v[94:97], v[162:165], v[206:209], v[94:97]
	v_mfma_f32_16x16x32_bf16 v[94:97], v[150:153], v[198:201], v[94:97]
	v_mfma_f32_16x16x32_bf16 v[78:81], v[150:153], v[210:213], v[78:81]
	v_mfma_f32_16x16x32_bf16 v[78:81], v[162:165], v[214:217], v[78:81]
	v_mfma_f32_16x16x32_bf16 v[82:85], v[146:149], v[214:217], v[82:85]
	v_mfma_f32_16x16x32_bf16 v[82:85], v[142:145], v[210:213], v[82:85]
	s_setprio 0
	s_setprio 1
	v_mfma_f32_16x16x32_bf16 v[122:125], v[166:169], v[182:185], v[122:125]
	v_mfma_f32_16x16x32_bf16 v[122:125], v[170:173], v[186:189], v[122:125]
	v_mfma_f32_16x16x32_bf16 v[118:121], v[178:181], v[186:189], v[118:121]
	v_mfma_f32_16x16x32_bf16 v[118:121], v[174:177], v[182:185], v[118:121]
	v_mfma_f32_16x16x32_bf16 v[102:105], v[174:177], v[190:193], v[102:105]
	v_mfma_f32_16x16x32_bf16 v[102:105], v[178:181], v[194:197], v[102:105]
	v_mfma_f32_16x16x32_bf16 v[106:109], v[170:173], v[194:197], v[106:109]
	v_mfma_f32_16x16x32_bf16 v[106:109], v[166:169], v[190:193], v[106:109]
	v_mfma_f32_16x16x32_bf16 v[90:93], v[166:169], v[198:201], v[90:93]
	v_mfma_f32_16x16x32_bf16 v[90:93], v[170:173], v[206:209], v[90:93]
	v_mfma_f32_16x16x32_bf16 v[86:89], v[178:181], v[206:209], v[86:89]
	v_mfma_f32_16x16x32_bf16 v[86:89], v[174:177], v[198:201], v[86:89]
	v_mfma_f32_16x16x32_bf16 v[70:73], v[174:177], v[210:213], v[70:73]
	v_mfma_f32_16x16x32_bf16 v[70:73], v[178:181], v[214:217], v[70:73]
	v_mfma_f32_16x16x32_bf16 v[74:77], v[170:173], v[214:217], v[74:77]
	v_mfma_f32_16x16x32_bf16 v[74:77], v[166:169], v[210:213], v[74:77]
	s_setprio 0
	s_barrier
	s_add_i32 s30, s33, s40
	s_add_i32 m0, s30, 0xffffff80
	ds_read_b128 v[182:185], v160 offset:49152
	ds_read_b128 v[186:189], v160 offset:50176
	ds_read_b128 v[190:193], v160 offset:51200
	ds_read_b128 v[194:197], v160 offset:52224
	ds_read_b128 v[198:201], v160 offset:53248
	ds_read_b128 v[206:209], v160 offset:54272
	ds_read_b128 v[210:213], v160 offset:55296
	ds_read_b128 v[214:217], v160 offset:56320
	global_load_lds_dwordx4 v0, s[28:29] offset:128
	s_add_i32 m0, s30, 0x1f80
	s_add_i32 s30, s57, s40
	global_load_lds_dwordx4 v14, s[28:29] offset:128
	s_add_u32 s28, s28, 0x80080
	s_addc_u32 s29, s29, 0
	s_mov_b32 m0, s30
	s_nop 0
	global_load_lds_dwordx4 v0, s[28:29]
	s_add_i32 m0, s30, 0x2000
	s_nop 0
	global_load_lds_dwordx4 v14, s[28:29]
	s_mov_b32 m0, s47
	s_nop 0
	global_load_lds_dwordx4 v136, s[100:101]
	s_mov_b32 m0, s48
	s_nop 0
	global_load_lds_dwordx4 v134, s[100:101]
	s_waitcnt vmcnt(8)
	s_waitcnt lgkmcnt(0)
	s_barrier
	s_setprio 1
	s_waitcnt lgkmcnt(0)
	v_mfma_f32_16x16x32_bf16 v[66:69], v[142:145], v[182:185], v[66:69]
	v_mfma_f32_16x16x32_bf16 v[66:69], v[146:149], v[186:189], v[66:69]
	v_mfma_f32_16x16x32_bf16 v[62:65], v[162:165], v[186:189], v[62:65]
	v_mfma_f32_16x16x32_bf16 v[62:65], v[150:153], v[182:185], v[62:65]
	v_mfma_f32_16x16x32_bf16 v[46:49], v[150:153], v[190:193], v[46:49]
	v_mfma_f32_16x16x32_bf16 v[46:49], v[162:165], v[194:197], v[46:49]
	v_mfma_f32_16x16x32_bf16 v[50:53], v[146:149], v[194:197], v[50:53]
	v_mfma_f32_16x16x32_bf16 v[50:53], v[142:145], v[190:193], v[50:53]
	v_mfma_f32_16x16x32_bf16 v[34:37], v[142:145], v[198:201], v[34:37]
	v_mfma_f32_16x16x32_bf16 v[34:37], v[146:149], v[206:209], v[34:37]
	v_mfma_f32_16x16x32_bf16 v[30:33], v[162:165], v[206:209], v[30:33]
	v_mfma_f32_16x16x32_bf16 v[30:33], v[150:153], v[198:201], v[30:33]
	v_mfma_f32_16x16x32_bf16 v[10:13], v[150:153], v[210:213], v[10:13]
	v_mfma_f32_16x16x32_bf16 v[10:13], v[162:165], v[214:217], v[10:13]
	v_mfma_f32_16x16x32_bf16 v[18:21], v[146:149], v[214:217], v[18:21]
	v_mfma_f32_16x16x32_bf16 v[18:21], v[142:145], v[210:213], v[18:21]
	s_setprio 0
	s_setprio 1
	v_mfma_f32_16x16x32_bf16 v[58:61], v[166:169], v[182:185], v[58:61]
	v_mfma_f32_16x16x32_bf16 v[58:61], v[170:173], v[186:189], v[58:61]
	v_mfma_f32_16x16x32_bf16 v[54:57], v[178:181], v[186:189], v[54:57]
	v_mfma_f32_16x16x32_bf16 v[54:57], v[174:177], v[182:185], v[54:57]
	v_mfma_f32_16x16x32_bf16 v[38:41], v[174:177], v[190:193], v[38:41]
	v_mfma_f32_16x16x32_bf16 v[38:41], v[178:181], v[194:197], v[38:41]
	v_mfma_f32_16x16x32_bf16 v[42:45], v[170:173], v[194:197], v[42:45]
	v_mfma_f32_16x16x32_bf16 v[42:45], v[166:169], v[190:193], v[42:45]
	v_mfma_f32_16x16x32_bf16 v[26:29], v[166:169], v[198:201], v[26:29]
	v_mfma_f32_16x16x32_bf16 v[26:29], v[170:173], v[206:209], v[26:29]
	v_mfma_f32_16x16x32_bf16 v[22:25], v[178:181], v[206:209], v[22:25]
	v_mfma_f32_16x16x32_bf16 v[22:25], v[174:177], v[198:201], v[22:25]
	v_mfma_f32_16x16x32_bf16 v[2:5], v[174:177], v[210:213], v[2:5]
	v_mfma_f32_16x16x32_bf16 v[2:5], v[178:181], v[214:217], v[2:5]
	v_mfma_f32_16x16x32_bf16 v[6:9], v[170:173], v[214:217], v[6:9]
	v_mfma_f32_16x16x32_bf16 v[6:9], v[166:169], v[210:213], v[6:9]
	s_setprio 0
	s_barrier
	s_add_i32 s56, s56, 2
	s_add_u32 s54, s54, 0x100
	s_addc_u32 s55, s55, 0
	s_add_u32 s26, s26, 0x100
	s_addc_u32 s27, s27, 0
	s_cmp_gt_u32 s56, 29
	s_cbranch_scc0 .LBB0_1223
	s_and_b64 vcc, exec, s[14:15]
	s_cbranch_vccz .LBB0_1226
	s_barrier

; #define PG8_STAGE(bufoff, gbase, voff) do { _Pragma("unroll") for (int _i = 0; _i < 2; ++_i) \
;         __builtin_amdgcn_global_load_lds((const unsigned*)((const char*)(gbase) + (voff)[_i]), (PG8_LAS unsigned*)(lds + (bufoff) + ldsw + _i * 8192), 16, 0, 0); } while (0)
; #define PG8_LDA(dst, b, h) do { _Pragma("unroll") for (int m = 0; m < 4; ++m) _Pragma("unroll") for (int k = 0; k < 2; ++k) dst[m][k] = *(const PG8_LAS bf16x8*)(lds + PG8_SA(b, h) + aoff + m * 2048 + k * 1024); } while (0)
; #define PG8_LDB(dst, b, h) do { _Pragma("unroll") for (int n = 0; n < 2; ++n) _Pragma("unroll") for (int k = 0; k < 2; ++k) dst[n][k] = *(const PG8_LAS bf16x8*)(lds + PG8_SB(b, h) + boff + n * 2048 + k * 1024); } while (0)
; #define PG8_WAIT_V(n) asm volatile("s_waitcnt vmcnt(" #n ")" ::: "memory")
; #define PG8_WAIT_L(n) asm volatile("s_waitcnt lgkmcnt(" #n ")" ::: "memory")
; #define PG8_BAR __builtin_amdgcn_s_barrier()
; #define PG8_SCHED __builtin_amdgcn_sched_barrier(0)
; template <class Epi, class Sched, bool ALIGN_EPI = false, bool SP2 = false>
; __device__ __forceinline__ void gemm_phase(PG8_LAS unsigned char* lds, const Gemm g, const Sched& S, const Epi& E) {
;     ...
;         const char* nA = has_next ? (const char*)g.A + (size_t)nxt.pm * tstep : cA; const char* nB = has_next ? (const char*)g.Bt + (size_t)nxt.pn * tstep : cB;
;         for (int t = 0; t < nt; t += 2) {
;             const bool last = (t == nt - 2);
;             const char* a1 = cA + (size_t)(t + 1) * kstep;
;             const char* a2 = last ? nA : cA + (size_t)(t + 2) * kstep; const char* b2 = last ? nB : cB + (size_t)(t + 2) * kstep;
;             const char* a3 = a2 + kstep; const char* b3 = b2 + kstep;
;             if (last && has_next) S.a_ready(nxt);
;             if constexpr (Epi::MID) { if (t == nt / 2) E.mid(acc, cur, wr, wc, fr, fq); }
;             if constexpr (SP2) {
;             PG8_LDB(B0, 0, 0); PG8_LDB(B1, 0, 1); PG8_SCHED; PG8_LDA(At, 0, 0); PG8_STAGE(PG8_SA(1, 1), a1 + hstep, voffA);
;             PG8_WAIT_V(8); PG8_WAIT_L(0); PG8_BAR; PG8_MMA(0, 0, At, B0); PG8_MMA(0, 1, At, B1); PG8_BAR; PG8_SCHED;
;             PG8_LDA(At, 0, 1); PG8_STAGE(PG8_SB(0, 0), b2, voffB); PG8_STAGE(PG8_SB(0, 1), b2 + hstep, voffB); PG8_STAGE(PG8_SA(0, 0), a2, voffA);
;             PG8_WAIT_V(8); PG8_WAIT_L(0); PG8_BAR; PG8_MMA(1, 0, At, B0); PG8_MMA(1, 1, At, B1); PG8_BAR; PG8_SCHED;
.LBB0_1328:
	s_add_u32 s51, s26, 0x100
	s_addc_u32 s52, s27, 0
	s_mov_b32 s53, -2
	s_add_u32 s4, s24, 0x100
	s_addc_u32 s5, s25, 0
	s_add_i32 s33, 0, 0x10000
	s_cmpk_eq_i32 s53, 0x54
	s_cselect_b32 s29, s21, s5
	s_cselect_b32 s28, s20, s4
	s_cselect_b32 s27, s23, s52
	s_cselect_b32 s26, s22, s51
	s_add_i32 s54, 0, 0x14000
	v_add_u32_e32 v98, s33, v199
	v_add_u32_e32 v146, s54, v199
	ds_read_b128 v[70:73], v98
	ds_read_b128 v[74:77], v98 offset:1024
	ds_read_b128 v[86:89], v98 offset:2048
	ds_read_b128 v[98:101], v98 offset:3072
	ds_read_b128 v[110:113], v146
	ds_read_b128 v[122:125], v146 offset:1024
	ds_read_b128 v[134:137], v146 offset:2048
	ds_read_b128 v[146:149], v146 offset:3072
	s_add_i32 m0, s39, 0xc000
	ds_read_b128 v[158:161], v201
	ds_read_b128 v[162:165], v201 offset:1024
	ds_read_b128 v[174:177], v201 offset:2048
	ds_read_b128 v[178:181], v201 offset:3072
	ds_read_b128 v[182:185], v201 offset:4096
	ds_read_b128 v[186:189], v201 offset:5120
	ds_read_b128 v[190:193], v201 offset:6144
	ds_read_b128 v[210:213], v201 offset:7168
	global_load_lds_dwordx4 v208, s[24:25]
	s_add_i32 m0, s39, 0xe000
	s_nop 0
	global_load_lds_dwordx4 v206, s[24:25]
	s_waitcnt vmcnt(8)
	s_waitcnt lgkmcnt(0)
	s_barrier
	s_setprio 1
	s_waitcnt lgkmcnt(0)
	v_mfma_f32_16x16x32_bf16 v[170:173], v[70:73], v[158:161], 0
	v_mfma_f32_16x16x32_bf16 v[170:173], v[74:77], v[162:165], v[170:173]
	v_mfma_f32_16x16x32_bf16 v[166:169], v[98:101], v[162:165], 0
	v_mfma_f32_16x16x32_bf16 v[166:169], v[86:89], v[158:161], v[166:169]
	v_mfma_f32_16x16x32_bf16 v[138:141], v[86:89], v[174:177], 0
	v_mfma_f32_16x16x32_bf16 v[138:141], v[98:101], v[178:181], v[138:141]
	v_mfma_f32_16x16x32_bf16 v[142:145], v[74:77], v[178:181], 0
	v_mfma_f32_16x16x32_bf16 v[142:145], v[70:73], v[174:177], v[142:145]
	v_mfma_f32_16x16x32_bf16 v[118:121], v[70:73], v[182:185], 0
	v_mfma_f32_16x16x32_bf16 v[118:121], v[74:77], v[186:189], v[118:121]
	v_mfma_f32_16x16x32_bf16 v[114:117], v[98:101], v[186:189], 0
	v_mfma_f32_16x16x32_bf16 v[114:117], v[86:89], v[182:185], v[114:117]
	v_mfma_f32_16x16x32_bf16 v[90:93], v[86:89], v[190:193], 0
	v_mfma_f32_16x16x32_bf16 v[90:93], v[98:101], v[210:213], v[90:93]
	v_mfma_f32_16x16x32_bf16 v[94:97], v[74:77], v[210:213], 0
	v_mfma_f32_16x16x32_bf16 v[94:97], v[70:73], v[190:193], v[94:97]
	s_setprio 0
	s_setprio 1
	v_mfma_f32_16x16x32_bf16 v[154:157], v[110:113], v[158:161], 0
	v_mfma_f32_16x16x32_bf16 v[154:157], v[122:125], v[162:165], v[154:157]
	v_mfma_f32_16x16x32_bf16 v[150:153], v[146:149], v[162:165], 0
	v_mfma_f32_16x16x32_bf16 v[150:153], v[134:137], v[158:161], v[150:153]
	v_mfma_f32_16x16x32_bf16 v[126:129], v[134:137], v[174:177], 0
	v_mfma_f32_16x16x32_bf16 v[126:129], v[146:149], v[178:181], v[126:129]
	v_mfma_f32_16x16x32_bf16 v[130:133], v[122:125], v[178:181], 0
	v_mfma_f32_16x16x32_bf16 v[130:133], v[110:113], v[174:177], v[130:133]
	v_mfma_f32_16x16x32_bf16 v[106:109], v[110:113], v[182:185], 0
	v_mfma_f32_16x16x32_bf16 v[106:109], v[122:125], v[186:189], v[106:109]
	v_mfma_f32_16x16x32_bf16 v[102:105], v[146:149], v[186:189], 0
	v_mfma_f32_16x16x32_bf16 v[102:105], v[134:137], v[182:185], v[102:105]
	v_mfma_f32_16x16x32_bf16 v[78:81], v[134:137], v[190:193], 0
	v_mfma_f32_16x16x32_bf16 v[78:81], v[146:149], v[210:213], v[78:81]
	v_mfma_f32_16x16x32_bf16 v[82:85], v[122:125], v[210:213], 0
	v_mfma_f32_16x16x32_bf16 v[82:85], v[110:113], v[190:193], v[82:85]
	s_setprio 0
	s_barrier
	s_add_i32 s24, s33, s38
	s_mov_b32 m0, s24
	ds_read_b128 v[158:161], v201 offset:16384
	ds_read_b128 v[162:165], v201 offset:17408
	ds_read_b128 v[174:177], v201 offset:18432
	ds_read_b128 v[178:181], v201 offset:19456
	ds_read_b128 v[182:185], v201 offset:20480
	ds_read_b128 v[186:189], v201 offset:21504
	ds_read_b128 v[190:193], v201 offset:22528
	ds_read_b128 v[210:213], v201 offset:23552
	global_load_lds_dwordx4 v0, s[26:27]
	s_add_i32 m0, s24, 0x2000
	s_add_u32 s100, s28, 0x80
	s_addc_u32 s101, s29, 0
	s_add_u32 s24, s26, 0x160000
	s_addc_u32 s25, s27, 0
	s_add_i32 s33, s54, s38
	global_load_lds_dwordx4 v196, s[26:27]
	s_mov_b32 m0, s33
	s_nop 0
	global_load_lds_dwordx4 v0, s[24:25]
	s_add_i32 m0, s33, 0x2000
	s_nop 0
	global_load_lds_dwordx4 v196, s[24:25]
	s_mov_b32 m0, s39
	s_nop 0
	global_load_lds_dwordx4 v14, s[28:29]
	s_mov_b32 m0, s40
	s_nop 0
	global_load_lds_dwordx4 v194, s[28:29]
	s_waitcnt vmcnt(8)
	s_waitcnt lgkmcnt(0)
	s_barrier
	s_setprio 1
	s_waitcnt lgkmcnt(0)
	v_mfma_f32_16x16x32_bf16 v[66:69], v[70:73], v[158:161], 0
	v_mfma_f32_16x16x32_bf16 v[66:69], v[74:77], v[162:165], v[66:69]
	v_mfma_f32_16x16x32_bf16 v[62:65], v[98:101], v[162:165], 0
	v_mfma_f32_16x16x32_bf16 v[62:65], v[86:89], v[158:161], v[62:65]
	v_mfma_f32_16x16x32_bf16 v[46:49], v[86:89], v[174:177], 0
	v_mfma_f32_16x16x32_bf16 v[46:49], v[98:101], v[178:181], v[46:49]
	v_mfma_f32_16x16x32_bf16 v[50:53], v[74:77], v[178:181], 0
	v_mfma_f32_16x16x32_bf16 v[50:53], v[70:73], v[174:177], v[50:53]
	v_mfma_f32_16x16x32_bf16 v[34:37], v[70:73], v[182:185], 0
	v_mfma_f32_16x16x32_bf16 v[34:37], v[74:77], v[186:189], v[34:37]
	v_mfma_f32_16x16x32_bf16 v[30:33], v[98:101], v[186:189], 0
	v_mfma_f32_16x16x32_bf16 v[30:33], v[86:89], v[182:185], v[30:33]
	v_mfma_f32_16x16x32_bf16 v[10:13], v[86:89], v[190:193], 0
	v_mfma_f32_16x16x32_bf16 v[10:13], v[98:101], v[210:213], v[10:13]
	v_mfma_f32_16x16x32_bf16 v[18:21], v[74:77], v[210:213], 0
	v_mfma_f32_16x16x32_bf16 v[18:21], v[70:73], v[190:193], v[18:21]
	s_setprio 0
	s_setprio 1
	v_mfma_f32_16x16x32_bf16 v[58:61], v[110:113], v[158:161], 0
	v_mfma_f32_16x16x32_bf16 v[58:61], v[122:125], v[162:165], v[58:61]
	v_mfma_f32_16x16x32_bf16 v[54:57], v[146:149], v[162:165], 0
	v_mfma_f32_16x16x32_bf16 v[54:57], v[134:137], v[158:161], v[54:57]
	v_mfma_f32_16x16x32_bf16 v[38:41], v[134:137], v[174:177], 0
	v_mfma_f32_16x16x32_bf16 v[38:41], v[146:149], v[178:181], v[38:41]
	v_mfma_f32_16x16x32_bf16 v[42:45], v[122:125], v[178:181], 0
	v_mfma_f32_16x16x32_bf16 v[42:45], v[110:113], v[174:177], v[42:45]
	v_mfma_f32_16x16x32_bf16 v[26:29], v[110:113], v[182:185], 0
	v_mfma_f32_16x16x32_bf16 v[26:29], v[122:125], v[186:189], v[26:29]
	v_mfma_f32_16x16x32_bf16 v[22:25], v[146:149], v[186:189], 0
	v_mfma_f32_16x16x32_bf16 v[22:25], v[134:137], v[182:185], v[22:25]
	v_mfma_f32_16x16x32_bf16 v[2:5], v[134:137], v[190:193], 0
	v_mfma_f32_16x16x32_bf16 v[2:5], v[146:149], v[210:213], v[2:5]
	v_mfma_f32_16x16x32_bf16 v[6:9], v[122:125], v[210:213], 0
	v_mfma_f32_16x16x32_bf16 v[6:9], v[110:113], v[190:193], v[6:9]
	s_setprio 0
	s_barrier
; #define PG8_STAGE(bufoff, gbase, voff) do { _Pragma("unroll") for (int _i = 0; _i < 2; ++_i) \
;         __builtin_amdgcn_global_load_lds((const unsigned*)((const char*)(gbase) + (voff)[_i]), (PG8_LAS unsigned*)(lds + (bufoff) + ldsw + _i * 8192), 16, 0, 0); } while (0)
; #define PG8_LDA(dst, b, h) do { _Pragma("unroll") for (int m = 0; m < 4; ++m) _Pragma("unroll") for (int k = 0; k < 2; ++k) dst[m][k] = *(const PG8_LAS bf16x8*)(lds + PG8_SA(b, h) + aoff + m * 2048 + k * 1024); } while (0)
; #define PG8_LDB(dst, b, h) do { _Pragma("unroll") for (int n = 0; n < 2; ++n) _Pragma("unroll") for (int k = 0; k < 2; ++k) dst[n][k] = *(const PG8_LAS bf16x8*)(lds + PG8_SB(b, h) + boff + n * 2048 + k * 1024); } while (0)
; #define PG8_MMA(ai, bj, At, Bt) do { __builtin_amdgcn_s_setprio(1); _Pragma("unroll") for (int m = 0; m < 4; ++m) _Pragma("unroll") for (int n = 0; n < 2; ++n) _Pragma("unroll") for (int k = 0; k < 2; ++k) \
;         acc[ai][bj][m][n] = __builtin_amdgcn_mfma_f32_16x16x32_bf16(Bt[n][k], At[m][k], acc[ai][bj][m][n], 0, 0, 0); __builtin_amdgcn_s_setprio(0); } while (0)
; #define PG8_WAIT_V(n) asm volatile("s_waitcnt vmcnt(" #n ")" ::: "memory")
; #define PG8_WAIT_L(n) asm volatile("s_waitcnt lgkmcnt(" #n ")" ::: "memory")
; #define PG8_BAR __builtin_amdgcn_s_barrier()
; #define PG8_SCHED __builtin_amdgcn_sched_barrier(0)
; template <class Epi, class Sched, bool ALIGN_EPI = false, bool SP2 = false>
; __device__ __forceinline__ void gemm_phase(PG8_LAS unsigned char* lds, const Gemm g, const Sched& S, const Epi& E) {
;     ...
;             PG8_LDB(B0, 1, 0); PG8_LDB(B1, 1, 1); PG8_SCHED; PG8_LDA(At, 1, 0); PG8_STAGE(PG8_SA(0, 1), a2 + hstep, voffA);
;             PG8_WAIT_V(8); PG8_WAIT_L(0); PG8_BAR; PG8_MMA(0, 0, At, B0); PG8_MMA(0, 1, At, B1); PG8_BAR; PG8_SCHED;
;             PG8_LDA(At, 1, 1); PG8_STAGE(PG8_SB(1, 0), b3, voffB); PG8_STAGE(PG8_SB(1, 1), b3 + hstep, voffB); PG8_STAGE(PG8_SA(1, 0), a3, voffA);
;             PG8_WAIT_V(8); PG8_WAIT_L(0); PG8_BAR; PG8_MMA(1, 0, At, B0); PG8_MMA(1, 1, At, B1); PG8_BAR; PG8_SCHED;
	s_add_i32 s33, 0, 0x18000
	s_add_i32 s54, 0, 0x1c000
	v_add_u32_e32 v98, s33, v199
	v_add_u32_e32 v146, s54, v199
	ds_read_b128 v[70:73], v98
	ds_read_b128 v[74:77], v98 offset:1024
	ds_read_b128 v[86:89], v98 offset:2048
	ds_read_b128 v[98:101], v98 offset:3072
	ds_read_b128 v[110:113], v146
	ds_read_b128 v[122:125], v146 offset:1024
	ds_read_b128 v[134:137], v146 offset:2048
	ds_read_b128 v[146:149], v146 offset:3072
	s_add_u32 s24, s28, 0x160000
	s_addc_u32 s25, s29, 0
	s_mov_b32 m0, s41
	ds_read_b128 v[158:161], v201 offset:32768
	ds_read_b128 v[162:165], v201 offset:33792
	ds_read_b128 v[174:177], v201 offset:34816
	ds_read_b128 v[178:181], v201 offset:35840
	ds_read_b128 v[182:185], v201 offset:36864
	ds_read_b128 v[186:189], v201 offset:37888
	ds_read_b128 v[190:193], v201 offset:38912
	ds_read_b128 v[210:213], v201 offset:39936
	global_load_lds_dwordx4 v14, s[24:25]
	s_mov_b32 m0, s42
	s_nop 0
	global_load_lds_dwordx4 v194, s[24:25]
	s_waitcnt vmcnt(8)
	s_waitcnt lgkmcnt(0)
	s_barrier
	s_setprio 1
	s_waitcnt lgkmcnt(0)
	v_mfma_f32_16x16x32_bf16 v[170:173], v[70:73], v[158:161], v[170:173]
	v_mfma_f32_16x16x32_bf16 v[170:173], v[74:77], v[162:165], v[170:173]
	v_mfma_f32_16x16x32_bf16 v[166:169], v[98:101], v[162:165], v[166:169]
	v_mfma_f32_16x16x32_bf16 v[166:169], v[86:89], v[158:161], v[166:169]
	v_mfma_f32_16x16x32_bf16 v[138:141], v[86:89], v[174:177], v[138:141]
	v_mfma_f32_16x16x32_bf16 v[138:141], v[98:101], v[178:181], v[138:141]
	v_mfma_f32_16x16x32_bf16 v[142:145], v[74:77], v[178:181], v[142:145]
	v_mfma_f32_16x16x32_bf16 v[142:145], v[70:73], v[174:177], v[142:145]
	v_mfma_f32_16x16x32_bf16 v[118:121], v[70:73], v[182:185], v[118:121]
	v_mfma_f32_16x16x32_bf16 v[118:121], v[74:77], v[186:189], v[118:121]
	v_mfma_f32_16x16x32_bf16 v[114:117], v[98:101], v[186:189], v[114:117]
	v_mfma_f32_16x16x32_bf16 v[114:117], v[86:89], v[182:185], v[114:117]
	v_mfma_f32_16x16x32_bf16 v[90:93], v[86:89], v[190:193], v[90:93]
	v_mfma_f32_16x16x32_bf16 v[90:93], v[98:101], v[210:213], v[90:93]
	v_mfma_f32_16x16x32_bf16 v[94:97], v[74:77], v[210:213], v[94:97]
	v_mfma_f32_16x16x32_bf16 v[94:97], v[70:73], v[190:193], v[94:97]
	s_setprio 0
	s_setprio 1
	v_mfma_f32_16x16x32_bf16 v[154:157], v[110:113], v[158:161], v[154:157]
	v_mfma_f32_16x16x32_bf16 v[154:157], v[122:125], v[162:165], v[154:157]
	v_mfma_f32_16x16x32_bf16 v[150:153], v[146:149], v[162:165], v[150:153]
	v_mfma_f32_16x16x32_bf16 v[150:153], v[134:137], v[158:161], v[150:153]
	v_mfma_f32_16x16x32_bf16 v[126:129], v[134:137], v[174:177], v[126:129]
	v_mfma_f32_16x16x32_bf16 v[126:129], v[146:149], v[178:181], v[126:129]
	v_mfma_f32_16x16x32_bf16 v[130:133], v[122:125], v[178:181], v[130:133]
	v_mfma_f32_16x16x32_bf16 v[130:133], v[110:113], v[174:177], v[130:133]
	v_mfma_f32_16x16x32_bf16 v[106:109], v[110:113], v[182:185], v[106:109]
	v_mfma_f32_16x16x32_bf16 v[106:109], v[122:125], v[186:189], v[106:109]
	v_mfma_f32_16x16x32_bf16 v[102:105], v[146:149], v[186:189], v[102:105]
	v_mfma_f32_16x16x32_bf16 v[102:105], v[134:137], v[182:185], v[102:105]
	v_mfma_f32_16x16x32_bf16 v[78:81], v[134:137], v[190:193], v[78:81]
	v_mfma_f32_16x16x32_bf16 v[78:81], v[146:149], v[210:213], v[78:81]
	v_mfma_f32_16x16x32_bf16 v[82:85], v[122:125], v[210:213], v[82:85]
	v_mfma_f32_16x16x32_bf16 v[82:85], v[110:113], v[190:193], v[82:85]
	s_setprio 0
	s_barrier
	s_add_i32 s24, s33, s38
	s_add_i32 m0, s24, 0xffffff80
	ds_read_b128 v[158:161], v201 offset:49152
	ds_read_b128 v[162:165], v201 offset:50176
	ds_read_b128 v[174:177], v201 offset:51200
	ds_read_b128 v[178:181], v201 offset:52224
	ds_read_b128 v[182:185], v201 offset:53248
	ds_read_b128 v[186:189], v201 offset:54272
	ds_read_b128 v[190:193], v201 offset:55296
	ds_read_b128 v[210:213], v201 offset:56320
	global_load_lds_dwordx4 v0, s[26:27] offset:128
	s_add_i32 m0, s24, 0x1f80
	s_add_u32 s24, s26, 0x160080
	s_addc_u32 s25, s27, 0
	global_load_lds_dwordx4 v196, s[26:27] offset:128
	s_add_i32 s26, s54, s38
	s_mov_b32 m0, s26
	s_nop 0
	global_load_lds_dwordx4 v0, s[24:25]
	s_add_i32 m0, s26, 0x2000
	s_nop 0
	global_load_lds_dwordx4 v196, s[24:25]
	s_mov_b32 m0, s44
	s_nop 0
	global_load_lds_dwordx4 v14, s[100:101]
	s_mov_b32 m0, s45
	s_nop 0
	global_load_lds_dwordx4 v194, s[100:101]
	s_waitcnt vmcnt(8)
	s_waitcnt lgkmcnt(0)
	s_barrier
	s_setprio 1
	s_waitcnt lgkmcnt(0)
	v_mfma_f32_16x16x32_bf16 v[66:69], v[70:73], v[158:161], v[66:69]
	v_mfma_f32_16x16x32_bf16 v[66:69], v[74:77], v[162:165], v[66:69]
	v_mfma_f32_16x16x32_bf16 v[62:65], v[98:101], v[162:165], v[62:65]
	v_mfma_f32_16x16x32_bf16 v[62:65], v[86:89], v[158:161], v[62:65]
	v_mfma_f32_16x16x32_bf16 v[46:49], v[86:89], v[174:177], v[46:49]
	v_mfma_f32_16x16x32_bf16 v[46:49], v[98:101], v[178:181], v[46:49]
	v_mfma_f32_16x16x32_bf16 v[50:53], v[74:77], v[178:181], v[50:53]
	v_mfma_f32_16x16x32_bf16 v[50:53], v[70:73], v[174:177], v[50:53]
	v_mfma_f32_16x16x32_bf16 v[34:37], v[70:73], v[182:185], v[34:37]
	v_mfma_f32_16x16x32_bf16 v[34:37], v[74:77], v[186:189], v[34:37]
	v_mfma_f32_16x16x32_bf16 v[30:33], v[98:101], v[186:189], v[30:33]
	v_mfma_f32_16x16x32_bf16 v[30:33], v[86:89], v[182:185], v[30:33]
	v_mfma_f32_16x16x32_bf16 v[10:13], v[86:89], v[190:193], v[10:13]
	v_mfma_f32_16x16x32_bf16 v[10:13], v[98:101], v[210:213], v[10:13]
	v_mfma_f32_16x16x32_bf16 v[18:21], v[74:77], v[210:213], v[18:21]
	v_mfma_f32_16x16x32_bf16 v[18:21], v[70:73], v[190:193], v[18:21]
	s_setprio 0
	s_setprio 1
	v_mfma_f32_16x16x32_bf16 v[58:61], v[110:113], v[158:161], v[58:61]
	v_mfma_f32_16x16x32_bf16 v[58:61], v[122:125], v[162:165], v[58:61]
	v_mfma_f32_16x16x32_bf16 v[54:57], v[146:149], v[162:165], v[54:57]
	v_mfma_f32_16x16x32_bf16 v[54:57], v[134:137], v[158:161], v[54:57]
	v_mfma_f32_16x16x32_bf16 v[38:41], v[134:137], v[174:177], v[38:41]
	v_mfma_f32_16x16x32_bf16 v[38:41], v[146:149], v[178:181], v[38:41]
	v_mfma_f32_16x16x32_bf16 v[42:45], v[122:125], v[178:181], v[42:45]
	v_mfma_f32_16x16x32_bf16 v[42:45], v[110:113], v[174:177], v[42:45]
	v_mfma_f32_16x16x32_bf16 v[26:29], v[110:113], v[182:185], v[26:29]
	v_mfma_f32_16x16x32_bf16 v[26:29], v[122:125], v[186:189], v[26:29]
	v_mfma_f32_16x16x32_bf16 v[22:25], v[146:149], v[186:189], v[22:25]
	v_mfma_f32_16x16x32_bf16 v[22:25], v[134:137], v[182:185], v[22:25]
	v_mfma_f32_16x16x32_bf16 v[2:5], v[134:137], v[190:193], v[2:5]
	v_mfma_f32_16x16x32_bf16 v[2:5], v[146:149], v[210:213], v[2:5]
	v_mfma_f32_16x16x32_bf16 v[6:9], v[122:125], v[210:213], v[6:9]
	v_mfma_f32_16x16x32_bf16 v[6:9], v[110:113], v[190:193], v[6:9]
	s_setprio 0
	s_barrier
	s_add_i32 s53, s53, 2
	s_add_u32 s51, s51, 0x100
	s_addc_u32 s52, s52, 0
	s_cmpk_gt_u32 s53, 0x55
	s_mov_b64 s[24:25], s[4:5]
; #define PG8_STAGE(bufoff, gbase, voff) do { _Pragma("unroll") for (int _i = 0; _i < 2; ++_i) \
;         __builtin_amdgcn_global_load_lds((const unsigned*)((const char*)(gbase) + (voff)[_i]), (PG8_LAS unsigned*)(lds + (bufoff) + ldsw + _i * 8192), 16, 0, 0); } while (0)
; #define PG8_LDA(dst, b, h) do { _Pragma("unroll") for (int m = 0; m < 4; ++m) _Pragma("unroll") for (int k = 0; k < 2; ++k) dst[m][k] = *(const PG8_LAS bf16x8*)(lds + PG8_SA(b, h) + aoff + m * 2048 + k * 1024); } while (0)
; #define PG8_LDB(dst, b, h) do { _Pragma("unroll") for (int n = 0; n < 2; ++n) _Pragma("unroll") for (int k = 0; k < 2; ++k) dst[n][k] = *(const PG8_LAS bf16x8*)(lds + PG8_SB(b, h) + boff + n * 2048 + k * 1024); } while (0)
; #define PG8_MMA(ai, bj, At, Bt) do { __builtin_amdgcn_s_setprio(1); _Pragma("unroll") for (int m = 0; m < 4; ++m) _Pragma("unroll") for (int n = 0; n < 2; ++n) _Pragma("unroll") for (int k = 0; k < 2; ++k) \
;         acc[ai][bj][m][n] = __builtin_amdgcn_mfma_f32_16x16x32_bf16(Bt[n][k], At[m][k], acc[ai][bj][m][n], 0, 0, 0); __builtin_amdgcn_s_setprio(0); } while (0)
; #define PG8_WAIT_V(n) asm volatile("s_waitcnt vmcnt(" #n ")" ::: "memory")
; #define PG8_WAIT_L(n) asm volatile("s_waitcnt lgkmcnt(" #n ")" ::: "memory")
; #define PG8_BAR __builtin_amdgcn_s_barrier()
; #define PG8_SCHED __builtin_amdgcn_sched_barrier(0)
; template <class Epi, class Sched, bool ALIGN_EPI = false, bool SP2 = false>
; __device__ __forceinline__ void gemm_phase(PG8_LAS unsigned char* lds, const Gemm g, const Sched& S, const Epi& E) {
;     ...
;             PG8_LDB(B0, 0, 0); PG8_LDB(B1, 0, 1); PG8_SCHED; PG8_LDA(At, 0, 0); PG8_STAGE(PG8_SA(1, 1), a1 + hstep, voffA);
;             PG8_WAIT_V(8); PG8_WAIT_L(0); PG8_BAR; PG8_MMA(0, 0, At, B0); PG8_MMA(0, 1, At, B1); PG8_BAR; PG8_SCHED;
;             PG8_LDA(At, 0, 1); PG8_STAGE(PG8_SB(0, 0), b2, voffB); PG8_STAGE(PG8_SB(0, 1), b2 + hstep, voffB); PG8_STAGE(PG8_SA(0, 0), a2, voffA);
;             PG8_WAIT_V(8); PG8_WAIT_L(0); PG8_BAR; PG8_MMA(1, 0, At, B0); PG8_MMA(1, 1, At, B1); PG8_BAR; PG8_SCHED;
.LBB0_1329:
	s_add_u32 s4, s24, 0x100
	s_addc_u32 s5, s25, 0
	s_add_i32 s33, 0, 0x10000
	s_cmpk_eq_i32 s53, 0x54
	s_cselect_b32 s29, s21, s5
	s_cselect_b32 s28, s20, s4
	s_cselect_b32 s27, s23, s52
	s_cselect_b32 s26, s22, s51
	s_add_i32 s54, 0, 0x14000
	v_add_u32_e32 v98, s33, v199
	v_add_u32_e32 v146, s54, v199
	ds_read_b128 v[70:73], v98
	ds_read_b128 v[74:77], v98 offset:1024
	ds_read_b128 v[86:89], v98 offset:2048
	ds_read_b128 v[98:101], v98 offset:3072
	ds_read_b128 v[110:113], v146
	ds_read_b128 v[122:125], v146 offset:1024
	ds_read_b128 v[134:137], v146 offset:2048
	ds_read_b128 v[146:149], v146 offset:3072
	s_add_i32 m0, s39, 0xc000
	ds_read_b128 v[158:161], v201
	ds_read_b128 v[162:165], v201 offset:1024
	ds_read_b128 v[174:177], v201 offset:2048
	ds_read_b128 v[178:181], v201 offset:3072
	ds_read_b128 v[182:185], v201 offset:4096
	ds_read_b128 v[186:189], v201 offset:5120
	ds_read_b128 v[190:193], v201 offset:6144
	ds_read_b128 v[210:213], v201 offset:7168
	global_load_lds_dwordx4 v208, s[24:25]
	s_add_i32 m0, s39, 0xe000
	s_nop 0
	global_load_lds_dwordx4 v206, s[24:25]
	s_waitcnt vmcnt(8)
	s_waitcnt lgkmcnt(0)
	s_barrier
	s_setprio 1
	s_waitcnt lgkmcnt(0)
	v_mfma_f32_16x16x32_bf16 v[170:173], v[70:73], v[158:161], v[170:173]
	v_mfma_f32_16x16x32_bf16 v[170:173], v[74:77], v[162:165], v[170:173]
	v_mfma_f32_16x16x32_bf16 v[166:169], v[98:101], v[162:165], v[166:169]
	v_mfma_f32_16x16x32_bf16 v[166:169], v[86:89], v[158:161], v[166:169]
	v_mfma_f32_16x16x32_bf16 v[138:141], v[86:89], v[174:177], v[138:141]
	v_mfma_f32_16x16x32_bf16 v[138:141], v[98:101], v[178:181], v[138:141]
	v_mfma_f32_16x16x32_bf16 v[142:145], v[74:77], v[178:181], v[142:145]
	v_mfma_f32_16x16x32_bf16 v[142:145], v[70:73], v[174:177], v[142:145]
	v_mfma_f32_16x16x32_bf16 v[118:121], v[70:73], v[182:185], v[118:121]
	v_mfma_f32_16x16x32_bf16 v[118:121], v[74:77], v[186:189], v[118:121]
	v_mfma_f32_16x16x32_bf16 v[114:117], v[98:101], v[186:189], v[114:117]
	v_mfma_f32_16x16x32_bf16 v[114:117], v[86:89], v[182:185], v[114:117]
	v_mfma_f32_16x16x32_bf16 v[90:93], v[86:89], v[190:193], v[90:93]
	v_mfma_f32_16x16x32_bf16 v[90:93], v[98:101], v[210:213], v[90:93]
	v_mfma_f32_16x16x32_bf16 v[94:97], v[74:77], v[210:213], v[94:97]
	v_mfma_f32_16x16x32_bf16 v[94:97], v[70:73], v[190:193], v[94:97]
	s_setprio 0
	s_setprio 1
	v_mfma_f32_16x16x32_bf16 v[154:157], v[110:113], v[158:161], v[154:157]
	v_mfma_f32_16x16x32_bf16 v[154:157], v[122:125], v[162:165], v[154:157]
	v_mfma_f32_16x16x32_bf16 v[150:153], v[146:149], v[162:165], v[150:153]
	v_mfma_f32_16x16x32_bf16 v[150:153], v[134:137], v[158:161], v[150:153]
	v_mfma_f32_16x16x32_bf16 v[126:129], v[134:137], v[174:177], v[126:129]
	v_mfma_f32_16x16x32_bf16 v[126:129], v[146:149], v[178:181], v[126:129]
	v_mfma_f32_16x16x32_bf16 v[130:133], v[122:125], v[178:181], v[130:133]
	v_mfma_f32_16x16x32_bf16 v[130:133], v[110:113], v[174:177], v[130:133]
	v_mfma_f32_16x16x32_bf16 v[106:109], v[110:113], v[182:185], v[106:109]
	v_mfma_f32_16x16x32_bf16 v[106:109], v[122:125], v[186:189], v[106:109]
	v_mfma_f32_16x16x32_bf16 v[102:105], v[146:149], v[186:189], v[102:105]
	v_mfma_f32_16x16x32_bf16 v[102:105], v[134:137], v[182:185], v[102:105]
	v_mfma_f32_16x16x32_bf16 v[78:81], v[134:137], v[190:193], v[78:81]
	v_mfma_f32_16x16x32_bf16 v[78:81], v[146:149], v[210:213], v[78:81]
	v_mfma_f32_16x16x32_bf16 v[82:85], v[122:125], v[210:213], v[82:85]
	v_mfma_f32_16x16x32_bf16 v[82:85], v[110:113], v[190:193], v[82:85]
	s_setprio 0
	s_barrier
	s_add_i32 s24, s33, s38
	s_mov_b32 m0, s24
	ds_read_b128 v[158:161], v201 offset:16384
	ds_read_b128 v[162:165], v201 offset:17408
	ds_read_b128 v[174:177], v201 offset:18432
	ds_read_b128 v[178:181], v201 offset:19456
	ds_read_b128 v[182:185], v201 offset:20480
	ds_read_b128 v[186:189], v201 offset:21504
	ds_read_b128 v[190:193], v201 offset:22528
	ds_read_b128 v[210:213], v201 offset:23552
	global_load_lds_dwordx4 v0, s[26:27]
	s_add_i32 m0, s24, 0x2000
	s_add_u32 s100, s28, 0x80
	s_addc_u32 s101, s29, 0
	s_add_u32 s24, s26, 0x160000
	s_addc_u32 s25, s27, 0
	s_add_i32 s33, s54, s38
	global_load_lds_dwordx4 v196, s[26:27]
	s_mov_b32 m0, s33
	s_nop 0
	global_load_lds_dwordx4 v0, s[24:25]
	s_add_i32 m0, s33, 0x2000
	s_nop 0
	global_load_lds_dwordx4 v196, s[24:25]
	s_mov_b32 m0, s39
	s_nop 0
	global_load_lds_dwordx4 v14, s[28:29]
	s_mov_b32 m0, s40
	s_nop 0
	global_load_lds_dwordx4 v194, s[28:29]
	s_waitcnt vmcnt(8)
	s_waitcnt lgkmcnt(0)
	s_barrier
	s_setprio 1
	s_waitcnt lgkmcnt(0)
	v_mfma_f32_16x16x32_bf16 v[66:69], v[70:73], v[158:161], v[66:69]
	v_mfma_f32_16x16x32_bf16 v[66:69], v[74:77], v[162:165], v[66:69]
	v_mfma_f32_16x16x32_bf16 v[62:65], v[98:101], v[162:165], v[62:65]
	v_mfma_f32_16x16x32_bf16 v[62:65], v[86:89], v[158:161], v[62:65]
	v_mfma_f32_16x16x32_bf16 v[46:49], v[86:89], v[174:177], v[46:49]
	v_mfma_f32_16x16x32_bf16 v[46:49], v[98:101], v[178:181], v[46:49]
	v_mfma_f32_16x16x32_bf16 v[50:53], v[74:77], v[178:181], v[50:53]
	v_mfma_f32_16x16x32_bf16 v[50:53], v[70:73], v[174:177], v[50:53]
	v_mfma_f32_16x16x32_bf16 v[34:37], v[70:73], v[182:185], v[34:37]
	v_mfma_f32_16x16x32_bf16 v[34:37], v[74:77], v[186:189], v[34:37]
	v_mfma_f32_16x16x32_bf16 v[30:33], v[98:101], v[186:189], v[30:33]
	v_mfma_f32_16x16x32_bf16 v[30:33], v[86:89], v[182:185], v[30:33]
	v_mfma_f32_16x16x32_bf16 v[10:13], v[86:89], v[190:193], v[10:13]
	v_mfma_f32_16x16x32_bf16 v[10:13], v[98:101], v[210:213], v[10:13]
	v_mfma_f32_16x16x32_bf16 v[18:21], v[74:77], v[210:213], v[18:21]
	v_mfma_f32_16x16x32_bf16 v[18:21], v[70:73], v[190:193], v[18:21]
	s_setprio 0
	s_setprio 1
	v_mfma_f32_16x16x32_bf16 v[58:61], v[110:113], v[158:161], v[58:61]
	v_mfma_f32_16x16x32_bf16 v[58:61], v[122:125], v[162:165], v[58:61]
	v_mfma_f32_16x16x32_bf16 v[54:57], v[146:149], v[162:165], v[54:57]
	v_mfma_f32_16x16x32_bf16 v[54:57], v[134:137], v[158:161], v[54:57]
	v_mfma_f32_16x16x32_bf16 v[38:41], v[134:137], v[174:177], v[38:41]
	v_mfma_f32_16x16x32_bf16 v[38:41], v[146:149], v[178:181], v[38:41]
	v_mfma_f32_16x16x32_bf16 v[42:45], v[122:125], v[178:181], v[42:45]
	v_mfma_f32_16x16x32_bf16 v[42:45], v[110:113], v[174:177], v[42:45]
	v_mfma_f32_16x16x32_bf16 v[26:29], v[110:113], v[182:185], v[26:29]
	v_mfma_f32_16x16x32_bf16 v[26:29], v[122:125], v[186:189], v[26:29]
	v_mfma_f32_16x16x32_bf16 v[22:25], v[146:149], v[186:189], v[22:25]
	v_mfma_f32_16x16x32_bf16 v[22:25], v[134:137], v[182:185], v[22:25]
	v_mfma_f32_16x16x32_bf16 v[2:5], v[134:137], v[190:193], v[2:5]
	v_mfma_f32_16x16x32_bf16 v[2:5], v[146:149], v[210:213], v[2:5]
	v_mfma_f32_16x16x32_bf16 v[6:9], v[122:125], v[210:213], v[6:9]
	v_mfma_f32_16x16x32_bf16 v[6:9], v[110:113], v[190:193], v[6:9]
	s_setprio 0
	s_barrier
; #define PG8_STAGE(bufoff, gbase, voff) do { _Pragma("unroll") for (int _i = 0; _i < 2; ++_i) \
;         __builtin_amdgcn_global_load_lds((const unsigned*)((const char*)(gbase) + (voff)[_i]), (PG8_LAS unsigned*)(lds + (bufoff) + ldsw + _i * 8192), 16, 0, 0); } while (0)
; #define PG8_LDA(dst, b, h) do { _Pragma("unroll") for (int m = 0; m < 4; ++m) _Pragma("unroll") for (int k = 0; k < 2; ++k) dst[m][k] = *(const PG8_LAS bf16x8*)(lds + PG8_SA(b, h) + aoff + m * 2048 + k * 1024); } while (0)
; #define PG8_LDB(dst, b, h) do { _Pragma("unroll") for (int n = 0; n < 2; ++n) _Pragma("unroll") for (int k = 0; k < 2; ++k) dst[n][k] = *(const PG8_LAS bf16x8*)(lds + PG8_SB(b, h) + boff + n * 2048 + k * 1024); } while (0)
; #define PG8_MMA(ai, bj, At, Bt) do { __builtin_amdgcn_s_setprio(1); _Pragma("unroll") for (int m = 0; m < 4; ++m) _Pragma("unroll") for (int n = 0; n < 2; ++n) _Pragma("unroll") for (int k = 0; k < 2; ++k) \
;         acc[ai][bj][m][n] = __builtin_amdgcn_mfma_f32_16x16x32_bf16(Bt[n][k], At[m][k], acc[ai][bj][m][n], 0, 0, 0); __builtin_amdgcn_s_setprio(0); } while (0)
; #define PG8_WAIT_V(n) asm volatile("s_waitcnt vmcnt(" #n ")" ::: "memory")
; #define PG8_WAIT_L(n) asm volatile("s_waitcnt lgkmcnt(" #n ")" ::: "memory")
; #define PG8_BAR __builtin_amdgcn_s_barrier()
; #define PG8_SCHED __builtin_amdgcn_sched_barrier(0)
; template <class Epi, class Sched, bool ALIGN_EPI = false, bool SP2 = false>
; __device__ __forceinline__ void gemm_phase(PG8_LAS unsigned char* lds, const Gemm g, const Sched& S, const Epi& E) {
;     ...
;             PG8_LDB(B0, 1, 0); PG8_LDB(B1, 1, 1); PG8_SCHED; PG8_LDA(At, 1, 0); PG8_STAGE(PG8_SA(0, 1), a2 + hstep, voffA);
;             PG8_WAIT_V(8); PG8_WAIT_L(0); PG8_BAR; PG8_MMA(0, 0, At, B0); PG8_MMA(0, 1, At, B1); PG8_BAR; PG8_SCHED;
;             PG8_LDA(At, 1, 1); PG8_STAGE(PG8_SB(1, 0), b3, voffB); PG8_STAGE(PG8_SB(1, 1), b3 + hstep, voffB); PG8_STAGE(PG8_SA(1, 0), a3, voffA);
;             PG8_WAIT_V(8); PG8_WAIT_L(0); PG8_BAR; PG8_MMA(1, 0, At, B0); PG8_MMA(1, 1, At, B1); PG8_BAR; PG8_SCHED;
	s_add_i32 s33, 0, 0x18000
	s_add_i32 s54, 0, 0x1c000
	v_add_u32_e32 v98, s33, v199
	v_add_u32_e32 v146, s54, v199
	ds_read_b128 v[70:73], v98
	ds_read_b128 v[74:77], v98 offset:1024
	ds_read_b128 v[86:89], v98 offset:2048
	ds_read_b128 v[98:101], v98 offset:3072
	ds_read_b128 v[110:113], v146
	ds_read_b128 v[122:125], v146 offset:1024
	ds_read_b128 v[134:137], v146 offset:2048
	ds_read_b128 v[146:149], v146 offset:3072
	s_add_u32 s24, s28, 0x160000
	s_addc_u32 s25, s29, 0
	s_mov_b32 m0, s41
	ds_read_b128 v[158:161], v201 offset:32768
	ds_read_b128 v[162:165], v201 offset:33792
	ds_read_b128 v[174:177], v201 offset:34816
	ds_read_b128 v[178:181], v201 offset:35840
	ds_read_b128 v[182:185], v201 offset:36864
	ds_read_b128 v[186:189], v201 offset:37888
	ds_read_b128 v[190:193], v201 offset:38912
	ds_read_b128 v[210:213], v201 offset:39936
	global_load_lds_dwordx4 v14, s[24:25]
	s_mov_b32 m0, s42
	s_nop 0
	global_load_lds_dwordx4 v194, s[24:25]
	s_waitcnt vmcnt(8)
	s_waitcnt lgkmcnt(0)
	s_barrier
	s_setprio 1
	s_waitcnt lgkmcnt(0)
	v_mfma_f32_16x16x32_bf16 v[170:173], v[70:73], v[158:161], v[170:173]
	v_mfma_f32_16x16x32_bf16 v[170:173], v[74:77], v[162:165], v[170:173]
	v_mfma_f32_16x16x32_bf16 v[166:169], v[98:101], v[162:165], v[166:169]
	v_mfma_f32_16x16x32_bf16 v[166:169], v[86:89], v[158:161], v[166:169]
	v_mfma_f32_16x16x32_bf16 v[138:141], v[86:89], v[174:177], v[138:141]
	v_mfma_f32_16x16x32_bf16 v[138:141], v[98:101], v[178:181], v[138:141]
	v_mfma_f32_16x16x32_bf16 v[142:145], v[74:77], v[178:181], v[142:145]
	v_mfma_f32_16x16x32_bf16 v[142:145], v[70:73], v[174:177], v[142:145]
	v_mfma_f32_16x16x32_bf16 v[118:121], v[70:73], v[182:185], v[118:121]
	v_mfma_f32_16x16x32_bf16 v[118:121], v[74:77], v[186:189], v[118:121]
	v_mfma_f32_16x16x32_bf16 v[114:117], v[98:101], v[186:189], v[114:117]
	v_mfma_f32_16x16x32_bf16 v[114:117], v[86:89], v[182:185], v[114:117]
	v_mfma_f32_16x16x32_bf16 v[90:93], v[86:89], v[190:193], v[90:93]
	v_mfma_f32_16x16x32_bf16 v[90:93], v[98:101], v[210:213], v[90:93]
	v_mfma_f32_16x16x32_bf16 v[94:97], v[74:77], v[210:213], v[94:97]
	v_mfma_f32_16x16x32_bf16 v[94:97], v[70:73], v[190:193], v[94:97]
	s_setprio 0
	s_setprio 1
	v_mfma_f32_16x16x32_bf16 v[154:157], v[110:113], v[158:161], v[154:157]
	v_mfma_f32_16x16x32_bf16 v[154:157], v[122:125], v[162:165], v[154:157]
	v_mfma_f32_16x16x32_bf16 v[150:153], v[146:149], v[162:165], v[150:153]
	v_mfma_f32_16x16x32_bf16 v[150:153], v[134:137], v[158:161], v[150:153]
	v_mfma_f32_16x16x32_bf16 v[126:129], v[134:137], v[174:177], v[126:129]
	v_mfma_f32_16x16x32_bf16 v[126:129], v[146:149], v[178:181], v[126:129]
	v_mfma_f32_16x16x32_bf16 v[130:133], v[122:125], v[178:181], v[130:133]
	v_mfma_f32_16x16x32_bf16 v[130:133], v[110:113], v[174:177], v[130:133]
	v_mfma_f32_16x16x32_bf16 v[106:109], v[110:113], v[182:185], v[106:109]
	v_mfma_f32_16x16x32_bf16 v[106:109], v[122:125], v[186:189], v[106:109]
	v_mfma_f32_16x16x32_bf16 v[102:105], v[146:149], v[186:189], v[102:105]
	v_mfma_f32_16x16x32_bf16 v[102:105], v[134:137], v[182:185], v[102:105]
	v_mfma_f32_16x16x32_bf16 v[78:81], v[134:137], v[190:193], v[78:81]
	v_mfma_f32_16x16x32_bf16 v[78:81], v[146:149], v[210:213], v[78:81]
	v_mfma_f32_16x16x32_bf16 v[82:85], v[122:125], v[210:213], v[82:85]
	v_mfma_f32_16x16x32_bf16 v[82:85], v[110:113], v[190:193], v[82:85]
	s_setprio 0
	s_barrier
	s_add_i32 s24, s33, s38
	s_add_i32 m0, s24, 0xffffff80
	ds_read_b128 v[158:161], v201 offset:49152
	ds_read_b128 v[162:165], v201 offset:50176
	ds_read_b128 v[174:177], v201 offset:51200
	ds_read_b128 v[178:181], v201 offset:52224
	ds_read_b128 v[182:185], v201 offset:53248
	ds_read_b128 v[186:189], v201 offset:54272
	ds_read_b128 v[190:193], v201 offset:55296
	ds_read_b128 v[210:213], v201 offset:56320
	global_load_lds_dwordx4 v0, s[26:27] offset:128
	s_add_i32 m0, s24, 0x1f80
	s_add_u32 s24, s26, 0x160080
	s_addc_u32 s25, s27, 0
	global_load_lds_dwordx4 v196, s[26:27] offset:128
	s_add_i32 s26, s54, s38
	s_mov_b32 m0, s26
	s_nop 0
	global_load_lds_dwordx4 v0, s[24:25]
	s_add_i32 m0, s26, 0x2000
	s_nop 0
	global_load_lds_dwordx4 v196, s[24:25]
	s_mov_b32 m0, s44
	s_nop 0
	global_load_lds_dwordx4 v14, s[100:101]
	s_mov_b32 m0, s45
	s_nop 0
	global_load_lds_dwordx4 v194, s[100:101]
	s_waitcnt vmcnt(8)
	s_waitcnt lgkmcnt(0)
	s_barrier
	s_setprio 1
	s_waitcnt lgkmcnt(0)
	v_mfma_f32_16x16x32_bf16 v[66:69], v[70:73], v[158:161], v[66:69]
	v_mfma_f32_16x16x32_bf16 v[66:69], v[74:77], v[162:165], v[66:69]
	v_mfma_f32_16x16x32_bf16 v[62:65], v[98:101], v[162:165], v[62:65]
	v_mfma_f32_16x16x32_bf16 v[62:65], v[86:89], v[158:161], v[62:65]
	v_mfma_f32_16x16x32_bf16 v[46:49], v[86:89], v[174:177], v[46:49]
	v_mfma_f32_16x16x32_bf16 v[46:49], v[98:101], v[178:181], v[46:49]
	v_mfma_f32_16x16x32_bf16 v[50:53], v[74:77], v[178:181], v[50:53]
	v_mfma_f32_16x16x32_bf16 v[50:53], v[70:73], v[174:177], v[50:53]
	v_mfma_f32_16x16x32_bf16 v[34:37], v[70:73], v[182:185], v[34:37]
	v_mfma_f32_16x16x32_bf16 v[34:37], v[74:77], v[186:189], v[34:37]
	v_mfma_f32_16x16x32_bf16 v[30:33], v[98:101], v[186:189], v[30:33]
	v_mfma_f32_16x16x32_bf16 v[30:33], v[86:89], v[182:185], v[30:33]
	v_mfma_f32_16x16x32_bf16 v[10:13], v[86:89], v[190:193], v[10:13]
	v_mfma_f32_16x16x32_bf16 v[10:13], v[98:101], v[210:213], v[10:13]
	v_mfma_f32_16x16x32_bf16 v[18:21], v[74:77], v[210:213], v[18:21]
	v_mfma_f32_16x16x32_bf16 v[18:21], v[70:73], v[190:193], v[18:21]
	s_setprio 0
	s_setprio 1
	v_mfma_f32_16x16x32_bf16 v[58:61], v[110:113], v[158:161], v[58:61]
	v_mfma_f32_16x16x32_bf16 v[58:61], v[122:125], v[162:165], v[58:61]
	v_mfma_f32_16x16x32_bf16 v[54:57], v[146:149], v[162:165], v[54:57]
	v_mfma_f32_16x16x32_bf16 v[54:57], v[134:137], v[158:161], v[54:57]
	v_mfma_f32_16x16x32_bf16 v[38:41], v[134:137], v[174:177], v[38:41]
	v_mfma_f32_16x16x32_bf16 v[38:41], v[146:149], v[178:181], v[38:41]
	v_mfma_f32_16x16x32_bf16 v[42:45], v[122:125], v[178:181], v[42:45]
	v_mfma_f32_16x16x32_bf16 v[42:45], v[110:113], v[174:177], v[42:45]
	v_mfma_f32_16x16x32_bf16 v[26:29], v[110:113], v[182:185], v[26:29]
	v_mfma_f32_16x16x32_bf16 v[26:29], v[122:125], v[186:189], v[26:29]
	v_mfma_f32_16x16x32_bf16 v[22:25], v[146:149], v[186:189], v[22:25]
	v_mfma_f32_16x16x32_bf16 v[22:25], v[134:137], v[182:185], v[22:25]
	v_mfma_f32_16x16x32_bf16 v[2:5], v[134:137], v[190:193], v[2:5]
	v_mfma_f32_16x16x32_bf16 v[2:5], v[146:149], v[210:213], v[2:5]
	v_mfma_f32_16x16x32_bf16 v[6:9], v[122:125], v[210:213], v[6:9]
	v_mfma_f32_16x16x32_bf16 v[6:9], v[110:113], v[190:193], v[6:9]
	s_setprio 0
	s_barrier
	s_add_i32 s53, s53, 2
	s_add_u32 s51, s51, 0x100
	s_addc_u32 s52, s52, 0
	s_cmpk_gt_u32 s53, 0x55
	s_mov_b64 s[24:25], s[4:5]
	s_cbranch_scc0 .LBB0_1329
	s_and_b64 vcc, exec, s[16:17]
	s_cbranch_vccz .LBB0_1332
	s_barrier

; __global__ void __launch_bounds__(NWAVES * 64, 2) hymba_fwd(Args args) {
	.amdhsa_kernel _Z9hymba_fwd4Args
		.amdhsa_group_segment_fixed_size 0
		.amdhsa_private_segment_fixed_size 0
		.amdhsa_kernarg_size 456
		.amdhsa_user_sgpr_count 2
		.amdhsa_user_sgpr_dispatch_ptr 0
		.amdhsa_user_sgpr_queue_ptr 0
		.amdhsa_user_sgpr_kernarg_segment_ptr 1
		.amdhsa_user_sgpr_dispatch_id 0
		.amdhsa_user_sgpr_kernarg_preload_length 0
		.amdhsa_user_sgpr_kernarg_preload_offset 0
		.amdhsa_user_sgpr_private_segment_size 0
		.amdhsa_uses_dynamic_stack 0
		.amdhsa_enable_private_segment 0
		.amdhsa_system_sgpr_workgroup_id_x 1
		.amdhsa_system_sgpr_workgroup_id_y 0
		.amdhsa_system_sgpr_workgroup_id_z 0
		.amdhsa_system_sgpr_workgroup_info 0
		.amdhsa_system_vgpr_workitem_id 0
		.amdhsa_next_free_vgpr 256
		.amdhsa_next_free_sgpr 102
		.amdhsa_accum_offset 256
		.amdhsa_reserve_vcc 1
		.amdhsa_float_round_mode_32 0
		.amdhsa_float_round_mode_16_64 0
		.amdhsa_float_denorm_mode_32 3
		.amdhsa_float_denorm_mode_16_64 3
		.amdhsa_dx10_clamp 1
		.amdhsa_ieee_mode 1
		.amdhsa_fp16_overflow 0
		.amdhsa_tg_split 0
		.amdhsa_exception_fp_ieee_invalid_op 0
		.amdhsa_exception_fp_denorm_src 0
		.amdhsa_exception_fp_ieee_div_zero 0
		.amdhsa_exception_fp_ieee_overflow 0
		.amdhsa_exception_fp_ieee_underflow 0
		.amdhsa_exception_fp_ieee_inexact 0
		.amdhsa_exception_int_div_zero 0
	.end_amdhsa_kernel

; __global__ void __launch_bounds__(NWAVES * 64, 2) hymba_fwd(Args args) {
amdhsa.kernels:
  - .agpr_count:     0
    .args:
      - .offset:         0
        .size:           200
        .value_kind:     by_value
      - .offset:         200
        .size:           4
        .value_kind:     hidden_block_count_x
      - .offset:         204
        .size:           4
        .value_kind:     hidden_block_count_y
      - .offset:         208
        .size:           4
        .value_kind:     hidden_block_count_z
      - .offset:         212
        .size:           2
        .value_kind:     hidden_group_size_x
      - .offset:         214
        .size:           2
        .value_kind:     hidden_group_size_y
      - .offset:         216
        .size:           2
        .value_kind:     hidden_group_size_z
      - .offset:         218
        .size:           2
        .value_kind:     hidden_remainder_x
      - .offset:         220
        .size:           2
        .value_kind:     hidden_remainder_y
      - .offset:         222
        .size:           2
        .value_kind:     hidden_remainder_z
      - .offset:         240
        .size:           8
        .value_kind:     hidden_global_offset_x
      - .offset:         248
        .size:           8
        .value_kind:     hidden_global_offset_y
      - .offset:         256
        .size:           8
        .value_kind:     hidden_global_offset_z
      - .offset:         264
        .size:           2
        .value_kind:     hidden_grid_dims
      - .offset:         320
        .size:           4
        .value_kind:     hidden_dynamic_lds_size
    .group_segment_fixed_size: 0
    .kernarg_segment_align: 8
    .kernarg_segment_size: 456
    .language:       OpenCL C
    .language_version:
      - 2
      - 0
    .max_flat_workgroup_size: 512
    .name:           _Z9hymba_fwd4Args
    .private_segment_fixed_size: 0
    .sgpr_count:     108
    .sgpr_spill_count: 126
    .symbol:         _Z9hymba_fwd4Args.kd
    .uniform_work_group_size: 1
    .uses_dynamic_stack: false
    .vgpr_count:     256
    .vgpr_spill_count: 0
    .wavefront_size: 64
